# LDS-DMA issue: m0 write moved ahead of the address add so the hazard s_nop before global_load_lds goes (76 sites), on top of peeled first iteration
# baseline (speedup 1.0000x reference)
; #define PG8_STAGE(bufoff, gbase, voff) do { _Pragma("unroll") for (int _i = 0; _i < 2; ++_i) \
;         __builtin_amdgcn_global_load_lds((const unsigned*)((const char*)(gbase) + (voff)[_i]), (PG8_LAS unsigned*)(lds + (bufoff) + ldsw + _i * 8192), 16, 0, 0); } while (0)
; #define PG8_LDA(dst, b, h) do { _Pragma("unroll") for (int m = 0; m < 4; ++m) _Pragma("unroll") for (int k = 0; k < 2; ++k) dst[m][k] = *(const PG8_LAS bf16x8*)(lds + PG8_SA(b, h) + aoff + m * 2048 + k * 1024); } while (0)
; #define PG8_LDB(dst, b, h) do { _Pragma("unroll") for (int n = 0; n < 2; ++n) _Pragma("unroll") for (int k = 0; k < 2; ++k) dst[n][k] = *(const PG8_LAS bf16x8*)(lds + PG8_SB(b, h) + boff + n * 2048 + k * 1024); } while (0)
; #define PG8_WAIT_V(n) asm volatile("s_waitcnt vmcnt(" #n ")" ::: "memory")
; #define PG8_WAIT_L(n) asm volatile("s_waitcnt lgkmcnt(" #n ")" ::: "memory")
; #define PG8_BAR __builtin_amdgcn_s_barrier()
; #define PG8_SCHED __builtin_amdgcn_sched_barrier(0)
; template <class Epi, class Sched, bool ALIGN_EPI = false, bool SP2 = false>
; __device__ __forceinline__ void gemm_phase(PG8_LAS unsigned char* lds, const Gemm g, const Sched& S, const Epi& E, const int tid) {
;     ...
;         const bool has_next = S.next(ui + 1, nxt);
;         const char* nA = has_next ? (const char*)g.A + (size_t)nxt.pm * tstep : cA; const char* nB = has_next ? (const char*)g.Bt + (size_t)nxt.pn * tstep : cB;
;         for (int t = 0; t < nt; t += 2) {
;             const bool last = (t == nt - 2);
;             const char* a1 = cA + (size_t)(t + 1) * kstep;
;             const char* a2 = last ? nA : cA + (size_t)(t + 2) * kstep; const char* b2 = last ? nB : cB + (size_t)(t + 2) * kstep;
;             const char* a3 = a2 + kstep; const char* b3 = b2 + kstep;
;             if (last && has_next) S.a_ready(nxt);
;             if constexpr (SP2) {
;             PG8_LDB(B0, 0, 0); PG8_LDB(B1, 0, 1); PG8_SCHED; PG8_LDA(At, 0, 0); PG8_STAGE(PG8_SA(1, 1), a1 + hstep, voffA);
;             PG8_WAIT_V(8); PG8_WAIT_L(0); PG8_BAR; PG8_MMA(0, 0, At, B0); PG8_MMA(0, 1, At, B1); PG8_BAR; PG8_SCHED;
;             PG8_LDA(At, 0, 1); PG8_STAGE(PG8_SB(0, 0), b2, voffB); PG8_STAGE(PG8_SB(0, 1), b2 + hstep, voffB); PG8_STAGE(PG8_SA(0, 0), a2, voffA);
;             PG8_WAIT_V(8); PG8_WAIT_L(0); PG8_BAR; PG8_MMA(1, 0, At, B0); PG8_MMA(1, 1, At, B1); PG8_BAR; PG8_SCHED;
.LBB0_98:
	s_ashr_i32 s13, s12, 31
	s_lshl_b64 s[14:15], s[12:13], 19
	s_add_u32 s14, s27, s14
	s_addc_u32 s15, s34, s15
	s_and_b64 s[16:17], s[2:3], exec
	s_cselect_b32 s13, s15, s19
	s_cselect_b32 s45, s14, s18
	s_ashr_i32 s11, s10, 31
	s_lshl_b64 s[16:17], s[10:11], 19
	s_add_u32 s16, s24, s16
	s_addc_u32 s17, s25, s17
	s_and_b64 s[22:23], s[2:3], exec
	s_cselect_b32 s11, s17, s21
	s_cselect_b32 s46, s16, s20
	s_add_u32 s18, s18, 0x40080
	s_addc_u32 s19, s19, 0
	s_add_u32 s47, s20, 0x100
	v_mov_b32_e32 v4, 0
	s_addc_u32 s48, s21, 0
	s_mov_b32 s49, -2
	s_add_u32 s20, s18, 0xfffc0080
	s_addc_u32 s21, s19, -1
	s_add_i32 s50, 0, 0x10000
	s_cmp_eq_u32 s49, 12
	s_cselect_b32 s23, s13, s21
	s_cselect_b32 s22, s45, s20
	s_cselect_b32 s21, s11, s48
	s_cselect_b32 s20, s46, s47
	s_add_i32 s52, 0, 0x14000
	v_add_u32_e32 v132, s50, v153
	v_add_u32_e32 v148, s52, v153
	ds_read_b128 v[116:119], v132
	ds_read_b128 v[120:123], v132 offset:1024
	ds_read_b128 v[124:127], v132 offset:2048
	ds_read_b128 v[132:135], v132 offset:3072
	ds_read_b128 v[178:181], v148
	ds_read_b128 v[182:185], v148 offset:1024
	ds_read_b128 v[186:189], v148 offset:2048
	ds_read_b128 v[190:193], v148 offset:3072
	v_lshl_add_u64 v[148:149], s[18:19], 0, v[172:173]
	s_add_i32 m0, s36, 0xc000
	ds_read_b128 v[194:197], v176
	ds_read_b128 v[198:201], v176 offset:1024
	ds_read_b128 v[202:205], v176 offset:2048
	ds_read_b128 v[206:209], v176 offset:3072
	ds_read_b128 v[210:213], v176 offset:4096
	ds_read_b128 v[214:217], v176 offset:5120
	ds_read_b128 v[218:221], v176 offset:6144
	ds_read_b128 v[222:225], v176 offset:7168
	global_load_lds_dwordx4 v[148:149], off
	s_add_i32 m0, s36, 0xe000
	v_lshl_add_u64 v[148:149], s[18:19], 0, v[174:175]
	global_load_lds_dwordx4 v[148:149], off
	s_waitcnt vmcnt(8)
	s_waitcnt lgkmcnt(0)
	s_barrier
	s_waitcnt lgkmcnt(0)
	v_mfma_f32_16x16x32_bf16 v[144:147], v[116:119], v[194:197], 0
	v_mfma_f32_16x16x32_bf16 v[140:143], v[124:127], v[194:197], 0
	v_mfma_f32_16x16x32_bf16 v[112:115], v[116:119], v[202:205], 0
	v_mfma_f32_16x16x32_bf16 v[108:111], v[124:127], v[202:205], 0
	v_mfma_f32_16x16x32_bf16 v[96:99], v[116:119], v[210:213], 0
	v_mfma_f32_16x16x32_bf16 v[92:95], v[124:127], v[210:213], 0
	v_mfma_f32_16x16x32_bf16 v[80:83], v[116:119], v[218:221], 0
	v_mfma_f32_16x16x32_bf16 v[76:79], v[124:127], v[218:221], 0
	v_mfma_f32_16x16x32_bf16 v[144:147], v[120:123], v[198:201], v[144:147]
	v_mfma_f32_16x16x32_bf16 v[140:143], v[132:135], v[198:201], v[140:143]
	v_mfma_f32_16x16x32_bf16 v[112:115], v[120:123], v[206:209], v[112:115]
	v_mfma_f32_16x16x32_bf16 v[108:111], v[132:135], v[206:209], v[108:111]
	v_mfma_f32_16x16x32_bf16 v[96:99], v[120:123], v[214:217], v[96:99]
	v_mfma_f32_16x16x32_bf16 v[92:95], v[132:135], v[214:217], v[92:95]
	v_mfma_f32_16x16x32_bf16 v[80:83], v[120:123], v[222:225], v[80:83]
	v_mfma_f32_16x16x32_bf16 v[76:79], v[132:135], v[222:225], v[76:79]
	v_mfma_f32_16x16x32_bf16 v[136:139], v[178:181], v[194:197], 0
	v_mfma_f32_16x16x32_bf16 v[128:131], v[186:189], v[194:197], 0
	v_mfma_f32_16x16x32_bf16 v[104:107], v[178:181], v[202:205], 0
	v_mfma_f32_16x16x32_bf16 v[100:103], v[186:189], v[202:205], 0
	v_mfma_f32_16x16x32_bf16 v[88:91], v[178:181], v[210:213], 0
	v_mfma_f32_16x16x32_bf16 v[84:87], v[186:189], v[210:213], 0
	v_mfma_f32_16x16x32_bf16 v[72:75], v[178:181], v[218:221], 0
	v_mfma_f32_16x16x32_bf16 v[68:71], v[186:189], v[218:221], 0
	v_mfma_f32_16x16x32_bf16 v[136:139], v[182:185], v[198:201], v[136:139]
	v_mfma_f32_16x16x32_bf16 v[128:131], v[190:193], v[198:201], v[128:131]
	v_mfma_f32_16x16x32_bf16 v[104:107], v[182:185], v[206:209], v[104:107]
	v_mfma_f32_16x16x32_bf16 v[100:103], v[190:193], v[206:209], v[100:103]
	v_mfma_f32_16x16x32_bf16 v[88:91], v[182:185], v[214:217], v[88:91]
	v_mfma_f32_16x16x32_bf16 v[84:87], v[190:193], v[214:217], v[84:87]
	v_mfma_f32_16x16x32_bf16 v[72:75], v[182:185], v[222:225], v[72:75]
	v_mfma_f32_16x16x32_bf16 v[68:71], v[190:193], v[222:225], v[68:71]
	s_barrier
	s_add_i32 s50, s50, s26
	v_lshl_add_u64 v[148:149], s[20:21], 0, v[168:169]
	s_mov_b32 m0, s50
	ds_read_b128 v[194:197], v176 offset:16384
	ds_read_b128 v[198:201], v176 offset:17408
	ds_read_b128 v[202:205], v176 offset:18432
	ds_read_b128 v[206:209], v176 offset:19456
	ds_read_b128 v[210:213], v176 offset:20480
	ds_read_b128 v[214:217], v176 offset:21504
	ds_read_b128 v[218:221], v176 offset:22528
	ds_read_b128 v[222:225], v176 offset:23552
	global_load_lds_dwordx4 v[148:149], off
	s_add_i32 m0, s50, 0x2000
	s_add_u32 s50, s20, 0x40000
	v_lshl_add_u64 v[150:151], s[20:21], 0, v[0:1]
	s_addc_u32 s51, s21, 0
	s_add_i32 s52, s52, s26
	global_load_lds_dwordx4 v[150:151], off
	v_lshl_add_u64 v[226:227], s[50:51], 0, v[168:169]
	s_mov_b32 m0, s52
	v_lshl_add_u64 v[238:239], s[22:23], 0, v[166:167]
	global_load_lds_dwordx4 v[226:227], off
	s_add_i32 m0, s52, 0x2000
	v_lshl_add_u64 v[226:227], s[50:51], 0, v[0:1]
	global_load_lds_dwordx4 v[226:227], off
	s_mov_b32 m0, s36
	v_lshl_add_u64 v[226:227], s[22:23], 0, v[170:171]
	global_load_lds_dwordx4 v[226:227], off
	s_mov_b32 m0, s37
	s_nop 0
	global_load_lds_dwordx4 v[238:239], off
	s_waitcnt vmcnt(8)
	s_waitcnt lgkmcnt(0)
	s_barrier
; #define PG8_STAGE(bufoff, gbase, voff) do { _Pragma("unroll") for (int _i = 0; _i < 2; ++_i) \
;         __builtin_amdgcn_global_load_lds((const unsigned*)((const char*)(gbase) + (voff)[_i]), (PG8_LAS unsigned*)(lds + (bufoff) + ldsw + _i * 8192), 16, 0, 0); } while (0)
; #define PG8_LDA(dst, b, h) do { _Pragma("unroll") for (int m = 0; m < 4; ++m) _Pragma("unroll") for (int k = 0; k < 2; ++k) dst[m][k] = *(const PG8_LAS bf16x8*)(lds + PG8_SA(b, h) + aoff + m * 2048 + k * 1024); } while (0)
; #define PG8_LDB(dst, b, h) do { _Pragma("unroll") for (int n = 0; n < 2; ++n) _Pragma("unroll") for (int k = 0; k < 2; ++k) dst[n][k] = *(const PG8_LAS bf16x8*)(lds + PG8_SB(b, h) + boff + n * 2048 + k * 1024); } while (0)
; #define PG8_MMA(ai, bj, At, Bt) do { __builtin_amdgcn_s_setprio(1); _Pragma("unroll") for (int m = 0; m < 4; ++m) _Pragma("unroll") for (int n = 0; n < 2; ++n) _Pragma("unroll") for (int k = 0; k < 2; ++k) \
;         acc[ai][bj][m][n] = __builtin_amdgcn_mfma_f32_16x16x32_bf16(Bt[n][k], At[m][k], acc[ai][bj][m][n], 0, 0, 0); __builtin_amdgcn_s_setprio(0); } while (0)
; #define PG8_WAIT_V(n) asm volatile("s_waitcnt vmcnt(" #n ")" ::: "memory")
; #define PG8_WAIT_L(n) asm volatile("s_waitcnt lgkmcnt(" #n ")" ::: "memory")
; #define PG8_BAR __builtin_amdgcn_s_barrier()
; #define PG8_SCHED __builtin_amdgcn_sched_barrier(0)
; template <class Epi, class Sched, bool ALIGN_EPI = false, bool SP2 = false>
; __device__ __forceinline__ void gemm_phase(PG8_LAS unsigned char* lds, const Gemm g, const Sched& S, const Epi& E, const int tid) {
;     ...
;             PG8_WAIT_V(8); PG8_WAIT_L(0); PG8_BAR; PG8_MMA(1, 0, At, B0); PG8_MMA(1, 1, At, B1); PG8_BAR; PG8_SCHED;
;             PG8_LDB(B0, 1, 0); PG8_LDB(B1, 1, 1); PG8_SCHED; PG8_LDA(At, 1, 0); PG8_STAGE(PG8_SA(0, 1), a2 + hstep, voffA);
;             PG8_WAIT_V(8); PG8_WAIT_L(0); PG8_BAR; PG8_MMA(0, 0, At, B0); PG8_MMA(0, 1, At, B1); PG8_BAR; PG8_SCHED;
;             PG8_LDA(At, 1, 1); PG8_STAGE(PG8_SB(1, 0), b3, voffB); PG8_STAGE(PG8_SB(1, 1), b3 + hstep, voffB); PG8_STAGE(PG8_SA(1, 0), a3, voffA);
	s_waitcnt lgkmcnt(0)
	v_mfma_f32_16x16x32_bf16 v[64:67], v[116:119], v[194:197], 0
	v_mfma_f32_16x16x32_bf16 v[60:63], v[124:127], v[194:197], 0
	v_mfma_f32_16x16x32_bf16 v[56:59], v[116:119], v[202:205], 0
	v_mfma_f32_16x16x32_bf16 v[48:51], v[124:127], v[202:205], 0
	v_mfma_f32_16x16x32_bf16 v[40:43], v[116:119], v[210:213], 0
	v_mfma_f32_16x16x32_bf16 v[32:35], v[124:127], v[210:213], 0
	v_mfma_f32_16x16x32_bf16 v[24:27], v[116:119], v[218:221], 0
	v_mfma_f32_16x16x32_bf16 v[16:19], v[124:127], v[218:221], 0
	v_mfma_f32_16x16x32_bf16 v[64:67], v[120:123], v[198:201], v[64:67]
	v_mfma_f32_16x16x32_bf16 v[60:63], v[132:135], v[198:201], v[60:63]
	v_mfma_f32_16x16x32_bf16 v[56:59], v[120:123], v[206:209], v[56:59]
	v_mfma_f32_16x16x32_bf16 v[48:51], v[132:135], v[206:209], v[48:51]
	v_mfma_f32_16x16x32_bf16 v[40:43], v[120:123], v[214:217], v[40:43]
	v_mfma_f32_16x16x32_bf16 v[32:35], v[132:135], v[214:217], v[32:35]
	v_mfma_f32_16x16x32_bf16 v[24:27], v[120:123], v[222:225], v[24:27]
	v_mfma_f32_16x16x32_bf16 v[16:19], v[132:135], v[222:225], v[16:19]
	v_mfma_f32_16x16x32_bf16 v[52:55], v[178:181], v[194:197], 0
	v_mfma_f32_16x16x32_bf16 v[44:47], v[186:189], v[194:197], 0
	v_mfma_f32_16x16x32_bf16 v[36:39], v[178:181], v[202:205], 0
	v_mfma_f32_16x16x32_bf16 v[28:31], v[186:189], v[202:205], 0
	v_mfma_f32_16x16x32_bf16 v[20:23], v[178:181], v[210:213], 0
	v_mfma_f32_16x16x32_bf16 v[12:15], v[186:189], v[210:213], 0
	v_mfma_f32_16x16x32_bf16 v[8:11], v[178:181], v[218:221], 0
	v_mfma_f32_16x16x32_bf16 v[4:7], v[186:189], v[218:221], 0
	v_mfma_f32_16x16x32_bf16 v[52:55], v[182:185], v[198:201], v[52:55]
	v_mfma_f32_16x16x32_bf16 v[44:47], v[190:193], v[198:201], v[44:47]
	v_mfma_f32_16x16x32_bf16 v[36:39], v[182:185], v[206:209], v[36:39]
	v_mfma_f32_16x16x32_bf16 v[28:31], v[190:193], v[206:209], v[28:31]
	v_mfma_f32_16x16x32_bf16 v[20:23], v[182:185], v[214:217], v[20:23]
	v_mfma_f32_16x16x32_bf16 v[12:15], v[190:193], v[214:217], v[12:15]
	v_mfma_f32_16x16x32_bf16 v[8:11], v[182:185], v[222:225], v[8:11]
	v_mfma_f32_16x16x32_bf16 v[4:7], v[190:193], v[222:225], v[4:7]
	s_barrier
	s_add_i32 s50, 0, 0x18000
	s_add_i32 s51, 0, 0x1c000
	v_add_u32_e32 v132, s50, v153
	v_add_u32_e32 v177, s51, v153
	ds_read_b128 v[116:119], v132
	ds_read_b128 v[120:123], v132 offset:1024
	ds_read_b128 v[124:127], v132 offset:2048
	ds_read_b128 v[132:135], v132 offset:3072
	ds_read_b128 v[178:181], v177
	ds_read_b128 v[182:185], v177 offset:1024
	ds_read_b128 v[186:189], v177 offset:2048
	ds_read_b128 v[190:193], v177 offset:3072
	s_add_u32 s22, s22, 0x40000
	s_addc_u32 s23, s23, 0
	s_mov_b32 m0, s38
	v_lshl_add_u64 v[240:241], s[22:23], 0, v[170:171]
	ds_read_b128 v[194:197], v176 offset:32768
	ds_read_b128 v[198:201], v176 offset:33792
	ds_read_b128 v[202:205], v176 offset:34816
	ds_read_b128 v[206:209], v176 offset:35840
	ds_read_b128 v[210:213], v176 offset:36864
	ds_read_b128 v[214:217], v176 offset:37888
	ds_read_b128 v[218:221], v176 offset:38912
	ds_read_b128 v[222:225], v176 offset:39936
	global_load_lds_dwordx4 v[240:241], off
	s_mov_b32 m0, s39
	v_lshl_add_u64 v[240:241], s[22:23], 0, v[166:167]
	global_load_lds_dwordx4 v[240:241], off
	s_waitcnt vmcnt(8)
	s_waitcnt lgkmcnt(0)
	s_barrier
	s_waitcnt lgkmcnt(0)
	v_mfma_f32_16x16x32_bf16 v[144:147], v[116:119], v[194:197], v[144:147]
	v_mfma_f32_16x16x32_bf16 v[140:143], v[124:127], v[194:197], v[140:143]
	v_mfma_f32_16x16x32_bf16 v[112:115], v[116:119], v[202:205], v[112:115]
	v_mfma_f32_16x16x32_bf16 v[108:111], v[124:127], v[202:205], v[108:111]
	v_mfma_f32_16x16x32_bf16 v[96:99], v[116:119], v[210:213], v[96:99]
	v_mfma_f32_16x16x32_bf16 v[92:95], v[124:127], v[210:213], v[92:95]
	v_mfma_f32_16x16x32_bf16 v[80:83], v[116:119], v[218:221], v[80:83]
	v_mfma_f32_16x16x32_bf16 v[76:79], v[124:127], v[218:221], v[76:79]
	v_mfma_f32_16x16x32_bf16 v[144:147], v[120:123], v[198:201], v[144:147]
	v_mfma_f32_16x16x32_bf16 v[140:143], v[132:135], v[198:201], v[140:143]
	v_mfma_f32_16x16x32_bf16 v[112:115], v[120:123], v[206:209], v[112:115]
	v_mfma_f32_16x16x32_bf16 v[108:111], v[132:135], v[206:209], v[108:111]
	v_mfma_f32_16x16x32_bf16 v[96:99], v[120:123], v[214:217], v[96:99]
	v_mfma_f32_16x16x32_bf16 v[92:95], v[132:135], v[214:217], v[92:95]
	v_mfma_f32_16x16x32_bf16 v[80:83], v[120:123], v[222:225], v[80:83]
	v_mfma_f32_16x16x32_bf16 v[76:79], v[132:135], v[222:225], v[76:79]
	v_mfma_f32_16x16x32_bf16 v[136:139], v[178:181], v[194:197], v[136:139]
	v_mfma_f32_16x16x32_bf16 v[128:131], v[186:189], v[194:197], v[128:131]
	v_mfma_f32_16x16x32_bf16 v[104:107], v[178:181], v[202:205], v[104:107]
	v_mfma_f32_16x16x32_bf16 v[100:103], v[186:189], v[202:205], v[100:103]
	v_mfma_f32_16x16x32_bf16 v[88:91], v[178:181], v[210:213], v[88:91]
	v_mfma_f32_16x16x32_bf16 v[84:87], v[186:189], v[210:213], v[84:87]
	v_mfma_f32_16x16x32_bf16 v[72:75], v[178:181], v[218:221], v[72:75]
	v_mfma_f32_16x16x32_bf16 v[68:71], v[186:189], v[218:221], v[68:71]
	v_mfma_f32_16x16x32_bf16 v[136:139], v[182:185], v[198:201], v[136:139]
	v_mfma_f32_16x16x32_bf16 v[128:131], v[190:193], v[198:201], v[128:131]
	v_mfma_f32_16x16x32_bf16 v[104:107], v[182:185], v[206:209], v[104:107]
	v_mfma_f32_16x16x32_bf16 v[100:103], v[190:193], v[206:209], v[100:103]
	v_mfma_f32_16x16x32_bf16 v[88:91], v[182:185], v[214:217], v[88:91]
	v_mfma_f32_16x16x32_bf16 v[84:87], v[190:193], v[214:217], v[84:87]
	v_mfma_f32_16x16x32_bf16 v[72:75], v[182:185], v[222:225], v[72:75]
	v_mfma_f32_16x16x32_bf16 v[68:71], v[190:193], v[222:225], v[68:71]
	s_barrier
; #define PG8_STAGE(bufoff, gbase, voff) do { _Pragma("unroll") for (int _i = 0; _i < 2; ++_i) \
;         __builtin_amdgcn_global_load_lds((const unsigned*)((const char*)(gbase) + (voff)[_i]), (PG8_LAS unsigned*)(lds + (bufoff) + ldsw + _i * 8192), 16, 0, 0); } while (0)
; #define PG8_LDA(dst, b, h) do { _Pragma("unroll") for (int m = 0; m < 4; ++m) _Pragma("unroll") for (int k = 0; k < 2; ++k) dst[m][k] = *(const PG8_LAS bf16x8*)(lds + PG8_SA(b, h) + aoff + m * 2048 + k * 1024); } while (0)
; #define PG8_LDB(dst, b, h) do { _Pragma("unroll") for (int n = 0; n < 2; ++n) _Pragma("unroll") for (int k = 0; k < 2; ++k) dst[n][k] = *(const PG8_LAS bf16x8*)(lds + PG8_SB(b, h) + boff + n * 2048 + k * 1024); } while (0)
; #define PG8_MMA(ai, bj, At, Bt) do { __builtin_amdgcn_s_setprio(1); _Pragma("unroll") for (int m = 0; m < 4; ++m) _Pragma("unroll") for (int n = 0; n < 2; ++n) _Pragma("unroll") for (int k = 0; k < 2; ++k) \
;         acc[ai][bj][m][n] = __builtin_amdgcn_mfma_f32_16x16x32_bf16(Bt[n][k], At[m][k], acc[ai][bj][m][n], 0, 0, 0); __builtin_amdgcn_s_setprio(0); } while (0)
; #define PG8_BAR __builtin_amdgcn_s_barrier()
; template <class Epi, class Sched, bool ALIGN_EPI = false, bool SP2 = false>
; __device__ __forceinline__ void gemm_phase(PG8_LAS unsigned char* lds, const Gemm g, const Sched& S, const Epi& E, const int tid) {
;     ...
;             PG8_LDB(B0, 0, 0); PG8_LDB(B1, 0, 1); PG8_SCHED; PG8_LDA(At, 0, 0); PG8_STAGE(PG8_SA(1, 1), a1 + hstep, voffA);
;             PG8_WAIT_V(8); PG8_WAIT_L(0); PG8_BAR; PG8_MMA(0, 0, At, B0); PG8_MMA(0, 1, At, B1); PG8_BAR; PG8_SCHED;
;             PG8_LDA(At, 0, 1); PG8_STAGE(PG8_SB(0, 0), b2, voffB); PG8_STAGE(PG8_SB(0, 1), b2 + hstep, voffB); PG8_STAGE(PG8_SA(0, 0), a2, voffA);
;             PG8_WAIT_V(8); PG8_WAIT_L(0); PG8_BAR; PG8_MMA(1, 0, At, B0); PG8_MMA(1, 1, At, B1); PG8_BAR; PG8_SCHED;
;             PG8_LDB(B0, 1, 0); PG8_LDB(B1, 1, 1); PG8_SCHED; PG8_LDA(At, 1, 0); PG8_STAGE(PG8_SA(0, 1), a2 + hstep, voffA);
;             PG8_WAIT_V(8); PG8_WAIT_L(0); PG8_BAR; PG8_MMA(0, 0, At, B0); PG8_MMA(0, 1, At, B1); PG8_BAR; PG8_SCHED;
;             PG8_LDA(At, 1, 1); PG8_STAGE(PG8_SB(1, 0), b3, voffB); PG8_STAGE(PG8_SB(1, 1), b3 + hstep, voffB); PG8_STAGE(PG8_SA(1, 0), a3, voffA);
;             PG8_WAIT_V(8); PG8_WAIT_L(0); PG8_BAR; PG8_MMA(1, 0, At, B0); PG8_MMA(1, 1, At, B1); PG8_BAR; PG8_SCHED;
	s_add_i32 s22, s50, s26
	v_lshl_add_u64 v[148:149], v[148:149], 0, s[0:1]
	s_mov_b32 m0, s22
	ds_read_b128 v[194:197], v176 offset:49152
	ds_read_b128 v[198:201], v176 offset:50176
	ds_read_b128 v[202:205], v176 offset:51200
	ds_read_b128 v[206:209], v176 offset:52224
	ds_read_b128 v[210:213], v176 offset:53248
	ds_read_b128 v[214:217], v176 offset:54272
	ds_read_b128 v[218:221], v176 offset:55296
	ds_read_b128 v[222:225], v176 offset:56320
	global_load_lds_dwordx4 v[148:149], off
	s_add_i32 m0, s22, 0x2000
	s_add_u32 s20, s20, 0x40080
	v_lshl_add_u64 v[148:149], v[150:151], 0, s[0:1]
	s_addc_u32 s21, s21, 0
	s_add_i32 s22, s51, s26
	global_load_lds_dwordx4 v[148:149], off
	s_mov_b32 m0, s22
	v_lshl_add_u64 v[148:149], s[20:21], 0, v[168:169]
	global_load_lds_dwordx4 v[148:149], off
	s_add_i32 m0, s22, 0x2000
	v_lshl_add_u64 v[148:149], s[20:21], 0, v[0:1]
	global_load_lds_dwordx4 v[148:149], off
	s_mov_b32 m0, s40
	v_lshl_add_u64 v[148:149], v[226:227], 0, s[0:1]
	global_load_lds_dwordx4 v[148:149], off
	s_mov_b32 m0, s41
	v_lshl_add_u64 v[148:149], v[238:239], 0, s[0:1]
	global_load_lds_dwordx4 v[148:149], off
	s_waitcnt vmcnt(8)
	s_waitcnt lgkmcnt(0)
	s_barrier
	s_waitcnt lgkmcnt(0)
	v_mfma_f32_16x16x32_bf16 v[64:67], v[116:119], v[194:197], v[64:67]
	v_mfma_f32_16x16x32_bf16 v[60:63], v[124:127], v[194:197], v[60:63]
	v_mfma_f32_16x16x32_bf16 v[56:59], v[116:119], v[202:205], v[56:59]
	v_mfma_f32_16x16x32_bf16 v[48:51], v[124:127], v[202:205], v[48:51]
	v_mfma_f32_16x16x32_bf16 v[40:43], v[116:119], v[210:213], v[40:43]
	v_mfma_f32_16x16x32_bf16 v[32:35], v[124:127], v[210:213], v[32:35]
	v_mfma_f32_16x16x32_bf16 v[24:27], v[116:119], v[218:221], v[24:27]
	v_mfma_f32_16x16x32_bf16 v[16:19], v[124:127], v[218:221], v[16:19]
	v_mfma_f32_16x16x32_bf16 v[64:67], v[120:123], v[198:201], v[64:67]
	v_mfma_f32_16x16x32_bf16 v[60:63], v[132:135], v[198:201], v[60:63]
	v_mfma_f32_16x16x32_bf16 v[56:59], v[120:123], v[206:209], v[56:59]
	v_mfma_f32_16x16x32_bf16 v[48:51], v[132:135], v[206:209], v[48:51]
	v_mfma_f32_16x16x32_bf16 v[40:43], v[120:123], v[214:217], v[40:43]
	v_mfma_f32_16x16x32_bf16 v[32:35], v[132:135], v[214:217], v[32:35]
	v_mfma_f32_16x16x32_bf16 v[24:27], v[120:123], v[222:225], v[24:27]
	v_mfma_f32_16x16x32_bf16 v[16:19], v[132:135], v[222:225], v[16:19]
	v_mfma_f32_16x16x32_bf16 v[52:55], v[178:181], v[194:197], v[52:55]
	v_mfma_f32_16x16x32_bf16 v[44:47], v[186:189], v[194:197], v[44:47]
	v_mfma_f32_16x16x32_bf16 v[36:39], v[178:181], v[202:205], v[36:39]
	v_mfma_f32_16x16x32_bf16 v[28:31], v[186:189], v[202:205], v[28:31]
	v_mfma_f32_16x16x32_bf16 v[20:23], v[178:181], v[210:213], v[20:23]
	v_mfma_f32_16x16x32_bf16 v[12:15], v[186:189], v[210:213], v[12:15]
	v_mfma_f32_16x16x32_bf16 v[8:11], v[178:181], v[218:221], v[8:11]
	v_mfma_f32_16x16x32_bf16 v[4:7], v[186:189], v[218:221], v[4:7]
	v_mfma_f32_16x16x32_bf16 v[52:55], v[182:185], v[198:201], v[52:55]
	v_mfma_f32_16x16x32_bf16 v[44:47], v[190:193], v[198:201], v[44:47]
	v_mfma_f32_16x16x32_bf16 v[36:39], v[182:185], v[206:209], v[36:39]
	v_mfma_f32_16x16x32_bf16 v[28:31], v[190:193], v[206:209], v[28:31]
	v_mfma_f32_16x16x32_bf16 v[20:23], v[182:185], v[214:217], v[20:23]
	v_mfma_f32_16x16x32_bf16 v[12:15], v[190:193], v[214:217], v[12:15]
	v_mfma_f32_16x16x32_bf16 v[8:11], v[182:185], v[222:225], v[8:11]
	v_mfma_f32_16x16x32_bf16 v[4:7], v[190:193], v[222:225], v[4:7]
	s_barrier
	s_add_i32 s49, s49, 2
	s_add_u32 s18, s18, 0x100
	s_addc_u32 s19, s19, 0
	s_add_u32 s47, s47, 0x100
	s_addc_u32 s48, s48, 0
	s_cmp_gt_u32 s49, 13
	s_cbranch_scc0 .LBB0_99
	s_branch .Lpeel_exit0
.LBB0_99:
	s_add_u32 s20, s18, 0xfffc0080
	s_addc_u32 s21, s19, -1
	s_add_i32 s50, 0, 0x10000
	s_cmp_eq_u32 s49, 12
	s_cselect_b32 s23, s13, s21
	s_cselect_b32 s22, s45, s20
	s_cselect_b32 s21, s11, s48
	s_cselect_b32 s20, s46, s47
	s_add_i32 s52, 0, 0x14000
	v_add_u32_e32 v132, s50, v153
	v_add_u32_e32 v148, s52, v153
	ds_read_b128 v[116:119], v132
	ds_read_b128 v[120:123], v132 offset:1024
	ds_read_b128 v[124:127], v132 offset:2048
	ds_read_b128 v[132:135], v132 offset:3072
	ds_read_b128 v[178:181], v148
	ds_read_b128 v[182:185], v148 offset:1024
	ds_read_b128 v[186:189], v148 offset:2048
	ds_read_b128 v[190:193], v148 offset:3072
	v_lshl_add_u64 v[148:149], s[18:19], 0, v[172:173]
	s_add_i32 m0, s36, 0xc000
	ds_read_b128 v[194:197], v176
	ds_read_b128 v[198:201], v176 offset:1024
	ds_read_b128 v[202:205], v176 offset:2048
	ds_read_b128 v[206:209], v176 offset:3072
	ds_read_b128 v[210:213], v176 offset:4096
	ds_read_b128 v[214:217], v176 offset:5120
	ds_read_b128 v[218:221], v176 offset:6144
	ds_read_b128 v[222:225], v176 offset:7168
	global_load_lds_dwordx4 v[148:149], off
	s_add_i32 m0, s36, 0xe000
	v_lshl_add_u64 v[148:149], s[18:19], 0, v[174:175]
	global_load_lds_dwordx4 v[148:149], off
	s_waitcnt vmcnt(8)
	s_waitcnt lgkmcnt(0)
	s_barrier
; #define PG8_STAGE(bufoff, gbase, voff) do { _Pragma("unroll") for (int _i = 0; _i < 2; ++_i) \
;         __builtin_amdgcn_global_load_lds((const unsigned*)((const char*)(gbase) + (voff)[_i]), (PG8_LAS unsigned*)(lds + (bufoff) + ldsw + _i * 8192), 16, 0, 0); } while (0)
; #define PG8_LDA(dst, b, h) do { _Pragma("unroll") for (int m = 0; m < 4; ++m) _Pragma("unroll") for (int k = 0; k < 2; ++k) dst[m][k] = *(const PG8_LAS bf16x8*)(lds + PG8_SA(b, h) + aoff + m * 2048 + k * 1024); } while (0)
; #define PG8_MMA(ai, bj, At, Bt) do { __builtin_amdgcn_s_setprio(1); _Pragma("unroll") for (int m = 0; m < 4; ++m) _Pragma("unroll") for (int n = 0; n < 2; ++n) _Pragma("unroll") for (int k = 0; k < 2; ++k) \
;         acc[ai][bj][m][n] = __builtin_amdgcn_mfma_f32_16x16x32_bf16(Bt[n][k], At[m][k], acc[ai][bj][m][n], 0, 0, 0); __builtin_amdgcn_s_setprio(0); } while (0)
; #define PG8_WAIT_V(n) asm volatile("s_waitcnt vmcnt(" #n ")" ::: "memory")
; #define PG8_WAIT_L(n) asm volatile("s_waitcnt lgkmcnt(" #n ")" ::: "memory")
; #define PG8_BAR __builtin_amdgcn_s_barrier()
; #define PG8_SCHED __builtin_amdgcn_sched_barrier(0)
; template <class Epi, class Sched, bool ALIGN_EPI = false, bool SP2 = false>
; __device__ __forceinline__ void gemm_phase(PG8_LAS unsigned char* lds, const Gemm g, const Sched& S, const Epi& E, const int tid) {
;     ...
;             PG8_WAIT_V(8); PG8_WAIT_L(0); PG8_BAR; PG8_MMA(0, 0, At, B0); PG8_MMA(0, 1, At, B1); PG8_BAR; PG8_SCHED;
;             PG8_LDA(At, 0, 1); PG8_STAGE(PG8_SB(0, 0), b2, voffB); PG8_STAGE(PG8_SB(0, 1), b2 + hstep, voffB); PG8_STAGE(PG8_SA(0, 0), a2, voffA);
;             PG8_WAIT_V(8); PG8_WAIT_L(0); PG8_BAR; PG8_MMA(1, 0, At, B0); PG8_MMA(1, 1, At, B1); PG8_BAR; PG8_SCHED;
	s_waitcnt lgkmcnt(0)
	v_mfma_f32_16x16x32_bf16 v[144:147], v[116:119], v[194:197], v[144:147]
	v_mfma_f32_16x16x32_bf16 v[140:143], v[124:127], v[194:197], v[140:143]
	v_mfma_f32_16x16x32_bf16 v[112:115], v[116:119], v[202:205], v[112:115]
	v_mfma_f32_16x16x32_bf16 v[108:111], v[124:127], v[202:205], v[108:111]
	v_mfma_f32_16x16x32_bf16 v[96:99], v[116:119], v[210:213], v[96:99]
	v_mfma_f32_16x16x32_bf16 v[92:95], v[124:127], v[210:213], v[92:95]
	v_mfma_f32_16x16x32_bf16 v[80:83], v[116:119], v[218:221], v[80:83]
	v_mfma_f32_16x16x32_bf16 v[76:79], v[124:127], v[218:221], v[76:79]
	v_mfma_f32_16x16x32_bf16 v[144:147], v[120:123], v[198:201], v[144:147]
	v_mfma_f32_16x16x32_bf16 v[140:143], v[132:135], v[198:201], v[140:143]
	v_mfma_f32_16x16x32_bf16 v[112:115], v[120:123], v[206:209], v[112:115]
	v_mfma_f32_16x16x32_bf16 v[108:111], v[132:135], v[206:209], v[108:111]
	v_mfma_f32_16x16x32_bf16 v[96:99], v[120:123], v[214:217], v[96:99]
	v_mfma_f32_16x16x32_bf16 v[92:95], v[132:135], v[214:217], v[92:95]
	v_mfma_f32_16x16x32_bf16 v[80:83], v[120:123], v[222:225], v[80:83]
	v_mfma_f32_16x16x32_bf16 v[76:79], v[132:135], v[222:225], v[76:79]
	v_mfma_f32_16x16x32_bf16 v[136:139], v[178:181], v[194:197], v[136:139]
	v_mfma_f32_16x16x32_bf16 v[128:131], v[186:189], v[194:197], v[128:131]
	v_mfma_f32_16x16x32_bf16 v[104:107], v[178:181], v[202:205], v[104:107]
	v_mfma_f32_16x16x32_bf16 v[100:103], v[186:189], v[202:205], v[100:103]
	v_mfma_f32_16x16x32_bf16 v[88:91], v[178:181], v[210:213], v[88:91]
	v_mfma_f32_16x16x32_bf16 v[84:87], v[186:189], v[210:213], v[84:87]
	v_mfma_f32_16x16x32_bf16 v[72:75], v[178:181], v[218:221], v[72:75]
	v_mfma_f32_16x16x32_bf16 v[68:71], v[186:189], v[218:221], v[68:71]
	v_mfma_f32_16x16x32_bf16 v[136:139], v[182:185], v[198:201], v[136:139]
	v_mfma_f32_16x16x32_bf16 v[128:131], v[190:193], v[198:201], v[128:131]
	v_mfma_f32_16x16x32_bf16 v[104:107], v[182:185], v[206:209], v[104:107]
	v_mfma_f32_16x16x32_bf16 v[100:103], v[190:193], v[206:209], v[100:103]
	v_mfma_f32_16x16x32_bf16 v[88:91], v[182:185], v[214:217], v[88:91]
	v_mfma_f32_16x16x32_bf16 v[84:87], v[190:193], v[214:217], v[84:87]
	v_mfma_f32_16x16x32_bf16 v[72:75], v[182:185], v[222:225], v[72:75]
	v_mfma_f32_16x16x32_bf16 v[68:71], v[190:193], v[222:225], v[68:71]
	s_barrier
	s_add_i32 s50, s50, s26
	v_lshl_add_u64 v[148:149], s[20:21], 0, v[168:169]
	s_mov_b32 m0, s50
	ds_read_b128 v[194:197], v176 offset:16384
	ds_read_b128 v[198:201], v176 offset:17408
	ds_read_b128 v[202:205], v176 offset:18432
	ds_read_b128 v[206:209], v176 offset:19456
	ds_read_b128 v[210:213], v176 offset:20480
	ds_read_b128 v[214:217], v176 offset:21504
	ds_read_b128 v[218:221], v176 offset:22528
	ds_read_b128 v[222:225], v176 offset:23552
	global_load_lds_dwordx4 v[148:149], off
	s_add_i32 m0, s50, 0x2000
	s_add_u32 s50, s20, 0x40000
	v_lshl_add_u64 v[150:151], s[20:21], 0, v[0:1]
	s_addc_u32 s51, s21, 0
	s_add_i32 s52, s52, s26
	global_load_lds_dwordx4 v[150:151], off
	v_lshl_add_u64 v[226:227], s[50:51], 0, v[168:169]
	s_mov_b32 m0, s52
	v_lshl_add_u64 v[238:239], s[22:23], 0, v[166:167]
	global_load_lds_dwordx4 v[226:227], off
	s_add_i32 m0, s52, 0x2000
	v_lshl_add_u64 v[226:227], s[50:51], 0, v[0:1]
	global_load_lds_dwordx4 v[226:227], off
	s_mov_b32 m0, s36
	v_lshl_add_u64 v[226:227], s[22:23], 0, v[170:171]
	global_load_lds_dwordx4 v[226:227], off
	s_mov_b32 m0, s37
	s_nop 0
	global_load_lds_dwordx4 v[238:239], off
	s_waitcnt vmcnt(8)
	s_waitcnt lgkmcnt(0)
	s_barrier
	s_waitcnt lgkmcnt(0)
	v_mfma_f32_16x16x32_bf16 v[64:67], v[116:119], v[194:197], v[64:67]
	v_mfma_f32_16x16x32_bf16 v[60:63], v[124:127], v[194:197], v[60:63]
	v_mfma_f32_16x16x32_bf16 v[56:59], v[116:119], v[202:205], v[56:59]
	v_mfma_f32_16x16x32_bf16 v[48:51], v[124:127], v[202:205], v[48:51]
	v_mfma_f32_16x16x32_bf16 v[40:43], v[116:119], v[210:213], v[40:43]
	v_mfma_f32_16x16x32_bf16 v[32:35], v[124:127], v[210:213], v[32:35]
	v_mfma_f32_16x16x32_bf16 v[24:27], v[116:119], v[218:221], v[24:27]
	v_mfma_f32_16x16x32_bf16 v[16:19], v[124:127], v[218:221], v[16:19]
	v_mfma_f32_16x16x32_bf16 v[64:67], v[120:123], v[198:201], v[64:67]
	v_mfma_f32_16x16x32_bf16 v[60:63], v[132:135], v[198:201], v[60:63]
	v_mfma_f32_16x16x32_bf16 v[56:59], v[120:123], v[206:209], v[56:59]
	v_mfma_f32_16x16x32_bf16 v[48:51], v[132:135], v[206:209], v[48:51]
	v_mfma_f32_16x16x32_bf16 v[40:43], v[120:123], v[214:217], v[40:43]
	v_mfma_f32_16x16x32_bf16 v[32:35], v[132:135], v[214:217], v[32:35]
	v_mfma_f32_16x16x32_bf16 v[24:27], v[120:123], v[222:225], v[24:27]
	v_mfma_f32_16x16x32_bf16 v[16:19], v[132:135], v[222:225], v[16:19]
	v_mfma_f32_16x16x32_bf16 v[52:55], v[178:181], v[194:197], v[52:55]
	v_mfma_f32_16x16x32_bf16 v[44:47], v[186:189], v[194:197], v[44:47]
	v_mfma_f32_16x16x32_bf16 v[36:39], v[178:181], v[202:205], v[36:39]
	v_mfma_f32_16x16x32_bf16 v[28:31], v[186:189], v[202:205], v[28:31]
	v_mfma_f32_16x16x32_bf16 v[20:23], v[178:181], v[210:213], v[20:23]
	v_mfma_f32_16x16x32_bf16 v[12:15], v[186:189], v[210:213], v[12:15]
	v_mfma_f32_16x16x32_bf16 v[8:11], v[178:181], v[218:221], v[8:11]
	v_mfma_f32_16x16x32_bf16 v[4:7], v[186:189], v[218:221], v[4:7]
	v_mfma_f32_16x16x32_bf16 v[52:55], v[182:185], v[198:201], v[52:55]
	v_mfma_f32_16x16x32_bf16 v[44:47], v[190:193], v[198:201], v[44:47]
	v_mfma_f32_16x16x32_bf16 v[36:39], v[182:185], v[206:209], v[36:39]
	v_mfma_f32_16x16x32_bf16 v[28:31], v[190:193], v[206:209], v[28:31]
	v_mfma_f32_16x16x32_bf16 v[20:23], v[182:185], v[214:217], v[20:23]
	v_mfma_f32_16x16x32_bf16 v[12:15], v[190:193], v[214:217], v[12:15]
	v_mfma_f32_16x16x32_bf16 v[8:11], v[182:185], v[222:225], v[8:11]
	v_mfma_f32_16x16x32_bf16 v[4:7], v[190:193], v[222:225], v[4:7]
	s_barrier
; #define PG8_STAGE(bufoff, gbase, voff) do { _Pragma("unroll") for (int _i = 0; _i < 2; ++_i) \
;         __builtin_amdgcn_global_load_lds((const unsigned*)((const char*)(gbase) + (voff)[_i]), (PG8_LAS unsigned*)(lds + (bufoff) + ldsw + _i * 8192), 16, 0, 0); } while (0)
; #define PG8_LDA(dst, b, h) do { _Pragma("unroll") for (int m = 0; m < 4; ++m) _Pragma("unroll") for (int k = 0; k < 2; ++k) dst[m][k] = *(const PG8_LAS bf16x8*)(lds + PG8_SA(b, h) + aoff + m * 2048 + k * 1024); } while (0)
; #define PG8_LDB(dst, b, h) do { _Pragma("unroll") for (int n = 0; n < 2; ++n) _Pragma("unroll") for (int k = 0; k < 2; ++k) dst[n][k] = *(const PG8_LAS bf16x8*)(lds + PG8_SB(b, h) + boff + n * 2048 + k * 1024); } while (0)
; #define PG8_MMA(ai, bj, At, Bt) do { __builtin_amdgcn_s_setprio(1); _Pragma("unroll") for (int m = 0; m < 4; ++m) _Pragma("unroll") for (int n = 0; n < 2; ++n) _Pragma("unroll") for (int k = 0; k < 2; ++k) \
;         acc[ai][bj][m][n] = __builtin_amdgcn_mfma_f32_16x16x32_bf16(Bt[n][k], At[m][k], acc[ai][bj][m][n], 0, 0, 0); __builtin_amdgcn_s_setprio(0); } while (0)
; #define PG8_WAIT_V(n) asm volatile("s_waitcnt vmcnt(" #n ")" ::: "memory")
; #define PG8_WAIT_L(n) asm volatile("s_waitcnt lgkmcnt(" #n ")" ::: "memory")
; #define PG8_BAR __builtin_amdgcn_s_barrier()
; #define PG8_SCHED __builtin_amdgcn_sched_barrier(0)
; template <class Epi, class Sched, bool ALIGN_EPI = false, bool SP2 = false>
; __device__ __forceinline__ void gemm_phase(PG8_LAS unsigned char* lds, const Gemm g, const Sched& S, const Epi& E, const int tid) {
;     ...
;             PG8_LDB(B0, 1, 0); PG8_LDB(B1, 1, 1); PG8_SCHED; PG8_LDA(At, 1, 0); PG8_STAGE(PG8_SA(0, 1), a2 + hstep, voffA);
;             PG8_WAIT_V(8); PG8_WAIT_L(0); PG8_BAR; PG8_MMA(0, 0, At, B0); PG8_MMA(0, 1, At, B1); PG8_BAR; PG8_SCHED;
;             PG8_LDA(At, 1, 1); PG8_STAGE(PG8_SB(1, 0), b3, voffB); PG8_STAGE(PG8_SB(1, 1), b3 + hstep, voffB); PG8_STAGE(PG8_SA(1, 0), a3, voffA);
;             PG8_WAIT_V(8); PG8_WAIT_L(0); PG8_BAR; PG8_MMA(1, 0, At, B0); PG8_MMA(1, 1, At, B1); PG8_BAR; PG8_SCHED;
	s_add_i32 s50, 0, 0x18000
	s_add_i32 s51, 0, 0x1c000
	v_add_u32_e32 v132, s50, v153
	v_add_u32_e32 v177, s51, v153
	ds_read_b128 v[116:119], v132
	ds_read_b128 v[120:123], v132 offset:1024
	ds_read_b128 v[124:127], v132 offset:2048
	ds_read_b128 v[132:135], v132 offset:3072
	ds_read_b128 v[178:181], v177
	ds_read_b128 v[182:185], v177 offset:1024
	ds_read_b128 v[186:189], v177 offset:2048
	ds_read_b128 v[190:193], v177 offset:3072
	s_add_u32 s22, s22, 0x40000
	s_addc_u32 s23, s23, 0
	s_mov_b32 m0, s38
	v_lshl_add_u64 v[240:241], s[22:23], 0, v[170:171]
	ds_read_b128 v[194:197], v176 offset:32768
	ds_read_b128 v[198:201], v176 offset:33792
	ds_read_b128 v[202:205], v176 offset:34816
	ds_read_b128 v[206:209], v176 offset:35840
	ds_read_b128 v[210:213], v176 offset:36864
	ds_read_b128 v[214:217], v176 offset:37888
	ds_read_b128 v[218:221], v176 offset:38912
	ds_read_b128 v[222:225], v176 offset:39936
	global_load_lds_dwordx4 v[240:241], off
	s_mov_b32 m0, s39
	v_lshl_add_u64 v[240:241], s[22:23], 0, v[166:167]
	global_load_lds_dwordx4 v[240:241], off
	s_waitcnt vmcnt(8)
	s_waitcnt lgkmcnt(0)
	s_barrier
	s_waitcnt lgkmcnt(0)
	v_mfma_f32_16x16x32_bf16 v[144:147], v[116:119], v[194:197], v[144:147]
	v_mfma_f32_16x16x32_bf16 v[140:143], v[124:127], v[194:197], v[140:143]
	v_mfma_f32_16x16x32_bf16 v[112:115], v[116:119], v[202:205], v[112:115]
	v_mfma_f32_16x16x32_bf16 v[108:111], v[124:127], v[202:205], v[108:111]
	v_mfma_f32_16x16x32_bf16 v[96:99], v[116:119], v[210:213], v[96:99]
	v_mfma_f32_16x16x32_bf16 v[92:95], v[124:127], v[210:213], v[92:95]
	v_mfma_f32_16x16x32_bf16 v[80:83], v[116:119], v[218:221], v[80:83]
	v_mfma_f32_16x16x32_bf16 v[76:79], v[124:127], v[218:221], v[76:79]
	v_mfma_f32_16x16x32_bf16 v[144:147], v[120:123], v[198:201], v[144:147]
	v_mfma_f32_16x16x32_bf16 v[140:143], v[132:135], v[198:201], v[140:143]
	v_mfma_f32_16x16x32_bf16 v[112:115], v[120:123], v[206:209], v[112:115]
	v_mfma_f32_16x16x32_bf16 v[108:111], v[132:135], v[206:209], v[108:111]
	v_mfma_f32_16x16x32_bf16 v[96:99], v[120:123], v[214:217], v[96:99]
	v_mfma_f32_16x16x32_bf16 v[92:95], v[132:135], v[214:217], v[92:95]
	v_mfma_f32_16x16x32_bf16 v[80:83], v[120:123], v[222:225], v[80:83]
	v_mfma_f32_16x16x32_bf16 v[76:79], v[132:135], v[222:225], v[76:79]
	v_mfma_f32_16x16x32_bf16 v[136:139], v[178:181], v[194:197], v[136:139]
	v_mfma_f32_16x16x32_bf16 v[128:131], v[186:189], v[194:197], v[128:131]
	v_mfma_f32_16x16x32_bf16 v[104:107], v[178:181], v[202:205], v[104:107]
	v_mfma_f32_16x16x32_bf16 v[100:103], v[186:189], v[202:205], v[100:103]
	v_mfma_f32_16x16x32_bf16 v[88:91], v[178:181], v[210:213], v[88:91]
	v_mfma_f32_16x16x32_bf16 v[84:87], v[186:189], v[210:213], v[84:87]
	v_mfma_f32_16x16x32_bf16 v[72:75], v[178:181], v[218:221], v[72:75]
	v_mfma_f32_16x16x32_bf16 v[68:71], v[186:189], v[218:221], v[68:71]
	v_mfma_f32_16x16x32_bf16 v[136:139], v[182:185], v[198:201], v[136:139]
	v_mfma_f32_16x16x32_bf16 v[128:131], v[190:193], v[198:201], v[128:131]
	v_mfma_f32_16x16x32_bf16 v[104:107], v[182:185], v[206:209], v[104:107]
	v_mfma_f32_16x16x32_bf16 v[100:103], v[190:193], v[206:209], v[100:103]
	v_mfma_f32_16x16x32_bf16 v[88:91], v[182:185], v[214:217], v[88:91]
	v_mfma_f32_16x16x32_bf16 v[84:87], v[190:193], v[214:217], v[84:87]
	v_mfma_f32_16x16x32_bf16 v[72:75], v[182:185], v[222:225], v[72:75]
	v_mfma_f32_16x16x32_bf16 v[68:71], v[190:193], v[222:225], v[68:71]
	s_barrier
	s_add_i32 s22, s50, s26
	v_lshl_add_u64 v[148:149], v[148:149], 0, s[0:1]
	s_mov_b32 m0, s22
	ds_read_b128 v[194:197], v176 offset:49152
	ds_read_b128 v[198:201], v176 offset:50176
	ds_read_b128 v[202:205], v176 offset:51200
	ds_read_b128 v[206:209], v176 offset:52224
	ds_read_b128 v[210:213], v176 offset:53248
	ds_read_b128 v[214:217], v176 offset:54272
	ds_read_b128 v[218:221], v176 offset:55296
	ds_read_b128 v[222:225], v176 offset:56320
	global_load_lds_dwordx4 v[148:149], off
	s_add_i32 m0, s22, 0x2000
	s_add_u32 s20, s20, 0x40080
	v_lshl_add_u64 v[148:149], v[150:151], 0, s[0:1]
	s_addc_u32 s21, s21, 0
	s_add_i32 s22, s51, s26
	global_load_lds_dwordx4 v[148:149], off
	s_mov_b32 m0, s22
	v_lshl_add_u64 v[148:149], s[20:21], 0, v[168:169]
	global_load_lds_dwordx4 v[148:149], off
	s_add_i32 m0, s22, 0x2000
	v_lshl_add_u64 v[148:149], s[20:21], 0, v[0:1]
	global_load_lds_dwordx4 v[148:149], off
	s_mov_b32 m0, s40
	v_lshl_add_u64 v[148:149], v[226:227], 0, s[0:1]
	global_load_lds_dwordx4 v[148:149], off
	s_mov_b32 m0, s41
	v_lshl_add_u64 v[148:149], v[238:239], 0, s[0:1]
	global_load_lds_dwordx4 v[148:149], off
	s_waitcnt vmcnt(8)
	s_waitcnt lgkmcnt(0)
	s_barrier
	s_waitcnt lgkmcnt(0)
	v_mfma_f32_16x16x32_bf16 v[64:67], v[116:119], v[194:197], v[64:67]
	v_mfma_f32_16x16x32_bf16 v[60:63], v[124:127], v[194:197], v[60:63]
	v_mfma_f32_16x16x32_bf16 v[56:59], v[116:119], v[202:205], v[56:59]
	v_mfma_f32_16x16x32_bf16 v[48:51], v[124:127], v[202:205], v[48:51]
	v_mfma_f32_16x16x32_bf16 v[40:43], v[116:119], v[210:213], v[40:43]
	v_mfma_f32_16x16x32_bf16 v[32:35], v[124:127], v[210:213], v[32:35]
	v_mfma_f32_16x16x32_bf16 v[24:27], v[116:119], v[218:221], v[24:27]
	v_mfma_f32_16x16x32_bf16 v[16:19], v[124:127], v[218:221], v[16:19]
	v_mfma_f32_16x16x32_bf16 v[64:67], v[120:123], v[198:201], v[64:67]
	v_mfma_f32_16x16x32_bf16 v[60:63], v[132:135], v[198:201], v[60:63]
	v_mfma_f32_16x16x32_bf16 v[56:59], v[120:123], v[206:209], v[56:59]
	v_mfma_f32_16x16x32_bf16 v[48:51], v[132:135], v[206:209], v[48:51]
	v_mfma_f32_16x16x32_bf16 v[40:43], v[120:123], v[214:217], v[40:43]
	v_mfma_f32_16x16x32_bf16 v[32:35], v[132:135], v[214:217], v[32:35]
	v_mfma_f32_16x16x32_bf16 v[24:27], v[120:123], v[222:225], v[24:27]
	v_mfma_f32_16x16x32_bf16 v[16:19], v[132:135], v[222:225], v[16:19]
	v_mfma_f32_16x16x32_bf16 v[52:55], v[178:181], v[194:197], v[52:55]
	v_mfma_f32_16x16x32_bf16 v[44:47], v[186:189], v[194:197], v[44:47]
	v_mfma_f32_16x16x32_bf16 v[36:39], v[178:181], v[202:205], v[36:39]
	v_mfma_f32_16x16x32_bf16 v[28:31], v[186:189], v[202:205], v[28:31]
	v_mfma_f32_16x16x32_bf16 v[20:23], v[178:181], v[210:213], v[20:23]
	v_mfma_f32_16x16x32_bf16 v[12:15], v[186:189], v[210:213], v[12:15]
	v_mfma_f32_16x16x32_bf16 v[8:11], v[178:181], v[218:221], v[8:11]
	v_mfma_f32_16x16x32_bf16 v[4:7], v[186:189], v[218:221], v[4:7]
	v_mfma_f32_16x16x32_bf16 v[52:55], v[182:185], v[198:201], v[52:55]
	v_mfma_f32_16x16x32_bf16 v[44:47], v[190:193], v[198:201], v[44:47]
	v_mfma_f32_16x16x32_bf16 v[36:39], v[182:185], v[206:209], v[36:39]
	v_mfma_f32_16x16x32_bf16 v[28:31], v[190:193], v[206:209], v[28:31]
	v_mfma_f32_16x16x32_bf16 v[20:23], v[182:185], v[214:217], v[20:23]
	v_mfma_f32_16x16x32_bf16 v[12:15], v[190:193], v[214:217], v[12:15]
	v_mfma_f32_16x16x32_bf16 v[8:11], v[182:185], v[222:225], v[8:11]
	v_mfma_f32_16x16x32_bf16 v[4:7], v[190:193], v[222:225], v[4:7]
	s_barrier
	s_add_i32 s49, s49, 2
	s_add_u32 s18, s18, 0x100
	s_addc_u32 s19, s19, 0
	s_add_u32 s47, s47, 0x100
	s_addc_u32 s48, s48, 0
	s_cmp_gt_u32 s49, 13
	s_cbranch_scc0 .LBB0_99

; #define PG8_STAGE(bufoff, gbase, voff) do { _Pragma("unroll") for (int _i = 0; _i < 2; ++_i) \
;         __builtin_amdgcn_global_load_lds((const unsigned*)((const char*)(gbase) + (voff)[_i]), (PG8_LAS unsigned*)(lds + (bufoff) + ldsw + _i * 8192), 16, 0, 0); } while (0)
; #define PG8_LDA(dst, b, h) do { _Pragma("unroll") for (int m = 0; m < 4; ++m) _Pragma("unroll") for (int k = 0; k < 2; ++k) dst[m][k] = *(const PG8_LAS bf16x8*)(lds + PG8_SA(b, h) + aoff + m * 2048 + k * 1024); } while (0)
; #define PG8_LDB(dst, b, h) do { _Pragma("unroll") for (int n = 0; n < 2; ++n) _Pragma("unroll") for (int k = 0; k < 2; ++k) dst[n][k] = *(const PG8_LAS bf16x8*)(lds + PG8_SB(b, h) + boff + n * 2048 + k * 1024); } while (0)
; #define PG8_WAIT_V(n) asm volatile("s_waitcnt vmcnt(" #n ")" ::: "memory")
; #define PG8_WAIT_L(n) asm volatile("s_waitcnt lgkmcnt(" #n ")" ::: "memory")
; #define PG8_BAR __builtin_amdgcn_s_barrier()
; #define PG8_SCHED __builtin_amdgcn_sched_barrier(0)
; template <class Epi, class Sched, bool ALIGN_EPI = false, bool SP2 = false>
; __device__ __forceinline__ void gemm_phase(PG8_LAS unsigned char* lds, const Gemm g, const Sched& S, const Epi& E, const int tid) {
;     ...
;         const bool has_next = S.next(ui + 1, nxt);
;         const char* nA = has_next ? (const char*)g.A + (size_t)nxt.pm * tstep : cA; const char* nB = has_next ? (const char*)g.Bt + (size_t)nxt.pn * tstep : cB;
;         for (int t = 0; t < nt; t += 2) {
;             const bool last = (t == nt - 2);
;             const char* a1 = cA + (size_t)(t + 1) * kstep;
;             const char* a2 = last ? nA : cA + (size_t)(t + 2) * kstep; const char* b2 = last ? nB : cB + (size_t)(t + 2) * kstep;
;             const char* a3 = a2 + kstep; const char* b3 = b2 + kstep;
;             if (last && has_next) S.a_ready(nxt);
;             if constexpr (SP2) {
;             PG8_LDB(B0, 0, 0); PG8_LDB(B1, 0, 1); PG8_SCHED; PG8_LDA(At, 0, 0); PG8_STAGE(PG8_SA(1, 1), a1 + hstep, voffA);
;             PG8_WAIT_V(8); PG8_WAIT_L(0); PG8_BAR; PG8_MMA(0, 0, At, B0); PG8_MMA(0, 1, At, B1); PG8_BAR; PG8_SCHED;
;             PG8_LDA(At, 0, 1); PG8_STAGE(PG8_SB(0, 0), b2, voffB); PG8_STAGE(PG8_SB(0, 1), b2 + hstep, voffB); PG8_STAGE(PG8_SA(0, 0), a2, voffA);
;             PG8_WAIT_V(8); PG8_WAIT_L(0); PG8_BAR; PG8_MMA(1, 0, At, B0); PG8_MMA(1, 1, At, B1); PG8_BAR; PG8_SCHED;
.LBB0_292:
	s_ashr_i32 s17, s16, 31
	s_lshl_b64 s[18:19], s[16:17], 19
	s_add_u32 s18, s34, s18
	s_addc_u32 s19, s40, s19
	s_and_b64 s[20:21], s[4:5], exec
	s_cselect_b32 s17, s19, s3
	s_cselect_b32 s23, s18, s2
	s_ashr_i32 s15, s14, 31
	s_lshl_b64 s[20:21], s[14:15], 19
	s_add_u32 s20, s41, s20
	s_addc_u32 s21, s42, s21
	s_and_b64 s[36:37], s[4:5], exec
	s_cselect_b32 s15, s21, s27
	s_cselect_b32 s51, s20, s26
	s_add_u32 s2, s2, 0x40080
	s_addc_u32 s3, s3, 0
	s_add_u32 s52, s26, 0x100
	v_mov_b32_e32 v12, 0
	s_addc_u32 s53, s27, 0
	s_mov_b32 s54, -2
	s_add_u32 s26, s2, 0xfffc0080
	s_addc_u32 s27, s3, -1
	s_add_i32 s55, 0, 0x10000
	s_cmp_eq_u32 s54, 12
	s_cselect_b32 s37, s17, s27
	s_cselect_b32 s36, s23, s26
	v_add_u32_e32 v146, s55, v165
	s_cselect_b32 s27, s15, s53
	s_cselect_b32 s26, s51, s52
	s_add_i32 s58, 0, 0x14000
	ds_read_b128 v[166:169], v146
	ds_read_b128 v[172:175], v146 offset:1024
	ds_read_b128 v[176:179], v146 offset:2048
	ds_read_b128 v[180:183], v146 offset:3072
	v_add_u32_e32 v146, s58, v165
	ds_read_b128 v[184:187], v146
	ds_read_b128 v[188:191], v146 offset:1024
	ds_read_b128 v[192:195], v146 offset:2048
	ds_read_b128 v[196:199], v146 offset:3072
	v_lshl_add_u64 v[146:147], s[2:3], 0, v[142:143]
	s_add_i32 m0, s25, 0xc000
	ds_read_b128 v[200:203], v171
	ds_read_b128 v[204:207], v171 offset:1024
	ds_read_b128 v[208:211], v171 offset:2048
	ds_read_b128 v[212:215], v171 offset:3072
	ds_read_b128 v[216:219], v171 offset:4096
	ds_read_b128 v[220:223], v171 offset:5120
	ds_read_b128 v[224:227], v171 offset:6144
	ds_read_b128 v[238:241], v171 offset:7168
	global_load_lds_dwordx4 v[146:147], off
	s_add_i32 m0, s25, 0xe000
	v_lshl_add_u64 v[146:147], s[2:3], 0, v[144:145]
	global_load_lds_dwordx4 v[146:147], off
	s_waitcnt vmcnt(8)
	s_waitcnt lgkmcnt(0)
	s_barrier
	s_waitcnt lgkmcnt(0)
	v_mfma_f32_16x16x32_bf16 v[72:75], v[166:169], v[200:203], 0
	v_mfma_f32_16x16x32_bf16 v[68:71], v[176:179], v[200:203], 0
	v_mfma_f32_16x16x32_bf16 v[64:67], v[166:169], v[208:211], 0
	v_mfma_f32_16x16x32_bf16 v[60:63], v[176:179], v[208:211], 0
	v_mfma_f32_16x16x32_bf16 v[56:59], v[166:169], v[216:219], 0
	v_mfma_f32_16x16x32_bf16 v[52:55], v[176:179], v[216:219], 0
	v_mfma_f32_16x16x32_bf16 v[48:51], v[166:169], v[224:227], 0
	v_mfma_f32_16x16x32_bf16 v[44:47], v[176:179], v[224:227], 0
	v_mfma_f32_16x16x32_bf16 v[72:75], v[172:175], v[204:207], v[72:75]
	v_mfma_f32_16x16x32_bf16 v[68:71], v[180:183], v[204:207], v[68:71]
	v_mfma_f32_16x16x32_bf16 v[64:67], v[172:175], v[212:215], v[64:67]
	v_mfma_f32_16x16x32_bf16 v[60:63], v[180:183], v[212:215], v[60:63]
	v_mfma_f32_16x16x32_bf16 v[56:59], v[172:175], v[220:223], v[56:59]
	v_mfma_f32_16x16x32_bf16 v[52:55], v[180:183], v[220:223], v[52:55]
	v_mfma_f32_16x16x32_bf16 v[48:51], v[172:175], v[238:241], v[48:51]
	v_mfma_f32_16x16x32_bf16 v[44:47], v[180:183], v[238:241], v[44:47]
	v_mfma_f32_16x16x32_bf16 v[128:131], v[184:187], v[200:203], 0
	v_mfma_f32_16x16x32_bf16 v[124:127], v[192:195], v[200:203], 0
	v_mfma_f32_16x16x32_bf16 v[120:123], v[184:187], v[208:211], 0
	v_mfma_f32_16x16x32_bf16 v[116:119], v[192:195], v[208:211], 0
	v_mfma_f32_16x16x32_bf16 v[112:115], v[184:187], v[216:219], 0
	v_mfma_f32_16x16x32_bf16 v[108:111], v[192:195], v[216:219], 0
	v_mfma_f32_16x16x32_bf16 v[104:107], v[184:187], v[224:227], 0
	v_mfma_f32_16x16x32_bf16 v[100:103], v[192:195], v[224:227], 0
	v_mfma_f32_16x16x32_bf16 v[128:131], v[188:191], v[204:207], v[128:131]
	v_mfma_f32_16x16x32_bf16 v[124:127], v[196:199], v[204:207], v[124:127]
	v_mfma_f32_16x16x32_bf16 v[120:123], v[188:191], v[212:215], v[120:123]
	v_mfma_f32_16x16x32_bf16 v[116:119], v[196:199], v[212:215], v[116:119]
	v_mfma_f32_16x16x32_bf16 v[112:115], v[188:191], v[220:223], v[112:115]
	v_mfma_f32_16x16x32_bf16 v[108:111], v[196:199], v[220:223], v[108:111]
	v_mfma_f32_16x16x32_bf16 v[104:107], v[188:191], v[238:241], v[104:107]
	v_mfma_f32_16x16x32_bf16 v[100:103], v[196:199], v[238:241], v[100:103]
	s_barrier
	s_add_i32 s55, s55, s43
	v_lshl_add_u64 v[146:147], s[26:27], 0, v[132:133]
	s_mov_b32 m0, s55
	ds_read_b128 v[200:203], v171 offset:16384
	ds_read_b128 v[204:207], v171 offset:17408
	ds_read_b128 v[208:211], v171 offset:18432
	ds_read_b128 v[212:215], v171 offset:19456
	ds_read_b128 v[216:219], v171 offset:20480
	ds_read_b128 v[220:223], v171 offset:21504
	ds_read_b128 v[224:227], v171 offset:22528
	ds_read_b128 v[238:241], v171 offset:23552
	global_load_lds_dwordx4 v[146:147], off
	s_add_i32 m0, s55, 0x2000
	s_add_u32 s56, s26, 0x40000
	v_lshl_add_u64 v[148:149], s[26:27], 0, v[136:137]
	s_addc_u32 s57, s27, 0
	s_add_i32 s55, s58, s43
	global_load_lds_dwordx4 v[148:149], off
	v_lshl_add_u64 v[150:151], s[56:57], 0, v[132:133]
	s_mov_b32 m0, s55
	v_lshl_add_u64 v[242:243], s[36:37], 0, v[134:135]
	global_load_lds_dwordx4 v[150:151], off
	s_add_i32 m0, s55, 0x2000
	v_lshl_add_u64 v[150:151], s[56:57], 0, v[136:137]
	global_load_lds_dwordx4 v[150:151], off
	s_mov_b32 m0, s25
	v_lshl_add_u64 v[150:151], s[36:37], 0, v[0:1]
	global_load_lds_dwordx4 v[150:151], off
	s_mov_b32 m0, s44
	s_nop 0
	global_load_lds_dwordx4 v[242:243], off
	s_waitcnt vmcnt(8)
	s_waitcnt lgkmcnt(0)
	s_barrier
; #define PG8_STAGE(bufoff, gbase, voff) do { _Pragma("unroll") for (int _i = 0; _i < 2; ++_i) \
;         __builtin_amdgcn_global_load_lds((const unsigned*)((const char*)(gbase) + (voff)[_i]), (PG8_LAS unsigned*)(lds + (bufoff) + ldsw + _i * 8192), 16, 0, 0); } while (0)
; #define PG8_LDA(dst, b, h) do { _Pragma("unroll") for (int m = 0; m < 4; ++m) _Pragma("unroll") for (int k = 0; k < 2; ++k) dst[m][k] = *(const PG8_LAS bf16x8*)(lds + PG8_SA(b, h) + aoff + m * 2048 + k * 1024); } while (0)
; #define PG8_LDB(dst, b, h) do { _Pragma("unroll") for (int n = 0; n < 2; ++n) _Pragma("unroll") for (int k = 0; k < 2; ++k) dst[n][k] = *(const PG8_LAS bf16x8*)(lds + PG8_SB(b, h) + boff + n * 2048 + k * 1024); } while (0)
; #define PG8_MMA(ai, bj, At, Bt) do { __builtin_amdgcn_s_setprio(1); _Pragma("unroll") for (int m = 0; m < 4; ++m) _Pragma("unroll") for (int n = 0; n < 2; ++n) _Pragma("unroll") for (int k = 0; k < 2; ++k) \
;         acc[ai][bj][m][n] = __builtin_amdgcn_mfma_f32_16x16x32_bf16(Bt[n][k], At[m][k], acc[ai][bj][m][n], 0, 0, 0); __builtin_amdgcn_s_setprio(0); } while (0)
; #define PG8_WAIT_V(n) asm volatile("s_waitcnt vmcnt(" #n ")" ::: "memory")
; #define PG8_WAIT_L(n) asm volatile("s_waitcnt lgkmcnt(" #n ")" ::: "memory")
; #define PG8_BAR __builtin_amdgcn_s_barrier()
; #define PG8_SCHED __builtin_amdgcn_sched_barrier(0)
; template <class Epi, class Sched, bool ALIGN_EPI = false, bool SP2 = false>
; __device__ __forceinline__ void gemm_phase(PG8_LAS unsigned char* lds, const Gemm g, const Sched& S, const Epi& E, const int tid) {
;     ...
;             PG8_WAIT_V(8); PG8_WAIT_L(0); PG8_BAR; PG8_MMA(1, 0, At, B0); PG8_MMA(1, 1, At, B1); PG8_BAR; PG8_SCHED;
;             PG8_LDB(B0, 1, 0); PG8_LDB(B1, 1, 1); PG8_SCHED; PG8_LDA(At, 1, 0); PG8_STAGE(PG8_SA(0, 1), a2 + hstep, voffA);
;             PG8_WAIT_V(8); PG8_WAIT_L(0); PG8_BAR; PG8_MMA(0, 0, At, B0); PG8_MMA(0, 1, At, B1); PG8_BAR; PG8_SCHED;
	s_waitcnt lgkmcnt(0)
	v_mfma_f32_16x16x32_bf16 v[40:43], v[166:169], v[200:203], 0
	v_mfma_f32_16x16x32_bf16 v[36:39], v[176:179], v[200:203], 0
	v_mfma_f32_16x16x32_bf16 v[32:35], v[166:169], v[208:211], 0
	v_mfma_f32_16x16x32_bf16 v[28:31], v[176:179], v[208:211], 0
	v_mfma_f32_16x16x32_bf16 v[24:27], v[166:169], v[216:219], 0
	v_mfma_f32_16x16x32_bf16 v[20:23], v[176:179], v[216:219], 0
	v_mfma_f32_16x16x32_bf16 v[8:11], v[166:169], v[224:227], 0
	v_mfma_f32_16x16x32_bf16 v[4:7], v[176:179], v[224:227], 0
	v_mfma_f32_16x16x32_bf16 v[40:43], v[172:175], v[204:207], v[40:43]
	v_mfma_f32_16x16x32_bf16 v[36:39], v[180:183], v[204:207], v[36:39]
	v_mfma_f32_16x16x32_bf16 v[32:35], v[172:175], v[212:215], v[32:35]
	v_mfma_f32_16x16x32_bf16 v[28:31], v[180:183], v[212:215], v[28:31]
	v_mfma_f32_16x16x32_bf16 v[24:27], v[172:175], v[220:223], v[24:27]
	v_mfma_f32_16x16x32_bf16 v[20:23], v[180:183], v[220:223], v[20:23]
	v_mfma_f32_16x16x32_bf16 v[8:11], v[172:175], v[238:241], v[8:11]
	v_mfma_f32_16x16x32_bf16 v[4:7], v[180:183], v[238:241], v[4:7]
	v_mfma_f32_16x16x32_bf16 v[96:99], v[184:187], v[200:203], 0
	v_mfma_f32_16x16x32_bf16 v[92:95], v[192:195], v[200:203], 0
	v_mfma_f32_16x16x32_bf16 v[88:91], v[184:187], v[208:211], 0
	v_mfma_f32_16x16x32_bf16 v[84:87], v[192:195], v[208:211], 0
	v_mfma_f32_16x16x32_bf16 v[80:83], v[184:187], v[216:219], 0
	v_mfma_f32_16x16x32_bf16 v[76:79], v[192:195], v[216:219], 0
	v_mfma_f32_16x16x32_bf16 v[16:19], v[184:187], v[224:227], 0
	v_mfma_f32_16x16x32_bf16 v[12:15], v[192:195], v[224:227], 0
	v_mfma_f32_16x16x32_bf16 v[96:99], v[188:191], v[204:207], v[96:99]
	v_mfma_f32_16x16x32_bf16 v[92:95], v[196:199], v[204:207], v[92:95]
	v_mfma_f32_16x16x32_bf16 v[88:91], v[188:191], v[212:215], v[88:91]
	v_mfma_f32_16x16x32_bf16 v[84:87], v[196:199], v[212:215], v[84:87]
	v_mfma_f32_16x16x32_bf16 v[80:83], v[188:191], v[220:223], v[80:83]
	v_mfma_f32_16x16x32_bf16 v[76:79], v[196:199], v[220:223], v[76:79]
	v_mfma_f32_16x16x32_bf16 v[16:19], v[188:191], v[238:241], v[16:19]
	v_mfma_f32_16x16x32_bf16 v[12:15], v[196:199], v[238:241], v[12:15]
	s_barrier
	s_add_i32 s55, 0, 0x18000
	v_add_u32_e32 v153, s55, v165
	s_add_i32 s56, 0, 0x1c000
	ds_read_b128 v[166:169], v153
	ds_read_b128 v[172:175], v153 offset:1024
	ds_read_b128 v[176:179], v153 offset:2048
	ds_read_b128 v[180:183], v153 offset:3072
	v_add_u32_e32 v153, s56, v165
	ds_read_b128 v[184:187], v153
	ds_read_b128 v[188:191], v153 offset:1024
	ds_read_b128 v[192:195], v153 offset:2048
	ds_read_b128 v[196:199], v153 offset:3072
	s_add_u32 s36, s36, 0x40000
	s_addc_u32 s37, s37, 0
	s_mov_b32 m0, s45
	v_lshl_add_u64 v[244:245], s[36:37], 0, v[0:1]
	ds_read_b128 v[200:203], v171 offset:32768
	ds_read_b128 v[204:207], v171 offset:33792
	ds_read_b128 v[208:211], v171 offset:34816
	ds_read_b128 v[212:215], v171 offset:35840
	ds_read_b128 v[216:219], v171 offset:36864
	ds_read_b128 v[220:223], v171 offset:37888
	ds_read_b128 v[224:227], v171 offset:38912
	ds_read_b128 v[238:241], v171 offset:39936
	global_load_lds_dwordx4 v[244:245], off
	s_mov_b32 m0, s46
	v_lshl_add_u64 v[244:245], s[36:37], 0, v[134:135]
	global_load_lds_dwordx4 v[244:245], off
	s_waitcnt vmcnt(8)
	s_waitcnt lgkmcnt(0)
	s_barrier
	s_waitcnt lgkmcnt(0)
	v_mfma_f32_16x16x32_bf16 v[72:75], v[166:169], v[200:203], v[72:75]
	v_mfma_f32_16x16x32_bf16 v[68:71], v[176:179], v[200:203], v[68:71]
	v_mfma_f32_16x16x32_bf16 v[64:67], v[166:169], v[208:211], v[64:67]
	v_mfma_f32_16x16x32_bf16 v[60:63], v[176:179], v[208:211], v[60:63]
	v_mfma_f32_16x16x32_bf16 v[56:59], v[166:169], v[216:219], v[56:59]
	v_mfma_f32_16x16x32_bf16 v[52:55], v[176:179], v[216:219], v[52:55]
	v_mfma_f32_16x16x32_bf16 v[48:51], v[166:169], v[224:227], v[48:51]
	v_mfma_f32_16x16x32_bf16 v[44:47], v[176:179], v[224:227], v[44:47]
	v_mfma_f32_16x16x32_bf16 v[72:75], v[172:175], v[204:207], v[72:75]
	v_mfma_f32_16x16x32_bf16 v[68:71], v[180:183], v[204:207], v[68:71]
	v_mfma_f32_16x16x32_bf16 v[64:67], v[172:175], v[212:215], v[64:67]
	v_mfma_f32_16x16x32_bf16 v[60:63], v[180:183], v[212:215], v[60:63]
	v_mfma_f32_16x16x32_bf16 v[56:59], v[172:175], v[220:223], v[56:59]
	v_mfma_f32_16x16x32_bf16 v[52:55], v[180:183], v[220:223], v[52:55]
	v_mfma_f32_16x16x32_bf16 v[48:51], v[172:175], v[238:241], v[48:51]
	v_mfma_f32_16x16x32_bf16 v[44:47], v[180:183], v[238:241], v[44:47]
	v_mfma_f32_16x16x32_bf16 v[128:131], v[184:187], v[200:203], v[128:131]
	v_mfma_f32_16x16x32_bf16 v[124:127], v[192:195], v[200:203], v[124:127]
	v_mfma_f32_16x16x32_bf16 v[120:123], v[184:187], v[208:211], v[120:123]
	v_mfma_f32_16x16x32_bf16 v[116:119], v[192:195], v[208:211], v[116:119]
	v_mfma_f32_16x16x32_bf16 v[112:115], v[184:187], v[216:219], v[112:115]
	v_mfma_f32_16x16x32_bf16 v[108:111], v[192:195], v[216:219], v[108:111]
	v_mfma_f32_16x16x32_bf16 v[104:107], v[184:187], v[224:227], v[104:107]
	v_mfma_f32_16x16x32_bf16 v[100:103], v[192:195], v[224:227], v[100:103]
	v_mfma_f32_16x16x32_bf16 v[128:131], v[188:191], v[204:207], v[128:131]
	v_mfma_f32_16x16x32_bf16 v[124:127], v[196:199], v[204:207], v[124:127]
	v_mfma_f32_16x16x32_bf16 v[120:123], v[188:191], v[212:215], v[120:123]
	v_mfma_f32_16x16x32_bf16 v[116:119], v[196:199], v[212:215], v[116:119]
	v_mfma_f32_16x16x32_bf16 v[112:115], v[188:191], v[220:223], v[112:115]
	v_mfma_f32_16x16x32_bf16 v[108:111], v[196:199], v[220:223], v[108:111]
	v_mfma_f32_16x16x32_bf16 v[104:107], v[188:191], v[238:241], v[104:107]
	v_mfma_f32_16x16x32_bf16 v[100:103], v[196:199], v[238:241], v[100:103]
	s_barrier
; #define PG8_STAGE(bufoff, gbase, voff) do { _Pragma("unroll") for (int _i = 0; _i < 2; ++_i) \
;         __builtin_amdgcn_global_load_lds((const unsigned*)((const char*)(gbase) + (voff)[_i]), (PG8_LAS unsigned*)(lds + (bufoff) + ldsw + _i * 8192), 16, 0, 0); } while (0)
; #define PG8_LDA(dst, b, h) do { _Pragma("unroll") for (int m = 0; m < 4; ++m) _Pragma("unroll") for (int k = 0; k < 2; ++k) dst[m][k] = *(const PG8_LAS bf16x8*)(lds + PG8_SA(b, h) + aoff + m * 2048 + k * 1024); } while (0)
; #define PG8_WAIT_V(n) asm volatile("s_waitcnt vmcnt(" #n ")" ::: "memory")
; #define PG8_WAIT_L(n) asm volatile("s_waitcnt lgkmcnt(" #n ")" ::: "memory")
; #define PG8_BAR __builtin_amdgcn_s_barrier()
; template <class Epi, class Sched, bool ALIGN_EPI = false, bool SP2 = false>
; __device__ __forceinline__ void gemm_phase(PG8_LAS unsigned char* lds, const Gemm g, const Sched& S, const Epi& E, const int tid) {
;     ...
;         for (int t = 0; t < nt; t += 2) {
;             const bool last = (t == nt - 2);
;             const char* a1 = cA + (size_t)(t + 1) * kstep;
;             const char* a2 = last ? nA : cA + (size_t)(t + 2) * kstep; const char* b2 = last ? nB : cB + (size_t)(t + 2) * kstep;
;             const char* a3 = a2 + kstep; const char* b3 = b2 + kstep;
;             if (last && has_next) S.a_ready(nxt);
;             if constexpr (SP2) {
;             PG8_LDB(B0, 0, 0); PG8_LDB(B1, 0, 1); PG8_SCHED; PG8_LDA(At, 0, 0); PG8_STAGE(PG8_SA(1, 1), a1 + hstep, voffA);
;             PG8_WAIT_V(8); PG8_WAIT_L(0); PG8_BAR; PG8_MMA(0, 0, At, B0); PG8_MMA(0, 1, At, B1); PG8_BAR; PG8_SCHED;
;             PG8_LDA(At, 0, 1); PG8_STAGE(PG8_SB(0, 0), b2, voffB); PG8_STAGE(PG8_SB(0, 1), b2 + hstep, voffB); PG8_STAGE(PG8_SA(0, 0), a2, voffA);
;             PG8_WAIT_V(8); PG8_WAIT_L(0); PG8_BAR; PG8_MMA(1, 0, At, B0); PG8_MMA(1, 1, At, B1); PG8_BAR; PG8_SCHED;
;             PG8_LDB(B0, 1, 0); PG8_LDB(B1, 1, 1); PG8_SCHED; PG8_LDA(At, 1, 0); PG8_STAGE(PG8_SA(0, 1), a2 + hstep, voffA);
;             PG8_WAIT_V(8); PG8_WAIT_L(0); PG8_BAR; PG8_MMA(0, 0, At, B0); PG8_MMA(0, 1, At, B1); PG8_BAR; PG8_SCHED;
;             PG8_LDA(At, 1, 1); PG8_STAGE(PG8_SB(1, 0), b3, voffB); PG8_STAGE(PG8_SB(1, 1), b3 + hstep, voffB); PG8_STAGE(PG8_SA(1, 0), a3, voffA);
;             PG8_WAIT_V(8); PG8_WAIT_L(0); PG8_BAR; PG8_MMA(1, 0, At, B0); PG8_MMA(1, 1, At, B1); PG8_BAR; PG8_SCHED;
	s_add_i32 s36, s55, s43
	v_lshl_add_u64 v[146:147], v[146:147], 0, s[0:1]
	s_mov_b32 m0, s36
	ds_read_b128 v[200:203], v171 offset:49152
	ds_read_b128 v[204:207], v171 offset:50176
	ds_read_b128 v[208:211], v171 offset:51200
	ds_read_b128 v[212:215], v171 offset:52224
	ds_read_b128 v[216:219], v171 offset:53248
	ds_read_b128 v[220:223], v171 offset:54272
	ds_read_b128 v[224:227], v171 offset:55296
	ds_read_b128 v[238:241], v171 offset:56320
	global_load_lds_dwordx4 v[146:147], off
	s_add_i32 m0, s36, 0x2000
	s_add_u32 s26, s26, 0x40080
	v_lshl_add_u64 v[146:147], v[148:149], 0, s[0:1]
	s_addc_u32 s27, s27, 0
	s_add_i32 s36, s56, s43
	global_load_lds_dwordx4 v[146:147], off
	s_mov_b32 m0, s36
	v_lshl_add_u64 v[146:147], s[26:27], 0, v[132:133]
	global_load_lds_dwordx4 v[146:147], off
	s_add_i32 m0, s36, 0x2000
	v_lshl_add_u64 v[146:147], s[26:27], 0, v[136:137]
	global_load_lds_dwordx4 v[146:147], off
	s_mov_b32 m0, s48
	v_lshl_add_u64 v[146:147], v[150:151], 0, s[0:1]
	global_load_lds_dwordx4 v[146:147], off
	s_mov_b32 m0, s49
	v_lshl_add_u64 v[146:147], v[242:243], 0, s[0:1]
	global_load_lds_dwordx4 v[146:147], off
	s_waitcnt vmcnt(8)
	s_waitcnt lgkmcnt(0)
	s_barrier
	s_waitcnt lgkmcnt(0)
	v_mfma_f32_16x16x32_bf16 v[40:43], v[166:169], v[200:203], v[40:43]
	v_mfma_f32_16x16x32_bf16 v[36:39], v[176:179], v[200:203], v[36:39]
	v_mfma_f32_16x16x32_bf16 v[32:35], v[166:169], v[208:211], v[32:35]
	v_mfma_f32_16x16x32_bf16 v[28:31], v[176:179], v[208:211], v[28:31]
	v_mfma_f32_16x16x32_bf16 v[24:27], v[166:169], v[216:219], v[24:27]
	v_mfma_f32_16x16x32_bf16 v[20:23], v[176:179], v[216:219], v[20:23]
	v_mfma_f32_16x16x32_bf16 v[8:11], v[166:169], v[224:227], v[8:11]
	v_mfma_f32_16x16x32_bf16 v[4:7], v[176:179], v[224:227], v[4:7]
	v_mfma_f32_16x16x32_bf16 v[40:43], v[172:175], v[204:207], v[40:43]
	v_mfma_f32_16x16x32_bf16 v[36:39], v[180:183], v[204:207], v[36:39]
	v_mfma_f32_16x16x32_bf16 v[32:35], v[172:175], v[212:215], v[32:35]
	v_mfma_f32_16x16x32_bf16 v[28:31], v[180:183], v[212:215], v[28:31]
	v_mfma_f32_16x16x32_bf16 v[24:27], v[172:175], v[220:223], v[24:27]
	v_mfma_f32_16x16x32_bf16 v[20:23], v[180:183], v[220:223], v[20:23]
	v_mfma_f32_16x16x32_bf16 v[8:11], v[172:175], v[238:241], v[8:11]
	v_mfma_f32_16x16x32_bf16 v[4:7], v[180:183], v[238:241], v[4:7]
	v_mfma_f32_16x16x32_bf16 v[96:99], v[184:187], v[200:203], v[96:99]
	v_mfma_f32_16x16x32_bf16 v[92:95], v[192:195], v[200:203], v[92:95]
	v_mfma_f32_16x16x32_bf16 v[88:91], v[184:187], v[208:211], v[88:91]
	v_mfma_f32_16x16x32_bf16 v[84:87], v[192:195], v[208:211], v[84:87]
	v_mfma_f32_16x16x32_bf16 v[80:83], v[184:187], v[216:219], v[80:83]
	v_mfma_f32_16x16x32_bf16 v[76:79], v[192:195], v[216:219], v[76:79]
	v_mfma_f32_16x16x32_bf16 v[16:19], v[184:187], v[224:227], v[16:19]
	v_mfma_f32_16x16x32_bf16 v[12:15], v[192:195], v[224:227], v[12:15]
	v_mfma_f32_16x16x32_bf16 v[96:99], v[188:191], v[204:207], v[96:99]
	v_mfma_f32_16x16x32_bf16 v[92:95], v[196:199], v[204:207], v[92:95]
	v_mfma_f32_16x16x32_bf16 v[88:91], v[188:191], v[212:215], v[88:91]
	v_mfma_f32_16x16x32_bf16 v[84:87], v[196:199], v[212:215], v[84:87]
	v_mfma_f32_16x16x32_bf16 v[80:83], v[188:191], v[220:223], v[80:83]
	v_mfma_f32_16x16x32_bf16 v[76:79], v[196:199], v[220:223], v[76:79]
	v_mfma_f32_16x16x32_bf16 v[16:19], v[188:191], v[238:241], v[16:19]
	v_mfma_f32_16x16x32_bf16 v[12:15], v[196:199], v[238:241], v[12:15]
	s_barrier
	s_add_i32 s54, s54, 2
	s_add_u32 s2, s2, 0x100
	s_addc_u32 s3, s3, 0
	s_add_u32 s52, s52, 0x100
	s_addc_u32 s53, s53, 0
	s_cmp_gt_u32 s54, 13
	s_cbranch_scc0 .LBB0_293
	s_branch .Lpeel_exit1
.LBB0_293:
	s_add_u32 s26, s2, 0xfffc0080
	s_addc_u32 s27, s3, -1
	s_add_i32 s55, 0, 0x10000
	s_cmp_eq_u32 s54, 12
	s_cselect_b32 s37, s17, s27
	s_cselect_b32 s36, s23, s26
	v_add_u32_e32 v146, s55, v165
	s_cselect_b32 s27, s15, s53
	s_cselect_b32 s26, s51, s52
	s_add_i32 s58, 0, 0x14000
	ds_read_b128 v[166:169], v146
	ds_read_b128 v[172:175], v146 offset:1024
	ds_read_b128 v[176:179], v146 offset:2048
	ds_read_b128 v[180:183], v146 offset:3072
	v_add_u32_e32 v146, s58, v165
	ds_read_b128 v[184:187], v146
	ds_read_b128 v[188:191], v146 offset:1024
	ds_read_b128 v[192:195], v146 offset:2048
	ds_read_b128 v[196:199], v146 offset:3072
	v_lshl_add_u64 v[146:147], s[2:3], 0, v[142:143]
	s_add_i32 m0, s25, 0xc000
	ds_read_b128 v[200:203], v171
	ds_read_b128 v[204:207], v171 offset:1024
	ds_read_b128 v[208:211], v171 offset:2048
	ds_read_b128 v[212:215], v171 offset:3072
	ds_read_b128 v[216:219], v171 offset:4096
	ds_read_b128 v[220:223], v171 offset:5120
	ds_read_b128 v[224:227], v171 offset:6144
	ds_read_b128 v[238:241], v171 offset:7168
	global_load_lds_dwordx4 v[146:147], off
	s_add_i32 m0, s25, 0xe000
	v_lshl_add_u64 v[146:147], s[2:3], 0, v[144:145]
	global_load_lds_dwordx4 v[146:147], off
	s_waitcnt vmcnt(8)
	s_waitcnt lgkmcnt(0)
	s_barrier
; #define PG8_STAGE(bufoff, gbase, voff) do { _Pragma("unroll") for (int _i = 0; _i < 2; ++_i) \
;         __builtin_amdgcn_global_load_lds((const unsigned*)((const char*)(gbase) + (voff)[_i]), (PG8_LAS unsigned*)(lds + (bufoff) + ldsw + _i * 8192), 16, 0, 0); } while (0)
; #define PG8_LDA(dst, b, h) do { _Pragma("unroll") for (int m = 0; m < 4; ++m) _Pragma("unroll") for (int k = 0; k < 2; ++k) dst[m][k] = *(const PG8_LAS bf16x8*)(lds + PG8_SA(b, h) + aoff + m * 2048 + k * 1024); } while (0)
; #define PG8_LDB(dst, b, h) do { _Pragma("unroll") for (int n = 0; n < 2; ++n) _Pragma("unroll") for (int k = 0; k < 2; ++k) dst[n][k] = *(const PG8_LAS bf16x8*)(lds + PG8_SB(b, h) + boff + n * 2048 + k * 1024); } while (0)
; #define PG8_MMA(ai, bj, At, Bt) do { __builtin_amdgcn_s_setprio(1); _Pragma("unroll") for (int m = 0; m < 4; ++m) _Pragma("unroll") for (int n = 0; n < 2; ++n) _Pragma("unroll") for (int k = 0; k < 2; ++k) \
;         acc[ai][bj][m][n] = __builtin_amdgcn_mfma_f32_16x16x32_bf16(Bt[n][k], At[m][k], acc[ai][bj][m][n], 0, 0, 0); __builtin_amdgcn_s_setprio(0); } while (0)
; #define PG8_WAIT_V(n) asm volatile("s_waitcnt vmcnt(" #n ")" ::: "memory")
; #define PG8_WAIT_L(n) asm volatile("s_waitcnt lgkmcnt(" #n ")" ::: "memory")
; #define PG8_BAR __builtin_amdgcn_s_barrier()
; #define PG8_SCHED __builtin_amdgcn_sched_barrier(0)
; template <class Epi, class Sched, bool ALIGN_EPI = false, bool SP2 = false>
; __device__ __forceinline__ void gemm_phase(PG8_LAS unsigned char* lds, const Gemm g, const Sched& S, const Epi& E, const int tid) {
;     ...
;             PG8_LDB(B0, 0, 0); PG8_LDB(B1, 0, 1); PG8_SCHED; PG8_LDA(At, 0, 0); PG8_STAGE(PG8_SA(1, 1), a1 + hstep, voffA);
;             PG8_WAIT_V(8); PG8_WAIT_L(0); PG8_BAR; PG8_MMA(0, 0, At, B0); PG8_MMA(0, 1, At, B1); PG8_BAR; PG8_SCHED;
;             PG8_LDA(At, 0, 1); PG8_STAGE(PG8_SB(0, 0), b2, voffB); PG8_STAGE(PG8_SB(0, 1), b2 + hstep, voffB); PG8_STAGE(PG8_SA(0, 0), a2, voffA);
;             PG8_WAIT_V(8); PG8_WAIT_L(0); PG8_BAR; PG8_MMA(1, 0, At, B0); PG8_MMA(1, 1, At, B1); PG8_BAR; PG8_SCHED;
	s_waitcnt lgkmcnt(0)
	v_mfma_f32_16x16x32_bf16 v[72:75], v[166:169], v[200:203], v[72:75]
	v_mfma_f32_16x16x32_bf16 v[68:71], v[176:179], v[200:203], v[68:71]
	v_mfma_f32_16x16x32_bf16 v[64:67], v[166:169], v[208:211], v[64:67]
	v_mfma_f32_16x16x32_bf16 v[60:63], v[176:179], v[208:211], v[60:63]
	v_mfma_f32_16x16x32_bf16 v[56:59], v[166:169], v[216:219], v[56:59]
	v_mfma_f32_16x16x32_bf16 v[52:55], v[176:179], v[216:219], v[52:55]
	v_mfma_f32_16x16x32_bf16 v[48:51], v[166:169], v[224:227], v[48:51]
	v_mfma_f32_16x16x32_bf16 v[44:47], v[176:179], v[224:227], v[44:47]
	v_mfma_f32_16x16x32_bf16 v[72:75], v[172:175], v[204:207], v[72:75]
	v_mfma_f32_16x16x32_bf16 v[68:71], v[180:183], v[204:207], v[68:71]
	v_mfma_f32_16x16x32_bf16 v[64:67], v[172:175], v[212:215], v[64:67]
	v_mfma_f32_16x16x32_bf16 v[60:63], v[180:183], v[212:215], v[60:63]
	v_mfma_f32_16x16x32_bf16 v[56:59], v[172:175], v[220:223], v[56:59]
	v_mfma_f32_16x16x32_bf16 v[52:55], v[180:183], v[220:223], v[52:55]
	v_mfma_f32_16x16x32_bf16 v[48:51], v[172:175], v[238:241], v[48:51]
	v_mfma_f32_16x16x32_bf16 v[44:47], v[180:183], v[238:241], v[44:47]
	v_mfma_f32_16x16x32_bf16 v[128:131], v[184:187], v[200:203], v[128:131]
	v_mfma_f32_16x16x32_bf16 v[124:127], v[192:195], v[200:203], v[124:127]
	v_mfma_f32_16x16x32_bf16 v[120:123], v[184:187], v[208:211], v[120:123]
	v_mfma_f32_16x16x32_bf16 v[116:119], v[192:195], v[208:211], v[116:119]
	v_mfma_f32_16x16x32_bf16 v[112:115], v[184:187], v[216:219], v[112:115]
	v_mfma_f32_16x16x32_bf16 v[108:111], v[192:195], v[216:219], v[108:111]
	v_mfma_f32_16x16x32_bf16 v[104:107], v[184:187], v[224:227], v[104:107]
	v_mfma_f32_16x16x32_bf16 v[100:103], v[192:195], v[224:227], v[100:103]
	v_mfma_f32_16x16x32_bf16 v[128:131], v[188:191], v[204:207], v[128:131]
	v_mfma_f32_16x16x32_bf16 v[124:127], v[196:199], v[204:207], v[124:127]
	v_mfma_f32_16x16x32_bf16 v[120:123], v[188:191], v[212:215], v[120:123]
	v_mfma_f32_16x16x32_bf16 v[116:119], v[196:199], v[212:215], v[116:119]
	v_mfma_f32_16x16x32_bf16 v[112:115], v[188:191], v[220:223], v[112:115]
	v_mfma_f32_16x16x32_bf16 v[108:111], v[196:199], v[220:223], v[108:111]
	v_mfma_f32_16x16x32_bf16 v[104:107], v[188:191], v[238:241], v[104:107]
	v_mfma_f32_16x16x32_bf16 v[100:103], v[196:199], v[238:241], v[100:103]
	s_barrier
	s_add_i32 s55, s55, s43
	v_lshl_add_u64 v[146:147], s[26:27], 0, v[132:133]
	s_mov_b32 m0, s55
	ds_read_b128 v[200:203], v171 offset:16384
	ds_read_b128 v[204:207], v171 offset:17408
	ds_read_b128 v[208:211], v171 offset:18432
	ds_read_b128 v[212:215], v171 offset:19456
	ds_read_b128 v[216:219], v171 offset:20480
	ds_read_b128 v[220:223], v171 offset:21504
	ds_read_b128 v[224:227], v171 offset:22528
	ds_read_b128 v[238:241], v171 offset:23552
	global_load_lds_dwordx4 v[146:147], off
	s_add_i32 m0, s55, 0x2000
	s_add_u32 s56, s26, 0x40000
	v_lshl_add_u64 v[148:149], s[26:27], 0, v[136:137]
	s_addc_u32 s57, s27, 0
	s_add_i32 s55, s58, s43
	global_load_lds_dwordx4 v[148:149], off
	v_lshl_add_u64 v[150:151], s[56:57], 0, v[132:133]
	s_mov_b32 m0, s55
	v_lshl_add_u64 v[242:243], s[36:37], 0, v[134:135]
	global_load_lds_dwordx4 v[150:151], off
	s_add_i32 m0, s55, 0x2000
	v_lshl_add_u64 v[150:151], s[56:57], 0, v[136:137]
	global_load_lds_dwordx4 v[150:151], off
	s_mov_b32 m0, s25
	v_lshl_add_u64 v[150:151], s[36:37], 0, v[0:1]
	global_load_lds_dwordx4 v[150:151], off
	s_mov_b32 m0, s44
	s_nop 0
	global_load_lds_dwordx4 v[242:243], off
	s_waitcnt vmcnt(8)
	s_waitcnt lgkmcnt(0)
	s_barrier
	s_waitcnt lgkmcnt(0)
	v_mfma_f32_16x16x32_bf16 v[40:43], v[166:169], v[200:203], v[40:43]
	v_mfma_f32_16x16x32_bf16 v[36:39], v[176:179], v[200:203], v[36:39]
	v_mfma_f32_16x16x32_bf16 v[32:35], v[166:169], v[208:211], v[32:35]
	v_mfma_f32_16x16x32_bf16 v[28:31], v[176:179], v[208:211], v[28:31]
	v_mfma_f32_16x16x32_bf16 v[24:27], v[166:169], v[216:219], v[24:27]
	v_mfma_f32_16x16x32_bf16 v[20:23], v[176:179], v[216:219], v[20:23]
	v_mfma_f32_16x16x32_bf16 v[8:11], v[166:169], v[224:227], v[8:11]
	v_mfma_f32_16x16x32_bf16 v[4:7], v[176:179], v[224:227], v[4:7]
	v_mfma_f32_16x16x32_bf16 v[40:43], v[172:175], v[204:207], v[40:43]
	v_mfma_f32_16x16x32_bf16 v[36:39], v[180:183], v[204:207], v[36:39]
	v_mfma_f32_16x16x32_bf16 v[32:35], v[172:175], v[212:215], v[32:35]
	v_mfma_f32_16x16x32_bf16 v[28:31], v[180:183], v[212:215], v[28:31]
	v_mfma_f32_16x16x32_bf16 v[24:27], v[172:175], v[220:223], v[24:27]
	v_mfma_f32_16x16x32_bf16 v[20:23], v[180:183], v[220:223], v[20:23]
	v_mfma_f32_16x16x32_bf16 v[8:11], v[172:175], v[238:241], v[8:11]
	v_mfma_f32_16x16x32_bf16 v[4:7], v[180:183], v[238:241], v[4:7]
	v_mfma_f32_16x16x32_bf16 v[96:99], v[184:187], v[200:203], v[96:99]
	v_mfma_f32_16x16x32_bf16 v[92:95], v[192:195], v[200:203], v[92:95]
	v_mfma_f32_16x16x32_bf16 v[88:91], v[184:187], v[208:211], v[88:91]
	v_mfma_f32_16x16x32_bf16 v[84:87], v[192:195], v[208:211], v[84:87]
	v_mfma_f32_16x16x32_bf16 v[80:83], v[184:187], v[216:219], v[80:83]
	v_mfma_f32_16x16x32_bf16 v[76:79], v[192:195], v[216:219], v[76:79]
	v_mfma_f32_16x16x32_bf16 v[16:19], v[184:187], v[224:227], v[16:19]
	v_mfma_f32_16x16x32_bf16 v[12:15], v[192:195], v[224:227], v[12:15]
	v_mfma_f32_16x16x32_bf16 v[96:99], v[188:191], v[204:207], v[96:99]
	v_mfma_f32_16x16x32_bf16 v[92:95], v[196:199], v[204:207], v[92:95]
	v_mfma_f32_16x16x32_bf16 v[88:91], v[188:191], v[212:215], v[88:91]
	v_mfma_f32_16x16x32_bf16 v[84:87], v[196:199], v[212:215], v[84:87]
	v_mfma_f32_16x16x32_bf16 v[80:83], v[188:191], v[220:223], v[80:83]
	v_mfma_f32_16x16x32_bf16 v[76:79], v[196:199], v[220:223], v[76:79]
	v_mfma_f32_16x16x32_bf16 v[16:19], v[188:191], v[238:241], v[16:19]
	v_mfma_f32_16x16x32_bf16 v[12:15], v[196:199], v[238:241], v[12:15]
	s_barrier
; #define PG8_STAGE(bufoff, gbase, voff) do { _Pragma("unroll") for (int _i = 0; _i < 2; ++_i) \
;         __builtin_amdgcn_global_load_lds((const unsigned*)((const char*)(gbase) + (voff)[_i]), (PG8_LAS unsigned*)(lds + (bufoff) + ldsw + _i * 8192), 16, 0, 0); } while (0)
; #define PG8_LDA(dst, b, h) do { _Pragma("unroll") for (int m = 0; m < 4; ++m) _Pragma("unroll") for (int k = 0; k < 2; ++k) dst[m][k] = *(const PG8_LAS bf16x8*)(lds + PG8_SA(b, h) + aoff + m * 2048 + k * 1024); } while (0)
; #define PG8_LDB(dst, b, h) do { _Pragma("unroll") for (int n = 0; n < 2; ++n) _Pragma("unroll") for (int k = 0; k < 2; ++k) dst[n][k] = *(const PG8_LAS bf16x8*)(lds + PG8_SB(b, h) + boff + n * 2048 + k * 1024); } while (0)
; #define PG8_MMA(ai, bj, At, Bt) do { __builtin_amdgcn_s_setprio(1); _Pragma("unroll") for (int m = 0; m < 4; ++m) _Pragma("unroll") for (int n = 0; n < 2; ++n) _Pragma("unroll") for (int k = 0; k < 2; ++k) \
;         acc[ai][bj][m][n] = __builtin_amdgcn_mfma_f32_16x16x32_bf16(Bt[n][k], At[m][k], acc[ai][bj][m][n], 0, 0, 0); __builtin_amdgcn_s_setprio(0); } while (0)
; #define PG8_WAIT_V(n) asm volatile("s_waitcnt vmcnt(" #n ")" ::: "memory")
; #define PG8_WAIT_L(n) asm volatile("s_waitcnt lgkmcnt(" #n ")" ::: "memory")
; #define PG8_BAR __builtin_amdgcn_s_barrier()
; #define PG8_SCHED __builtin_amdgcn_sched_barrier(0)
; template <class Epi, class Sched, bool ALIGN_EPI = false, bool SP2 = false>
; __device__ __forceinline__ void gemm_phase(PG8_LAS unsigned char* lds, const Gemm g, const Sched& S, const Epi& E, const int tid) {
;     ...
;             PG8_LDB(B0, 1, 0); PG8_LDB(B1, 1, 1); PG8_SCHED; PG8_LDA(At, 1, 0); PG8_STAGE(PG8_SA(0, 1), a2 + hstep, voffA);
;             PG8_WAIT_V(8); PG8_WAIT_L(0); PG8_BAR; PG8_MMA(0, 0, At, B0); PG8_MMA(0, 1, At, B1); PG8_BAR; PG8_SCHED;
;             PG8_LDA(At, 1, 1); PG8_STAGE(PG8_SB(1, 0), b3, voffB); PG8_STAGE(PG8_SB(1, 1), b3 + hstep, voffB); PG8_STAGE(PG8_SA(1, 0), a3, voffA);
;             PG8_WAIT_V(8); PG8_WAIT_L(0); PG8_BAR; PG8_MMA(1, 0, At, B0); PG8_MMA(1, 1, At, B1); PG8_BAR; PG8_SCHED;
	s_add_i32 s55, 0, 0x18000
	v_add_u32_e32 v153, s55, v165
	s_add_i32 s56, 0, 0x1c000
	ds_read_b128 v[166:169], v153
	ds_read_b128 v[172:175], v153 offset:1024
	ds_read_b128 v[176:179], v153 offset:2048
	ds_read_b128 v[180:183], v153 offset:3072
	v_add_u32_e32 v153, s56, v165
	ds_read_b128 v[184:187], v153
	ds_read_b128 v[188:191], v153 offset:1024
	ds_read_b128 v[192:195], v153 offset:2048
	ds_read_b128 v[196:199], v153 offset:3072
	s_add_u32 s36, s36, 0x40000
	s_addc_u32 s37, s37, 0
	s_mov_b32 m0, s45
	v_lshl_add_u64 v[244:245], s[36:37], 0, v[0:1]
	ds_read_b128 v[200:203], v171 offset:32768
	ds_read_b128 v[204:207], v171 offset:33792
	ds_read_b128 v[208:211], v171 offset:34816
	ds_read_b128 v[212:215], v171 offset:35840
	ds_read_b128 v[216:219], v171 offset:36864
	ds_read_b128 v[220:223], v171 offset:37888
	ds_read_b128 v[224:227], v171 offset:38912
	ds_read_b128 v[238:241], v171 offset:39936
	global_load_lds_dwordx4 v[244:245], off
	s_mov_b32 m0, s46
	v_lshl_add_u64 v[244:245], s[36:37], 0, v[134:135]
	global_load_lds_dwordx4 v[244:245], off
	s_waitcnt vmcnt(8)
	s_waitcnt lgkmcnt(0)
	s_barrier
	s_waitcnt lgkmcnt(0)
	v_mfma_f32_16x16x32_bf16 v[72:75], v[166:169], v[200:203], v[72:75]
	v_mfma_f32_16x16x32_bf16 v[68:71], v[176:179], v[200:203], v[68:71]
	v_mfma_f32_16x16x32_bf16 v[64:67], v[166:169], v[208:211], v[64:67]
	v_mfma_f32_16x16x32_bf16 v[60:63], v[176:179], v[208:211], v[60:63]
	v_mfma_f32_16x16x32_bf16 v[56:59], v[166:169], v[216:219], v[56:59]
	v_mfma_f32_16x16x32_bf16 v[52:55], v[176:179], v[216:219], v[52:55]
	v_mfma_f32_16x16x32_bf16 v[48:51], v[166:169], v[224:227], v[48:51]
	v_mfma_f32_16x16x32_bf16 v[44:47], v[176:179], v[224:227], v[44:47]
	v_mfma_f32_16x16x32_bf16 v[72:75], v[172:175], v[204:207], v[72:75]
	v_mfma_f32_16x16x32_bf16 v[68:71], v[180:183], v[204:207], v[68:71]
	v_mfma_f32_16x16x32_bf16 v[64:67], v[172:175], v[212:215], v[64:67]
	v_mfma_f32_16x16x32_bf16 v[60:63], v[180:183], v[212:215], v[60:63]
	v_mfma_f32_16x16x32_bf16 v[56:59], v[172:175], v[220:223], v[56:59]
	v_mfma_f32_16x16x32_bf16 v[52:55], v[180:183], v[220:223], v[52:55]
	v_mfma_f32_16x16x32_bf16 v[48:51], v[172:175], v[238:241], v[48:51]
	v_mfma_f32_16x16x32_bf16 v[44:47], v[180:183], v[238:241], v[44:47]
	v_mfma_f32_16x16x32_bf16 v[128:131], v[184:187], v[200:203], v[128:131]
	v_mfma_f32_16x16x32_bf16 v[124:127], v[192:195], v[200:203], v[124:127]
	v_mfma_f32_16x16x32_bf16 v[120:123], v[184:187], v[208:211], v[120:123]
	v_mfma_f32_16x16x32_bf16 v[116:119], v[192:195], v[208:211], v[116:119]
	v_mfma_f32_16x16x32_bf16 v[112:115], v[184:187], v[216:219], v[112:115]
	v_mfma_f32_16x16x32_bf16 v[108:111], v[192:195], v[216:219], v[108:111]
	v_mfma_f32_16x16x32_bf16 v[104:107], v[184:187], v[224:227], v[104:107]
	v_mfma_f32_16x16x32_bf16 v[100:103], v[192:195], v[224:227], v[100:103]
	v_mfma_f32_16x16x32_bf16 v[128:131], v[188:191], v[204:207], v[128:131]
	v_mfma_f32_16x16x32_bf16 v[124:127], v[196:199], v[204:207], v[124:127]
	v_mfma_f32_16x16x32_bf16 v[120:123], v[188:191], v[212:215], v[120:123]
	v_mfma_f32_16x16x32_bf16 v[116:119], v[196:199], v[212:215], v[116:119]
	v_mfma_f32_16x16x32_bf16 v[112:115], v[188:191], v[220:223], v[112:115]
	v_mfma_f32_16x16x32_bf16 v[108:111], v[196:199], v[220:223], v[108:111]
	v_mfma_f32_16x16x32_bf16 v[104:107], v[188:191], v[238:241], v[104:107]
	v_mfma_f32_16x16x32_bf16 v[100:103], v[196:199], v[238:241], v[100:103]
	s_barrier
	s_add_i32 s36, s55, s43
	v_lshl_add_u64 v[146:147], v[146:147], 0, s[0:1]
	s_mov_b32 m0, s36
	ds_read_b128 v[200:203], v171 offset:49152
	ds_read_b128 v[204:207], v171 offset:50176
	ds_read_b128 v[208:211], v171 offset:51200
	ds_read_b128 v[212:215], v171 offset:52224
	ds_read_b128 v[216:219], v171 offset:53248
	ds_read_b128 v[220:223], v171 offset:54272
	ds_read_b128 v[224:227], v171 offset:55296
	ds_read_b128 v[238:241], v171 offset:56320
	global_load_lds_dwordx4 v[146:147], off
	s_add_i32 m0, s36, 0x2000
	s_add_u32 s26, s26, 0x40080
	v_lshl_add_u64 v[146:147], v[148:149], 0, s[0:1]
	s_addc_u32 s27, s27, 0
	s_add_i32 s36, s56, s43
	global_load_lds_dwordx4 v[146:147], off
	s_mov_b32 m0, s36
	v_lshl_add_u64 v[146:147], s[26:27], 0, v[132:133]
	global_load_lds_dwordx4 v[146:147], off
	s_add_i32 m0, s36, 0x2000
	v_lshl_add_u64 v[146:147], s[26:27], 0, v[136:137]
	global_load_lds_dwordx4 v[146:147], off
	s_mov_b32 m0, s48
	v_lshl_add_u64 v[146:147], v[150:151], 0, s[0:1]
	global_load_lds_dwordx4 v[146:147], off
	s_mov_b32 m0, s49
	v_lshl_add_u64 v[146:147], v[242:243], 0, s[0:1]
	global_load_lds_dwordx4 v[146:147], off
	s_waitcnt vmcnt(8)
	s_waitcnt lgkmcnt(0)
	s_barrier
	s_waitcnt lgkmcnt(0)
	v_mfma_f32_16x16x32_bf16 v[40:43], v[166:169], v[200:203], v[40:43]
	v_mfma_f32_16x16x32_bf16 v[36:39], v[176:179], v[200:203], v[36:39]
	v_mfma_f32_16x16x32_bf16 v[32:35], v[166:169], v[208:211], v[32:35]
	v_mfma_f32_16x16x32_bf16 v[28:31], v[176:179], v[208:211], v[28:31]
	v_mfma_f32_16x16x32_bf16 v[24:27], v[166:169], v[216:219], v[24:27]
	v_mfma_f32_16x16x32_bf16 v[20:23], v[176:179], v[216:219], v[20:23]
	v_mfma_f32_16x16x32_bf16 v[8:11], v[166:169], v[224:227], v[8:11]
	v_mfma_f32_16x16x32_bf16 v[4:7], v[176:179], v[224:227], v[4:7]
	v_mfma_f32_16x16x32_bf16 v[40:43], v[172:175], v[204:207], v[40:43]
	v_mfma_f32_16x16x32_bf16 v[36:39], v[180:183], v[204:207], v[36:39]
	v_mfma_f32_16x16x32_bf16 v[32:35], v[172:175], v[212:215], v[32:35]
	v_mfma_f32_16x16x32_bf16 v[28:31], v[180:183], v[212:215], v[28:31]
	v_mfma_f32_16x16x32_bf16 v[24:27], v[172:175], v[220:223], v[24:27]
	v_mfma_f32_16x16x32_bf16 v[20:23], v[180:183], v[220:223], v[20:23]
	v_mfma_f32_16x16x32_bf16 v[8:11], v[172:175], v[238:241], v[8:11]
	v_mfma_f32_16x16x32_bf16 v[4:7], v[180:183], v[238:241], v[4:7]
	v_mfma_f32_16x16x32_bf16 v[96:99], v[184:187], v[200:203], v[96:99]
	v_mfma_f32_16x16x32_bf16 v[92:95], v[192:195], v[200:203], v[92:95]
	v_mfma_f32_16x16x32_bf16 v[88:91], v[184:187], v[208:211], v[88:91]
	v_mfma_f32_16x16x32_bf16 v[84:87], v[192:195], v[208:211], v[84:87]
	v_mfma_f32_16x16x32_bf16 v[80:83], v[184:187], v[216:219], v[80:83]
	v_mfma_f32_16x16x32_bf16 v[76:79], v[192:195], v[216:219], v[76:79]
	v_mfma_f32_16x16x32_bf16 v[16:19], v[184:187], v[224:227], v[16:19]
	v_mfma_f32_16x16x32_bf16 v[12:15], v[192:195], v[224:227], v[12:15]
	v_mfma_f32_16x16x32_bf16 v[96:99], v[188:191], v[204:207], v[96:99]
	v_mfma_f32_16x16x32_bf16 v[92:95], v[196:199], v[204:207], v[92:95]
	v_mfma_f32_16x16x32_bf16 v[88:91], v[188:191], v[212:215], v[88:91]
	v_mfma_f32_16x16x32_bf16 v[84:87], v[196:199], v[212:215], v[84:87]
	v_mfma_f32_16x16x32_bf16 v[80:83], v[188:191], v[220:223], v[80:83]
	v_mfma_f32_16x16x32_bf16 v[76:79], v[196:199], v[220:223], v[76:79]
	v_mfma_f32_16x16x32_bf16 v[16:19], v[188:191], v[238:241], v[16:19]
	v_mfma_f32_16x16x32_bf16 v[12:15], v[196:199], v[238:241], v[12:15]
	s_barrier
	s_add_i32 s54, s54, 2
	s_add_u32 s2, s2, 0x100
	s_addc_u32 s3, s3, 0
	s_add_u32 s52, s52, 0x100
	s_addc_u32 s53, s53, 0
	s_cmp_gt_u32 s54, 13
	s_cbranch_scc0 .LBB0_293

; #define PG8_STAGE(bufoff, gbase, voff) do { _Pragma("unroll") for (int _i = 0; _i < 2; ++_i) \
;         __builtin_amdgcn_global_load_lds((const unsigned*)((const char*)(gbase) + (voff)[_i]), (PG8_LAS unsigned*)(lds + (bufoff) + ldsw + _i * 8192), 16, 0, 0); } while (0)
; #define PG8_LDA(dst, b, h) do { _Pragma("unroll") for (int m = 0; m < 4; ++m) _Pragma("unroll") for (int k = 0; k < 2; ++k) dst[m][k] = *(const PG8_LAS bf16x8*)(lds + PG8_SA(b, h) + aoff + m * 2048 + k * 1024); } while (0)
; #define PG8_LDB(dst, b, h) do { _Pragma("unroll") for (int n = 0; n < 2; ++n) _Pragma("unroll") for (int k = 0; k < 2; ++k) dst[n][k] = *(const PG8_LAS bf16x8*)(lds + PG8_SB(b, h) + boff + n * 2048 + k * 1024); } while (0)
; #define PG8_WAIT_V(n) asm volatile("s_waitcnt vmcnt(" #n ")" ::: "memory")
; #define PG8_WAIT_L(n) asm volatile("s_waitcnt lgkmcnt(" #n ")" ::: "memory")
; #define PG8_BAR __builtin_amdgcn_s_barrier()
; #define PG8_SCHED __builtin_amdgcn_sched_barrier(0)
; template <class Epi, class Sched, bool ALIGN_EPI = false, bool SP2 = false>
; __device__ __forceinline__ void gemm_phase(PG8_LAS unsigned char* lds, const Gemm g, const Sched& S, const Epi& E, const int tid) {
;     ...
;         const bool has_next = S.next(ui + 1, nxt);
;         const char* nA = has_next ? (const char*)g.A + (size_t)nxt.pm * tstep : cA; const char* nB = has_next ? (const char*)g.Bt + (size_t)nxt.pn * tstep : cB;
;         for (int t = 0; t < nt; t += 2) {
;             const bool last = (t == nt - 2);
;             const char* a1 = cA + (size_t)(t + 1) * kstep;
;             const char* a2 = last ? nA : cA + (size_t)(t + 2) * kstep; const char* b2 = last ? nB : cB + (size_t)(t + 2) * kstep;
;             const char* a3 = a2 + kstep; const char* b3 = b2 + kstep;
;             if (last && has_next) S.a_ready(nxt);
;             if constexpr (SP2) {
;             PG8_LDB(B0, 0, 0); PG8_LDB(B1, 0, 1); PG8_SCHED; PG8_LDA(At, 0, 0); PG8_STAGE(PG8_SA(1, 1), a1 + hstep, voffA);
;             PG8_WAIT_V(8); PG8_WAIT_L(0); PG8_BAR; PG8_MMA(0, 0, At, B0); PG8_MMA(0, 1, At, B1); PG8_BAR; PG8_SCHED;
;             PG8_LDA(At, 0, 1); PG8_STAGE(PG8_SB(0, 0), b2, voffB); PG8_STAGE(PG8_SB(0, 1), b2 + hstep, voffB); PG8_STAGE(PG8_SA(0, 0), a2, voffA);
;             PG8_WAIT_V(8); PG8_WAIT_L(0); PG8_BAR; PG8_MMA(1, 0, At, B0); PG8_MMA(1, 1, At, B1); PG8_BAR; PG8_SCHED;
.LBB0_475:
	s_add_u32 s6, s6, 0x80
	s_addc_u32 s7, s7, 0
	s_add_u32 s78, s58, 0x100
	v_mov_b32_e32 v4, 0
	s_addc_u32 s79, s59, 0
	s_mov_b32 s58, 0
	s_add_i32 s80, s58, 2
	s_add_u32 s81, s6, 0x80
	s_addc_u32 s59, s7, 0
	s_add_i32 s87, 0, 0x10000
	s_cmp_eq_u32 s70, s58
	s_cselect_b32 s59, s55, s59
	s_cselect_b32 s58, s54, s81
	v_add_u32_e32 v144, s87, v184
	s_cselect_b32 s83, s57, s79
	s_cselect_b32 s82, s56, s78
	s_add_i32 s81, 0, 0x14000
	ds_read_b128 v[132:135], v144
	ds_read_b128 v[136:139], v144 offset:1024
	ds_read_b128 v[140:143], v144 offset:2048
	ds_read_b128 v[174:177], v144 offset:3072
	v_add_u32_e32 v144, s81, v184
	ds_read_b128 v[178:181], v144
	ds_read_b128 v[188:191], v144 offset:1024
	ds_read_b128 v[192:195], v144 offset:2048
	ds_read_b128 v[196:199], v144 offset:3072
	v_lshl_add_u64 v[144:145], s[6:7], 0, v[170:171]
	s_add_i32 m0, s62, 0xc000
	ds_read_b128 v[200:203], v186
	ds_read_b128 v[204:207], v186 offset:1024
	ds_read_b128 v[208:211], v186 offset:2048
	ds_read_b128 v[212:215], v186 offset:3072
	ds_read_b128 v[216:219], v186 offset:4096
	ds_read_b128 v[220:223], v186 offset:5120
	ds_read_b128 v[224:227], v186 offset:6144
	ds_read_b128 v[238:241], v186 offset:7168
	global_load_lds_dwordx4 v[144:145], off
	s_add_i32 m0, s62, 0xe000
	v_lshl_add_u64 v[144:145], s[6:7], 0, v[172:173]
	global_load_lds_dwordx4 v[144:145], off
	s_waitcnt vmcnt(8)
	s_waitcnt lgkmcnt(0)
	s_barrier
	s_waitcnt lgkmcnt(0)
	v_mfma_f32_16x16x32_bf16 v[128:131], v[132:135], v[200:203], 0
	v_mfma_f32_16x16x32_bf16 v[124:127], v[140:143], v[200:203], 0
	v_mfma_f32_16x16x32_bf16 v[112:115], v[132:135], v[208:211], 0
	v_mfma_f32_16x16x32_bf16 v[108:111], v[140:143], v[208:211], 0
	v_mfma_f32_16x16x32_bf16 v[96:99], v[132:135], v[216:219], 0
	v_mfma_f32_16x16x32_bf16 v[92:95], v[140:143], v[216:219], 0
	v_mfma_f32_16x16x32_bf16 v[80:83], v[132:135], v[224:227], 0
	v_mfma_f32_16x16x32_bf16 v[76:79], v[140:143], v[224:227], 0
	v_mfma_f32_16x16x32_bf16 v[128:131], v[136:139], v[204:207], v[128:131]
	v_mfma_f32_16x16x32_bf16 v[124:127], v[174:177], v[204:207], v[124:127]
	v_mfma_f32_16x16x32_bf16 v[112:115], v[136:139], v[212:215], v[112:115]
	v_mfma_f32_16x16x32_bf16 v[108:111], v[174:177], v[212:215], v[108:111]
	v_mfma_f32_16x16x32_bf16 v[96:99], v[136:139], v[220:223], v[96:99]
	v_mfma_f32_16x16x32_bf16 v[92:95], v[174:177], v[220:223], v[92:95]
	v_mfma_f32_16x16x32_bf16 v[80:83], v[136:139], v[238:241], v[80:83]
	v_mfma_f32_16x16x32_bf16 v[76:79], v[174:177], v[238:241], v[76:79]
	v_mfma_f32_16x16x32_bf16 v[120:123], v[178:181], v[200:203], 0
	v_mfma_f32_16x16x32_bf16 v[116:119], v[192:195], v[200:203], 0
	v_mfma_f32_16x16x32_bf16 v[104:107], v[178:181], v[208:211], 0
	v_mfma_f32_16x16x32_bf16 v[100:103], v[192:195], v[208:211], 0
	v_mfma_f32_16x16x32_bf16 v[88:91], v[178:181], v[216:219], 0
	v_mfma_f32_16x16x32_bf16 v[84:87], v[192:195], v[216:219], 0
	v_mfma_f32_16x16x32_bf16 v[72:75], v[178:181], v[224:227], 0
	v_mfma_f32_16x16x32_bf16 v[68:71], v[192:195], v[224:227], 0
	v_mfma_f32_16x16x32_bf16 v[120:123], v[188:191], v[204:207], v[120:123]
	v_mfma_f32_16x16x32_bf16 v[116:119], v[196:199], v[204:207], v[116:119]
	v_mfma_f32_16x16x32_bf16 v[104:107], v[188:191], v[212:215], v[104:107]
	v_mfma_f32_16x16x32_bf16 v[100:103], v[196:199], v[212:215], v[100:103]
	v_mfma_f32_16x16x32_bf16 v[88:91], v[188:191], v[220:223], v[88:91]
	v_mfma_f32_16x16x32_bf16 v[84:87], v[196:199], v[220:223], v[84:87]
	v_mfma_f32_16x16x32_bf16 v[72:75], v[188:191], v[238:241], v[72:75]
	v_mfma_f32_16x16x32_bf16 v[68:71], v[196:199], v[238:241], v[68:71]
	s_barrier
	s_add_i32 s87, s87, s61
	v_lshl_add_u64 v[144:145], s[82:83], 0, v[146:147]
	s_mov_b32 m0, s87
	ds_read_b128 v[200:203], v186 offset:16384
	ds_read_b128 v[204:207], v186 offset:17408
	ds_read_b128 v[208:211], v186 offset:18432
	ds_read_b128 v[212:215], v186 offset:19456
	ds_read_b128 v[216:219], v186 offset:20480
	ds_read_b128 v[220:223], v186 offset:21504
	ds_read_b128 v[224:227], v186 offset:22528
	ds_read_b128 v[238:241], v186 offset:23552
	global_load_lds_dwordx4 v[144:145], off
	s_add_i32 m0, s87, 0x2000
	v_lshl_add_u64 v[242:243], s[82:83], 0, v[168:169]
	s_add_u32 s82, s82, s14
	s_addc_u32 s83, s83, 0
	s_add_i32 s81, s81, s61
	global_load_lds_dwordx4 v[242:243], off
	v_lshl_add_u64 v[244:245], s[82:83], 0, v[146:147]
	s_mov_b32 m0, s81
	v_lshl_add_u64 v[246:247], s[82:83], 0, v[168:169]
	global_load_lds_dwordx4 v[244:245], off
	s_add_i32 m0, s81, 0x2000
	v_lshl_add_u64 v[248:249], s[58:59], 0, v[0:1]
	global_load_lds_dwordx4 v[246:247], off
	s_mov_b32 m0, s62
	v_lshl_add_u64 v[148:149], s[58:59], 0, v[166:167]
	global_load_lds_dwordx4 v[248:249], off
	s_mov_b32 m0, s63
	s_nop 0
	global_load_lds_dwordx4 v[148:149], off
	s_waitcnt vmcnt(8)
	s_waitcnt lgkmcnt(0)
	s_barrier
; #define PG8_STAGE(bufoff, gbase, voff) do { _Pragma("unroll") for (int _i = 0; _i < 2; ++_i) \
;         __builtin_amdgcn_global_load_lds((const unsigned*)((const char*)(gbase) + (voff)[_i]), (PG8_LAS unsigned*)(lds + (bufoff) + ldsw + _i * 8192), 16, 0, 0); } while (0)
; #define PG8_LDA(dst, b, h) do { _Pragma("unroll") for (int m = 0; m < 4; ++m) _Pragma("unroll") for (int k = 0; k < 2; ++k) dst[m][k] = *(const PG8_LAS bf16x8*)(lds + PG8_SA(b, h) + aoff + m * 2048 + k * 1024); } while (0)
; #define PG8_LDB(dst, b, h) do { _Pragma("unroll") for (int n = 0; n < 2; ++n) _Pragma("unroll") for (int k = 0; k < 2; ++k) dst[n][k] = *(const PG8_LAS bf16x8*)(lds + PG8_SB(b, h) + boff + n * 2048 + k * 1024); } while (0)
; #define PG8_MMA(ai, bj, At, Bt) do { __builtin_amdgcn_s_setprio(1); _Pragma("unroll") for (int m = 0; m < 4; ++m) _Pragma("unroll") for (int n = 0; n < 2; ++n) _Pragma("unroll") for (int k = 0; k < 2; ++k) \
;         acc[ai][bj][m][n] = __builtin_amdgcn_mfma_f32_16x16x32_bf16(Bt[n][k], At[m][k], acc[ai][bj][m][n], 0, 0, 0); __builtin_amdgcn_s_setprio(0); } while (0)
; #define PG8_WAIT_V(n) asm volatile("s_waitcnt vmcnt(" #n ")" ::: "memory")
; #define PG8_WAIT_L(n) asm volatile("s_waitcnt lgkmcnt(" #n ")" ::: "memory")
; #define PG8_BAR __builtin_amdgcn_s_barrier()
; #define PG8_SCHED __builtin_amdgcn_sched_barrier(0)
; template <class Epi, class Sched, bool ALIGN_EPI = false, bool SP2 = false>
; __device__ __forceinline__ void gemm_phase(PG8_LAS unsigned char* lds, const Gemm g, const Sched& S, const Epi& E, const int tid) {
;     ...
;             PG8_WAIT_V(8); PG8_WAIT_L(0); PG8_BAR; PG8_MMA(1, 0, At, B0); PG8_MMA(1, 1, At, B1); PG8_BAR; PG8_SCHED;
;             PG8_LDB(B0, 1, 0); PG8_LDB(B1, 1, 1); PG8_SCHED; PG8_LDA(At, 1, 0); PG8_STAGE(PG8_SA(0, 1), a2 + hstep, voffA);
;             PG8_WAIT_V(8); PG8_WAIT_L(0); PG8_BAR; PG8_MMA(0, 0, At, B0); PG8_MMA(0, 1, At, B1); PG8_BAR; PG8_SCHED;
	s_waitcnt lgkmcnt(0)
	v_mfma_f32_16x16x32_bf16 v[64:67], v[132:135], v[200:203], 0
	v_mfma_f32_16x16x32_bf16 v[60:63], v[140:143], v[200:203], 0
	v_mfma_f32_16x16x32_bf16 v[48:51], v[132:135], v[208:211], 0
	v_mfma_f32_16x16x32_bf16 v[44:47], v[140:143], v[208:211], 0
	v_mfma_f32_16x16x32_bf16 v[32:35], v[132:135], v[216:219], 0
	v_mfma_f32_16x16x32_bf16 v[28:31], v[140:143], v[216:219], 0
	v_mfma_f32_16x16x32_bf16 v[16:19], v[132:135], v[224:227], 0
	v_mfma_f32_16x16x32_bf16 v[12:15], v[140:143], v[224:227], 0
	v_mfma_f32_16x16x32_bf16 v[64:67], v[136:139], v[204:207], v[64:67]
	v_mfma_f32_16x16x32_bf16 v[60:63], v[174:177], v[204:207], v[60:63]
	v_mfma_f32_16x16x32_bf16 v[48:51], v[136:139], v[212:215], v[48:51]
	v_mfma_f32_16x16x32_bf16 v[44:47], v[174:177], v[212:215], v[44:47]
	v_mfma_f32_16x16x32_bf16 v[32:35], v[136:139], v[220:223], v[32:35]
	v_mfma_f32_16x16x32_bf16 v[28:31], v[174:177], v[220:223], v[28:31]
	v_mfma_f32_16x16x32_bf16 v[16:19], v[136:139], v[238:241], v[16:19]
	v_mfma_f32_16x16x32_bf16 v[12:15], v[174:177], v[238:241], v[12:15]
	v_mfma_f32_16x16x32_bf16 v[56:59], v[178:181], v[200:203], 0
	v_mfma_f32_16x16x32_bf16 v[52:55], v[192:195], v[200:203], 0
	v_mfma_f32_16x16x32_bf16 v[40:43], v[178:181], v[208:211], 0
	v_mfma_f32_16x16x32_bf16 v[36:39], v[192:195], v[208:211], 0
	v_mfma_f32_16x16x32_bf16 v[24:27], v[178:181], v[216:219], 0
	v_mfma_f32_16x16x32_bf16 v[20:23], v[192:195], v[216:219], 0
	v_mfma_f32_16x16x32_bf16 v[8:11], v[178:181], v[224:227], 0
	v_mfma_f32_16x16x32_bf16 v[4:7], v[192:195], v[224:227], 0
	v_mfma_f32_16x16x32_bf16 v[56:59], v[188:191], v[204:207], v[56:59]
	v_mfma_f32_16x16x32_bf16 v[52:55], v[196:199], v[204:207], v[52:55]
	v_mfma_f32_16x16x32_bf16 v[40:43], v[188:191], v[212:215], v[40:43]
	v_mfma_f32_16x16x32_bf16 v[36:39], v[196:199], v[212:215], v[36:39]
	v_mfma_f32_16x16x32_bf16 v[24:27], v[188:191], v[220:223], v[24:27]
	v_mfma_f32_16x16x32_bf16 v[20:23], v[196:199], v[220:223], v[20:23]
	v_mfma_f32_16x16x32_bf16 v[8:11], v[188:191], v[238:241], v[8:11]
	v_mfma_f32_16x16x32_bf16 v[4:7], v[196:199], v[238:241], v[4:7]
	s_barrier
	s_add_i32 s81, 0, 0x18000
	v_add_u32_e32 v150, s81, v184
	s_add_i32 s82, 0, 0x1c000
	ds_read_b128 v[132:135], v150
	ds_read_b128 v[136:139], v150 offset:1024
	ds_read_b128 v[140:143], v150 offset:2048
	ds_read_b128 v[174:177], v150 offset:3072
	v_add_u32_e32 v150, s82, v184
	ds_read_b128 v[178:181], v150
	ds_read_b128 v[188:191], v150 offset:1024
	ds_read_b128 v[192:195], v150 offset:2048
	ds_read_b128 v[196:199], v150 offset:3072
	s_add_u32 s58, s58, s14
	s_addc_u32 s59, s59, 0
	s_mov_b32 m0, s64
	v_lshl_add_u64 v[150:151], s[58:59], 0, v[0:1]
	ds_read_b128 v[200:203], v186 offset:32768
	ds_read_b128 v[204:207], v186 offset:33792
	ds_read_b128 v[208:211], v186 offset:34816
	ds_read_b128 v[212:215], v186 offset:35840
	ds_read_b128 v[216:219], v186 offset:36864
	ds_read_b128 v[220:223], v186 offset:37888
	ds_read_b128 v[224:227], v186 offset:38912
	ds_read_b128 v[238:241], v186 offset:39936
	global_load_lds_dwordx4 v[150:151], off
	s_mov_b32 m0, s65
	v_lshl_add_u64 v[150:151], s[58:59], 0, v[166:167]
	global_load_lds_dwordx4 v[150:151], off
	s_waitcnt vmcnt(8)
	s_waitcnt lgkmcnt(0)
	s_barrier
	s_waitcnt lgkmcnt(0)
	v_mfma_f32_16x16x32_bf16 v[128:131], v[132:135], v[200:203], v[128:131]
	v_mfma_f32_16x16x32_bf16 v[124:127], v[140:143], v[200:203], v[124:127]
	v_mfma_f32_16x16x32_bf16 v[112:115], v[132:135], v[208:211], v[112:115]
	v_mfma_f32_16x16x32_bf16 v[108:111], v[140:143], v[208:211], v[108:111]
	v_mfma_f32_16x16x32_bf16 v[96:99], v[132:135], v[216:219], v[96:99]
	v_mfma_f32_16x16x32_bf16 v[92:95], v[140:143], v[216:219], v[92:95]
	v_mfma_f32_16x16x32_bf16 v[80:83], v[132:135], v[224:227], v[80:83]
	v_mfma_f32_16x16x32_bf16 v[76:79], v[140:143], v[224:227], v[76:79]
	v_mfma_f32_16x16x32_bf16 v[128:131], v[136:139], v[204:207], v[128:131]
	v_mfma_f32_16x16x32_bf16 v[124:127], v[174:177], v[204:207], v[124:127]
	v_mfma_f32_16x16x32_bf16 v[112:115], v[136:139], v[212:215], v[112:115]
	v_mfma_f32_16x16x32_bf16 v[108:111], v[174:177], v[212:215], v[108:111]
	v_mfma_f32_16x16x32_bf16 v[96:99], v[136:139], v[220:223], v[96:99]
	v_mfma_f32_16x16x32_bf16 v[92:95], v[174:177], v[220:223], v[92:95]
	v_mfma_f32_16x16x32_bf16 v[80:83], v[136:139], v[238:241], v[80:83]
	v_mfma_f32_16x16x32_bf16 v[76:79], v[174:177], v[238:241], v[76:79]
	v_mfma_f32_16x16x32_bf16 v[120:123], v[178:181], v[200:203], v[120:123]
	v_mfma_f32_16x16x32_bf16 v[116:119], v[192:195], v[200:203], v[116:119]
	v_mfma_f32_16x16x32_bf16 v[104:107], v[178:181], v[208:211], v[104:107]
	v_mfma_f32_16x16x32_bf16 v[100:103], v[192:195], v[208:211], v[100:103]
	v_mfma_f32_16x16x32_bf16 v[88:91], v[178:181], v[216:219], v[88:91]
	v_mfma_f32_16x16x32_bf16 v[84:87], v[192:195], v[216:219], v[84:87]
	v_mfma_f32_16x16x32_bf16 v[72:75], v[178:181], v[224:227], v[72:75]
	v_mfma_f32_16x16x32_bf16 v[68:71], v[192:195], v[224:227], v[68:71]
	v_mfma_f32_16x16x32_bf16 v[120:123], v[188:191], v[204:207], v[120:123]
	v_mfma_f32_16x16x32_bf16 v[116:119], v[196:199], v[204:207], v[116:119]
	v_mfma_f32_16x16x32_bf16 v[104:107], v[188:191], v[212:215], v[104:107]
	v_mfma_f32_16x16x32_bf16 v[100:103], v[196:199], v[212:215], v[100:103]
	v_mfma_f32_16x16x32_bf16 v[88:91], v[188:191], v[220:223], v[88:91]
	v_mfma_f32_16x16x32_bf16 v[84:87], v[196:199], v[220:223], v[84:87]
	v_mfma_f32_16x16x32_bf16 v[72:75], v[188:191], v[238:241], v[72:75]
	v_mfma_f32_16x16x32_bf16 v[68:71], v[196:199], v[238:241], v[68:71]
	s_barrier
; #define PG8_STAGE(bufoff, gbase, voff) do { _Pragma("unroll") for (int _i = 0; _i < 2; ++_i) \
;         __builtin_amdgcn_global_load_lds((const unsigned*)((const char*)(gbase) + (voff)[_i]), (PG8_LAS unsigned*)(lds + (bufoff) + ldsw + _i * 8192), 16, 0, 0); } while (0)
; #define PG8_LDA(dst, b, h) do { _Pragma("unroll") for (int m = 0; m < 4; ++m) _Pragma("unroll") for (int k = 0; k < 2; ++k) dst[m][k] = *(const PG8_LAS bf16x8*)(lds + PG8_SA(b, h) + aoff + m * 2048 + k * 1024); } while (0)
; #define PG8_WAIT_V(n) asm volatile("s_waitcnt vmcnt(" #n ")" ::: "memory")
; #define PG8_WAIT_L(n) asm volatile("s_waitcnt lgkmcnt(" #n ")" ::: "memory")
; #define PG8_BAR __builtin_amdgcn_s_barrier()
; template <class Epi, class Sched, bool ALIGN_EPI = false, bool SP2 = false>
; __device__ __forceinline__ void gemm_phase(PG8_LAS unsigned char* lds, const Gemm g, const Sched& S, const Epi& E, const int tid) {
;     ...
;         for (int t = 0; t < nt; t += 2) {
;             const bool last = (t == nt - 2);
;             const char* a1 = cA + (size_t)(t + 1) * kstep;
;             const char* a2 = last ? nA : cA + (size_t)(t + 2) * kstep; const char* b2 = last ? nB : cB + (size_t)(t + 2) * kstep;
;             const char* a3 = a2 + kstep; const char* b3 = b2 + kstep;
;             if (last && has_next) S.a_ready(nxt);
;             if constexpr (SP2) {
;             PG8_LDB(B0, 0, 0); PG8_LDB(B1, 0, 1); PG8_SCHED; PG8_LDA(At, 0, 0); PG8_STAGE(PG8_SA(1, 1), a1 + hstep, voffA);
;             PG8_WAIT_V(8); PG8_WAIT_L(0); PG8_BAR; PG8_MMA(0, 0, At, B0); PG8_MMA(0, 1, At, B1); PG8_BAR; PG8_SCHED;
;             PG8_LDA(At, 0, 1); PG8_STAGE(PG8_SB(0, 0), b2, voffB); PG8_STAGE(PG8_SB(0, 1), b2 + hstep, voffB); PG8_STAGE(PG8_SA(0, 0), a2, voffA);
;             PG8_WAIT_V(8); PG8_WAIT_L(0); PG8_BAR; PG8_MMA(1, 0, At, B0); PG8_MMA(1, 1, At, B1); PG8_BAR; PG8_SCHED;
;             PG8_LDB(B0, 1, 0); PG8_LDB(B1, 1, 1); PG8_SCHED; PG8_LDA(At, 1, 0); PG8_STAGE(PG8_SA(0, 1), a2 + hstep, voffA);
;             PG8_WAIT_V(8); PG8_WAIT_L(0); PG8_BAR; PG8_MMA(0, 0, At, B0); PG8_MMA(0, 1, At, B1); PG8_BAR; PG8_SCHED;
;             PG8_LDA(At, 1, 1); PG8_STAGE(PG8_SB(1, 0), b3, voffB); PG8_STAGE(PG8_SB(1, 1), b3 + hstep, voffB); PG8_STAGE(PG8_SA(1, 0), a3, voffA);
;             PG8_WAIT_V(8); PG8_WAIT_L(0); PG8_BAR; PG8_MMA(1, 0, At, B0); PG8_MMA(1, 1, At, B1); PG8_BAR; PG8_SCHED;
	s_add_i32 s58, s81, s61
	v_lshl_add_u64 v[144:145], v[144:145], 0, s[0:1]
	s_mov_b32 m0, s58
	ds_read_b128 v[200:203], v186 offset:49152
	ds_read_b128 v[204:207], v186 offset:50176
	ds_read_b128 v[208:211], v186 offset:51200
	ds_read_b128 v[212:215], v186 offset:52224
	ds_read_b128 v[216:219], v186 offset:53248
	ds_read_b128 v[220:223], v186 offset:54272
	ds_read_b128 v[224:227], v186 offset:55296
	ds_read_b128 v[238:241], v186 offset:56320
	global_load_lds_dwordx4 v[144:145], off
	v_lshl_add_u64 v[144:145], v[242:243], 0, s[0:1]
	s_add_i32 m0, s58, 0x2000
	s_add_i32 s58, s82, s61
	global_load_lds_dwordx4 v[144:145], off
	s_mov_b32 m0, s58
	v_lshl_add_u64 v[144:145], v[244:245], 0, s[0:1]
	global_load_lds_dwordx4 v[144:145], off
	s_add_i32 m0, s58, 0x2000
	v_lshl_add_u64 v[144:145], v[246:247], 0, s[0:1]
	global_load_lds_dwordx4 v[144:145], off
	s_mov_b32 m0, s66
	v_lshl_add_u64 v[144:145], v[248:249], 0, s[0:1]
	global_load_lds_dwordx4 v[144:145], off
	s_mov_b32 m0, s67
	v_lshl_add_u64 v[144:145], v[148:149], 0, s[0:1]
	global_load_lds_dwordx4 v[144:145], off
	s_waitcnt vmcnt(8)
	s_waitcnt lgkmcnt(0)
	s_barrier
	s_waitcnt lgkmcnt(0)
	v_mfma_f32_16x16x32_bf16 v[64:67], v[132:135], v[200:203], v[64:67]
	v_mfma_f32_16x16x32_bf16 v[60:63], v[140:143], v[200:203], v[60:63]
	v_mfma_f32_16x16x32_bf16 v[48:51], v[132:135], v[208:211], v[48:51]
	v_mfma_f32_16x16x32_bf16 v[44:47], v[140:143], v[208:211], v[44:47]
	v_mfma_f32_16x16x32_bf16 v[32:35], v[132:135], v[216:219], v[32:35]
	v_mfma_f32_16x16x32_bf16 v[28:31], v[140:143], v[216:219], v[28:31]
	v_mfma_f32_16x16x32_bf16 v[16:19], v[132:135], v[224:227], v[16:19]
	v_mfma_f32_16x16x32_bf16 v[12:15], v[140:143], v[224:227], v[12:15]
	v_mfma_f32_16x16x32_bf16 v[64:67], v[136:139], v[204:207], v[64:67]
	v_mfma_f32_16x16x32_bf16 v[60:63], v[174:177], v[204:207], v[60:63]
	v_mfma_f32_16x16x32_bf16 v[48:51], v[136:139], v[212:215], v[48:51]
	v_mfma_f32_16x16x32_bf16 v[44:47], v[174:177], v[212:215], v[44:47]
	v_mfma_f32_16x16x32_bf16 v[32:35], v[136:139], v[220:223], v[32:35]
	v_mfma_f32_16x16x32_bf16 v[28:31], v[174:177], v[220:223], v[28:31]
	v_mfma_f32_16x16x32_bf16 v[16:19], v[136:139], v[238:241], v[16:19]
	v_mfma_f32_16x16x32_bf16 v[12:15], v[174:177], v[238:241], v[12:15]
	v_mfma_f32_16x16x32_bf16 v[56:59], v[178:181], v[200:203], v[56:59]
	v_mfma_f32_16x16x32_bf16 v[52:55], v[192:195], v[200:203], v[52:55]
	v_mfma_f32_16x16x32_bf16 v[40:43], v[178:181], v[208:211], v[40:43]
	v_mfma_f32_16x16x32_bf16 v[36:39], v[192:195], v[208:211], v[36:39]
	v_mfma_f32_16x16x32_bf16 v[24:27], v[178:181], v[216:219], v[24:27]
	v_mfma_f32_16x16x32_bf16 v[20:23], v[192:195], v[216:219], v[20:23]
	v_mfma_f32_16x16x32_bf16 v[8:11], v[178:181], v[224:227], v[8:11]
	v_mfma_f32_16x16x32_bf16 v[4:7], v[192:195], v[224:227], v[4:7]
	v_mfma_f32_16x16x32_bf16 v[56:59], v[188:191], v[204:207], v[56:59]
	v_mfma_f32_16x16x32_bf16 v[52:55], v[196:199], v[204:207], v[52:55]
	v_mfma_f32_16x16x32_bf16 v[40:43], v[188:191], v[212:215], v[40:43]
	v_mfma_f32_16x16x32_bf16 v[36:39], v[196:199], v[212:215], v[36:39]
	v_mfma_f32_16x16x32_bf16 v[24:27], v[188:191], v[220:223], v[24:27]
	v_mfma_f32_16x16x32_bf16 v[20:23], v[196:199], v[220:223], v[20:23]
	v_mfma_f32_16x16x32_bf16 v[8:11], v[188:191], v[238:241], v[8:11]
	v_mfma_f32_16x16x32_bf16 v[4:7], v[196:199], v[238:241], v[4:7]
	s_barrier
	s_add_u32 s6, s6, 0x100
	s_addc_u32 s7, s7, 0
	s_add_u32 s78, s78, 0x100
	s_addc_u32 s79, s79, 0
	s_cmp_ge_u32 s80, s69
	s_mov_b32 s58, s80
	s_cbranch_scc0 .LBB0_476
	s_branch .Lpeel_exit2
.LBB0_476:
	s_add_i32 s80, s58, 2
	s_add_u32 s81, s6, 0x80
	s_addc_u32 s59, s7, 0
	s_add_i32 s87, 0, 0x10000
	s_cmp_eq_u32 s70, s58
	s_cselect_b32 s59, s55, s59
	s_cselect_b32 s58, s54, s81
	v_add_u32_e32 v144, s87, v184
	s_cselect_b32 s83, s57, s79
	s_cselect_b32 s82, s56, s78
	s_add_i32 s81, 0, 0x14000
	ds_read_b128 v[132:135], v144
	ds_read_b128 v[136:139], v144 offset:1024
	ds_read_b128 v[140:143], v144 offset:2048
	ds_read_b128 v[174:177], v144 offset:3072
	v_add_u32_e32 v144, s81, v184
	ds_read_b128 v[178:181], v144
	ds_read_b128 v[188:191], v144 offset:1024
	ds_read_b128 v[192:195], v144 offset:2048
	ds_read_b128 v[196:199], v144 offset:3072
	v_lshl_add_u64 v[144:145], s[6:7], 0, v[170:171]
	s_add_i32 m0, s62, 0xc000
	ds_read_b128 v[200:203], v186
	ds_read_b128 v[204:207], v186 offset:1024
	ds_read_b128 v[208:211], v186 offset:2048
	ds_read_b128 v[212:215], v186 offset:3072
	ds_read_b128 v[216:219], v186 offset:4096
	ds_read_b128 v[220:223], v186 offset:5120
	ds_read_b128 v[224:227], v186 offset:6144
	ds_read_b128 v[238:241], v186 offset:7168
	global_load_lds_dwordx4 v[144:145], off
	s_add_i32 m0, s62, 0xe000
	v_lshl_add_u64 v[144:145], s[6:7], 0, v[172:173]
	global_load_lds_dwordx4 v[144:145], off
	s_waitcnt vmcnt(8)
	s_waitcnt lgkmcnt(0)
	s_barrier
; #define PG8_STAGE(bufoff, gbase, voff) do { _Pragma("unroll") for (int _i = 0; _i < 2; ++_i) \
;         __builtin_amdgcn_global_load_lds((const unsigned*)((const char*)(gbase) + (voff)[_i]), (PG8_LAS unsigned*)(lds + (bufoff) + ldsw + _i * 8192), 16, 0, 0); } while (0)
; #define PG8_LDA(dst, b, h) do { _Pragma("unroll") for (int m = 0; m < 4; ++m) _Pragma("unroll") for (int k = 0; k < 2; ++k) dst[m][k] = *(const PG8_LAS bf16x8*)(lds + PG8_SA(b, h) + aoff + m * 2048 + k * 1024); } while (0)
; #define PG8_LDB(dst, b, h) do { _Pragma("unroll") for (int n = 0; n < 2; ++n) _Pragma("unroll") for (int k = 0; k < 2; ++k) dst[n][k] = *(const PG8_LAS bf16x8*)(lds + PG8_SB(b, h) + boff + n * 2048 + k * 1024); } while (0)
; #define PG8_MMA(ai, bj, At, Bt) do { __builtin_amdgcn_s_setprio(1); _Pragma("unroll") for (int m = 0; m < 4; ++m) _Pragma("unroll") for (int n = 0; n < 2; ++n) _Pragma("unroll") for (int k = 0; k < 2; ++k) \
;         acc[ai][bj][m][n] = __builtin_amdgcn_mfma_f32_16x16x32_bf16(Bt[n][k], At[m][k], acc[ai][bj][m][n], 0, 0, 0); __builtin_amdgcn_s_setprio(0); } while (0)
; #define PG8_WAIT_V(n) asm volatile("s_waitcnt vmcnt(" #n ")" ::: "memory")
; #define PG8_WAIT_L(n) asm volatile("s_waitcnt lgkmcnt(" #n ")" ::: "memory")
; #define PG8_BAR __builtin_amdgcn_s_barrier()
; #define PG8_SCHED __builtin_amdgcn_sched_barrier(0)
; template <class Epi, class Sched, bool ALIGN_EPI = false, bool SP2 = false>
; __device__ __forceinline__ void gemm_phase(PG8_LAS unsigned char* lds, const Gemm g, const Sched& S, const Epi& E, const int tid) {
;     ...
;             PG8_LDB(B0, 0, 0); PG8_LDB(B1, 0, 1); PG8_SCHED; PG8_LDA(At, 0, 0); PG8_STAGE(PG8_SA(1, 1), a1 + hstep, voffA);
;             PG8_WAIT_V(8); PG8_WAIT_L(0); PG8_BAR; PG8_MMA(0, 0, At, B0); PG8_MMA(0, 1, At, B1); PG8_BAR; PG8_SCHED;
;             PG8_LDA(At, 0, 1); PG8_STAGE(PG8_SB(0, 0), b2, voffB); PG8_STAGE(PG8_SB(0, 1), b2 + hstep, voffB); PG8_STAGE(PG8_SA(0, 0), a2, voffA);
;             PG8_WAIT_V(8); PG8_WAIT_L(0); PG8_BAR; PG8_MMA(1, 0, At, B0); PG8_MMA(1, 1, At, B1); PG8_BAR; PG8_SCHED;
	s_waitcnt lgkmcnt(0)
	v_mfma_f32_16x16x32_bf16 v[128:131], v[132:135], v[200:203], v[128:131]
	v_mfma_f32_16x16x32_bf16 v[124:127], v[140:143], v[200:203], v[124:127]
	v_mfma_f32_16x16x32_bf16 v[112:115], v[132:135], v[208:211], v[112:115]
	v_mfma_f32_16x16x32_bf16 v[108:111], v[140:143], v[208:211], v[108:111]
	v_mfma_f32_16x16x32_bf16 v[96:99], v[132:135], v[216:219], v[96:99]
	v_mfma_f32_16x16x32_bf16 v[92:95], v[140:143], v[216:219], v[92:95]
	v_mfma_f32_16x16x32_bf16 v[80:83], v[132:135], v[224:227], v[80:83]
	v_mfma_f32_16x16x32_bf16 v[76:79], v[140:143], v[224:227], v[76:79]
	v_mfma_f32_16x16x32_bf16 v[128:131], v[136:139], v[204:207], v[128:131]
	v_mfma_f32_16x16x32_bf16 v[124:127], v[174:177], v[204:207], v[124:127]
	v_mfma_f32_16x16x32_bf16 v[112:115], v[136:139], v[212:215], v[112:115]
	v_mfma_f32_16x16x32_bf16 v[108:111], v[174:177], v[212:215], v[108:111]
	v_mfma_f32_16x16x32_bf16 v[96:99], v[136:139], v[220:223], v[96:99]
	v_mfma_f32_16x16x32_bf16 v[92:95], v[174:177], v[220:223], v[92:95]
	v_mfma_f32_16x16x32_bf16 v[80:83], v[136:139], v[238:241], v[80:83]
	v_mfma_f32_16x16x32_bf16 v[76:79], v[174:177], v[238:241], v[76:79]
	v_mfma_f32_16x16x32_bf16 v[120:123], v[178:181], v[200:203], v[120:123]
	v_mfma_f32_16x16x32_bf16 v[116:119], v[192:195], v[200:203], v[116:119]
	v_mfma_f32_16x16x32_bf16 v[104:107], v[178:181], v[208:211], v[104:107]
	v_mfma_f32_16x16x32_bf16 v[100:103], v[192:195], v[208:211], v[100:103]
	v_mfma_f32_16x16x32_bf16 v[88:91], v[178:181], v[216:219], v[88:91]
	v_mfma_f32_16x16x32_bf16 v[84:87], v[192:195], v[216:219], v[84:87]
	v_mfma_f32_16x16x32_bf16 v[72:75], v[178:181], v[224:227], v[72:75]
	v_mfma_f32_16x16x32_bf16 v[68:71], v[192:195], v[224:227], v[68:71]
	v_mfma_f32_16x16x32_bf16 v[120:123], v[188:191], v[204:207], v[120:123]
	v_mfma_f32_16x16x32_bf16 v[116:119], v[196:199], v[204:207], v[116:119]
	v_mfma_f32_16x16x32_bf16 v[104:107], v[188:191], v[212:215], v[104:107]
	v_mfma_f32_16x16x32_bf16 v[100:103], v[196:199], v[212:215], v[100:103]
	v_mfma_f32_16x16x32_bf16 v[88:91], v[188:191], v[220:223], v[88:91]
	v_mfma_f32_16x16x32_bf16 v[84:87], v[196:199], v[220:223], v[84:87]
	v_mfma_f32_16x16x32_bf16 v[72:75], v[188:191], v[238:241], v[72:75]
	v_mfma_f32_16x16x32_bf16 v[68:71], v[196:199], v[238:241], v[68:71]
	s_barrier
	s_add_i32 s87, s87, s61
	v_lshl_add_u64 v[144:145], s[82:83], 0, v[146:147]
	s_mov_b32 m0, s87
	ds_read_b128 v[200:203], v186 offset:16384
	ds_read_b128 v[204:207], v186 offset:17408
	ds_read_b128 v[208:211], v186 offset:18432
	ds_read_b128 v[212:215], v186 offset:19456
	ds_read_b128 v[216:219], v186 offset:20480
	ds_read_b128 v[220:223], v186 offset:21504
	ds_read_b128 v[224:227], v186 offset:22528
	ds_read_b128 v[238:241], v186 offset:23552
	global_load_lds_dwordx4 v[144:145], off
	s_add_i32 m0, s87, 0x2000
	v_lshl_add_u64 v[242:243], s[82:83], 0, v[168:169]
	s_add_u32 s82, s82, s14
	s_addc_u32 s83, s83, 0
	s_add_i32 s81, s81, s61
	global_load_lds_dwordx4 v[242:243], off
	v_lshl_add_u64 v[244:245], s[82:83], 0, v[146:147]
	s_mov_b32 m0, s81
	v_lshl_add_u64 v[246:247], s[82:83], 0, v[168:169]
	global_load_lds_dwordx4 v[244:245], off
	s_add_i32 m0, s81, 0x2000
	v_lshl_add_u64 v[248:249], s[58:59], 0, v[0:1]
	global_load_lds_dwordx4 v[246:247], off
	s_mov_b32 m0, s62
	v_lshl_add_u64 v[148:149], s[58:59], 0, v[166:167]
	global_load_lds_dwordx4 v[248:249], off
	s_mov_b32 m0, s63
	s_nop 0
	global_load_lds_dwordx4 v[148:149], off
	s_waitcnt vmcnt(8)
	s_waitcnt lgkmcnt(0)
	s_barrier
	s_waitcnt lgkmcnt(0)
	v_mfma_f32_16x16x32_bf16 v[64:67], v[132:135], v[200:203], v[64:67]
	v_mfma_f32_16x16x32_bf16 v[60:63], v[140:143], v[200:203], v[60:63]
	v_mfma_f32_16x16x32_bf16 v[48:51], v[132:135], v[208:211], v[48:51]
	v_mfma_f32_16x16x32_bf16 v[44:47], v[140:143], v[208:211], v[44:47]
	v_mfma_f32_16x16x32_bf16 v[32:35], v[132:135], v[216:219], v[32:35]
	v_mfma_f32_16x16x32_bf16 v[28:31], v[140:143], v[216:219], v[28:31]
	v_mfma_f32_16x16x32_bf16 v[16:19], v[132:135], v[224:227], v[16:19]
	v_mfma_f32_16x16x32_bf16 v[12:15], v[140:143], v[224:227], v[12:15]
	v_mfma_f32_16x16x32_bf16 v[64:67], v[136:139], v[204:207], v[64:67]
	v_mfma_f32_16x16x32_bf16 v[60:63], v[174:177], v[204:207], v[60:63]
	v_mfma_f32_16x16x32_bf16 v[48:51], v[136:139], v[212:215], v[48:51]
	v_mfma_f32_16x16x32_bf16 v[44:47], v[174:177], v[212:215], v[44:47]
	v_mfma_f32_16x16x32_bf16 v[32:35], v[136:139], v[220:223], v[32:35]
	v_mfma_f32_16x16x32_bf16 v[28:31], v[174:177], v[220:223], v[28:31]
	v_mfma_f32_16x16x32_bf16 v[16:19], v[136:139], v[238:241], v[16:19]
	v_mfma_f32_16x16x32_bf16 v[12:15], v[174:177], v[238:241], v[12:15]
	v_mfma_f32_16x16x32_bf16 v[56:59], v[178:181], v[200:203], v[56:59]
	v_mfma_f32_16x16x32_bf16 v[52:55], v[192:195], v[200:203], v[52:55]
	v_mfma_f32_16x16x32_bf16 v[40:43], v[178:181], v[208:211], v[40:43]
	v_mfma_f32_16x16x32_bf16 v[36:39], v[192:195], v[208:211], v[36:39]
	v_mfma_f32_16x16x32_bf16 v[24:27], v[178:181], v[216:219], v[24:27]
	v_mfma_f32_16x16x32_bf16 v[20:23], v[192:195], v[216:219], v[20:23]
	v_mfma_f32_16x16x32_bf16 v[8:11], v[178:181], v[224:227], v[8:11]
	v_mfma_f32_16x16x32_bf16 v[4:7], v[192:195], v[224:227], v[4:7]
	v_mfma_f32_16x16x32_bf16 v[56:59], v[188:191], v[204:207], v[56:59]
	v_mfma_f32_16x16x32_bf16 v[52:55], v[196:199], v[204:207], v[52:55]
	v_mfma_f32_16x16x32_bf16 v[40:43], v[188:191], v[212:215], v[40:43]
	v_mfma_f32_16x16x32_bf16 v[36:39], v[196:199], v[212:215], v[36:39]
	v_mfma_f32_16x16x32_bf16 v[24:27], v[188:191], v[220:223], v[24:27]
	v_mfma_f32_16x16x32_bf16 v[20:23], v[196:199], v[220:223], v[20:23]
	v_mfma_f32_16x16x32_bf16 v[8:11], v[188:191], v[238:241], v[8:11]
	v_mfma_f32_16x16x32_bf16 v[4:7], v[196:199], v[238:241], v[4:7]
	s_barrier
; #define PG8_STAGE(bufoff, gbase, voff) do { _Pragma("unroll") for (int _i = 0; _i < 2; ++_i) \
;         __builtin_amdgcn_global_load_lds((const unsigned*)((const char*)(gbase) + (voff)[_i]), (PG8_LAS unsigned*)(lds + (bufoff) + ldsw + _i * 8192), 16, 0, 0); } while (0)
; #define PG8_LDA(dst, b, h) do { _Pragma("unroll") for (int m = 0; m < 4; ++m) _Pragma("unroll") for (int k = 0; k < 2; ++k) dst[m][k] = *(const PG8_LAS bf16x8*)(lds + PG8_SA(b, h) + aoff + m * 2048 + k * 1024); } while (0)
; #define PG8_LDB(dst, b, h) do { _Pragma("unroll") for (int n = 0; n < 2; ++n) _Pragma("unroll") for (int k = 0; k < 2; ++k) dst[n][k] = *(const PG8_LAS bf16x8*)(lds + PG8_SB(b, h) + boff + n * 2048 + k * 1024); } while (0)
; #define PG8_MMA(ai, bj, At, Bt) do { __builtin_amdgcn_s_setprio(1); _Pragma("unroll") for (int m = 0; m < 4; ++m) _Pragma("unroll") for (int n = 0; n < 2; ++n) _Pragma("unroll") for (int k = 0; k < 2; ++k) \
;         acc[ai][bj][m][n] = __builtin_amdgcn_mfma_f32_16x16x32_bf16(Bt[n][k], At[m][k], acc[ai][bj][m][n], 0, 0, 0); __builtin_amdgcn_s_setprio(0); } while (0)
; #define PG8_WAIT_V(n) asm volatile("s_waitcnt vmcnt(" #n ")" ::: "memory")
; #define PG8_WAIT_L(n) asm volatile("s_waitcnt lgkmcnt(" #n ")" ::: "memory")
; #define PG8_BAR __builtin_amdgcn_s_barrier()
; #define PG8_SCHED __builtin_amdgcn_sched_barrier(0)
; template <class Epi, class Sched, bool ALIGN_EPI = false, bool SP2 = false>
; __device__ __forceinline__ void gemm_phase(PG8_LAS unsigned char* lds, const Gemm g, const Sched& S, const Epi& E, const int tid) {
;     ...
;             PG8_LDB(B0, 1, 0); PG8_LDB(B1, 1, 1); PG8_SCHED; PG8_LDA(At, 1, 0); PG8_STAGE(PG8_SA(0, 1), a2 + hstep, voffA);
;             PG8_WAIT_V(8); PG8_WAIT_L(0); PG8_BAR; PG8_MMA(0, 0, At, B0); PG8_MMA(0, 1, At, B1); PG8_BAR; PG8_SCHED;
;             PG8_LDA(At, 1, 1); PG8_STAGE(PG8_SB(1, 0), b3, voffB); PG8_STAGE(PG8_SB(1, 1), b3 + hstep, voffB); PG8_STAGE(PG8_SA(1, 0), a3, voffA);
;             PG8_WAIT_V(8); PG8_WAIT_L(0); PG8_BAR; PG8_MMA(1, 0, At, B0); PG8_MMA(1, 1, At, B1); PG8_BAR; PG8_SCHED;
	s_add_i32 s81, 0, 0x18000
	v_add_u32_e32 v150, s81, v184
	s_add_i32 s82, 0, 0x1c000
	ds_read_b128 v[132:135], v150
	ds_read_b128 v[136:139], v150 offset:1024
	ds_read_b128 v[140:143], v150 offset:2048
	ds_read_b128 v[174:177], v150 offset:3072
	v_add_u32_e32 v150, s82, v184
	ds_read_b128 v[178:181], v150
	ds_read_b128 v[188:191], v150 offset:1024
	ds_read_b128 v[192:195], v150 offset:2048
	ds_read_b128 v[196:199], v150 offset:3072
	s_add_u32 s58, s58, s14
	s_addc_u32 s59, s59, 0
	s_mov_b32 m0, s64
	v_lshl_add_u64 v[150:151], s[58:59], 0, v[0:1]
	ds_read_b128 v[200:203], v186 offset:32768
	ds_read_b128 v[204:207], v186 offset:33792
	ds_read_b128 v[208:211], v186 offset:34816
	ds_read_b128 v[212:215], v186 offset:35840
	ds_read_b128 v[216:219], v186 offset:36864
	ds_read_b128 v[220:223], v186 offset:37888
	ds_read_b128 v[224:227], v186 offset:38912
	ds_read_b128 v[238:241], v186 offset:39936
	global_load_lds_dwordx4 v[150:151], off
	s_mov_b32 m0, s65
	v_lshl_add_u64 v[150:151], s[58:59], 0, v[166:167]
	global_load_lds_dwordx4 v[150:151], off
	s_waitcnt vmcnt(8)
	s_waitcnt lgkmcnt(0)
	s_barrier
	s_waitcnt lgkmcnt(0)
	v_mfma_f32_16x16x32_bf16 v[128:131], v[132:135], v[200:203], v[128:131]
	v_mfma_f32_16x16x32_bf16 v[124:127], v[140:143], v[200:203], v[124:127]
	v_mfma_f32_16x16x32_bf16 v[112:115], v[132:135], v[208:211], v[112:115]
	v_mfma_f32_16x16x32_bf16 v[108:111], v[140:143], v[208:211], v[108:111]
	v_mfma_f32_16x16x32_bf16 v[96:99], v[132:135], v[216:219], v[96:99]
	v_mfma_f32_16x16x32_bf16 v[92:95], v[140:143], v[216:219], v[92:95]
	v_mfma_f32_16x16x32_bf16 v[80:83], v[132:135], v[224:227], v[80:83]
	v_mfma_f32_16x16x32_bf16 v[76:79], v[140:143], v[224:227], v[76:79]
	v_mfma_f32_16x16x32_bf16 v[128:131], v[136:139], v[204:207], v[128:131]
	v_mfma_f32_16x16x32_bf16 v[124:127], v[174:177], v[204:207], v[124:127]
	v_mfma_f32_16x16x32_bf16 v[112:115], v[136:139], v[212:215], v[112:115]
	v_mfma_f32_16x16x32_bf16 v[108:111], v[174:177], v[212:215], v[108:111]
	v_mfma_f32_16x16x32_bf16 v[96:99], v[136:139], v[220:223], v[96:99]
	v_mfma_f32_16x16x32_bf16 v[92:95], v[174:177], v[220:223], v[92:95]
	v_mfma_f32_16x16x32_bf16 v[80:83], v[136:139], v[238:241], v[80:83]
	v_mfma_f32_16x16x32_bf16 v[76:79], v[174:177], v[238:241], v[76:79]
	v_mfma_f32_16x16x32_bf16 v[120:123], v[178:181], v[200:203], v[120:123]
	v_mfma_f32_16x16x32_bf16 v[116:119], v[192:195], v[200:203], v[116:119]
	v_mfma_f32_16x16x32_bf16 v[104:107], v[178:181], v[208:211], v[104:107]
	v_mfma_f32_16x16x32_bf16 v[100:103], v[192:195], v[208:211], v[100:103]
	v_mfma_f32_16x16x32_bf16 v[88:91], v[178:181], v[216:219], v[88:91]
	v_mfma_f32_16x16x32_bf16 v[84:87], v[192:195], v[216:219], v[84:87]
	v_mfma_f32_16x16x32_bf16 v[72:75], v[178:181], v[224:227], v[72:75]
	v_mfma_f32_16x16x32_bf16 v[68:71], v[192:195], v[224:227], v[68:71]
	v_mfma_f32_16x16x32_bf16 v[120:123], v[188:191], v[204:207], v[120:123]
	v_mfma_f32_16x16x32_bf16 v[116:119], v[196:199], v[204:207], v[116:119]
	v_mfma_f32_16x16x32_bf16 v[104:107], v[188:191], v[212:215], v[104:107]
	v_mfma_f32_16x16x32_bf16 v[100:103], v[196:199], v[212:215], v[100:103]
	v_mfma_f32_16x16x32_bf16 v[88:91], v[188:191], v[220:223], v[88:91]
	v_mfma_f32_16x16x32_bf16 v[84:87], v[196:199], v[220:223], v[84:87]
	v_mfma_f32_16x16x32_bf16 v[72:75], v[188:191], v[238:241], v[72:75]
	v_mfma_f32_16x16x32_bf16 v[68:71], v[196:199], v[238:241], v[68:71]
	s_barrier
	s_add_i32 s58, s81, s61
	v_lshl_add_u64 v[144:145], v[144:145], 0, s[0:1]
	s_mov_b32 m0, s58
	ds_read_b128 v[200:203], v186 offset:49152
	ds_read_b128 v[204:207], v186 offset:50176
	ds_read_b128 v[208:211], v186 offset:51200
	ds_read_b128 v[212:215], v186 offset:52224
	ds_read_b128 v[216:219], v186 offset:53248
	ds_read_b128 v[220:223], v186 offset:54272
	ds_read_b128 v[224:227], v186 offset:55296
	ds_read_b128 v[238:241], v186 offset:56320
	global_load_lds_dwordx4 v[144:145], off
	v_lshl_add_u64 v[144:145], v[242:243], 0, s[0:1]
	s_add_i32 m0, s58, 0x2000
	s_add_i32 s58, s82, s61
	global_load_lds_dwordx4 v[144:145], off
	s_mov_b32 m0, s58
	v_lshl_add_u64 v[144:145], v[244:245], 0, s[0:1]
	global_load_lds_dwordx4 v[144:145], off
	s_add_i32 m0, s58, 0x2000
	v_lshl_add_u64 v[144:145], v[246:247], 0, s[0:1]
	global_load_lds_dwordx4 v[144:145], off
	s_mov_b32 m0, s66
	v_lshl_add_u64 v[144:145], v[248:249], 0, s[0:1]
	global_load_lds_dwordx4 v[144:145], off
	s_mov_b32 m0, s67
	v_lshl_add_u64 v[144:145], v[148:149], 0, s[0:1]
	global_load_lds_dwordx4 v[144:145], off
	s_waitcnt vmcnt(8)
	s_waitcnt lgkmcnt(0)
	s_barrier
	s_waitcnt lgkmcnt(0)
	v_mfma_f32_16x16x32_bf16 v[64:67], v[132:135], v[200:203], v[64:67]
	v_mfma_f32_16x16x32_bf16 v[60:63], v[140:143], v[200:203], v[60:63]
	v_mfma_f32_16x16x32_bf16 v[48:51], v[132:135], v[208:211], v[48:51]
	v_mfma_f32_16x16x32_bf16 v[44:47], v[140:143], v[208:211], v[44:47]
	v_mfma_f32_16x16x32_bf16 v[32:35], v[132:135], v[216:219], v[32:35]
	v_mfma_f32_16x16x32_bf16 v[28:31], v[140:143], v[216:219], v[28:31]
	v_mfma_f32_16x16x32_bf16 v[16:19], v[132:135], v[224:227], v[16:19]
	v_mfma_f32_16x16x32_bf16 v[12:15], v[140:143], v[224:227], v[12:15]
	v_mfma_f32_16x16x32_bf16 v[64:67], v[136:139], v[204:207], v[64:67]
	v_mfma_f32_16x16x32_bf16 v[60:63], v[174:177], v[204:207], v[60:63]
	v_mfma_f32_16x16x32_bf16 v[48:51], v[136:139], v[212:215], v[48:51]
	v_mfma_f32_16x16x32_bf16 v[44:47], v[174:177], v[212:215], v[44:47]
	v_mfma_f32_16x16x32_bf16 v[32:35], v[136:139], v[220:223], v[32:35]
	v_mfma_f32_16x16x32_bf16 v[28:31], v[174:177], v[220:223], v[28:31]
	v_mfma_f32_16x16x32_bf16 v[16:19], v[136:139], v[238:241], v[16:19]
	v_mfma_f32_16x16x32_bf16 v[12:15], v[174:177], v[238:241], v[12:15]
	v_mfma_f32_16x16x32_bf16 v[56:59], v[178:181], v[200:203], v[56:59]
	v_mfma_f32_16x16x32_bf16 v[52:55], v[192:195], v[200:203], v[52:55]
	v_mfma_f32_16x16x32_bf16 v[40:43], v[178:181], v[208:211], v[40:43]
	v_mfma_f32_16x16x32_bf16 v[36:39], v[192:195], v[208:211], v[36:39]
	v_mfma_f32_16x16x32_bf16 v[24:27], v[178:181], v[216:219], v[24:27]
	v_mfma_f32_16x16x32_bf16 v[20:23], v[192:195], v[216:219], v[20:23]
	v_mfma_f32_16x16x32_bf16 v[8:11], v[178:181], v[224:227], v[8:11]
	v_mfma_f32_16x16x32_bf16 v[4:7], v[192:195], v[224:227], v[4:7]
	v_mfma_f32_16x16x32_bf16 v[56:59], v[188:191], v[204:207], v[56:59]
	v_mfma_f32_16x16x32_bf16 v[52:55], v[196:199], v[204:207], v[52:55]
	v_mfma_f32_16x16x32_bf16 v[40:43], v[188:191], v[212:215], v[40:43]
	v_mfma_f32_16x16x32_bf16 v[36:39], v[196:199], v[212:215], v[36:39]
	v_mfma_f32_16x16x32_bf16 v[24:27], v[188:191], v[220:223], v[24:27]
	v_mfma_f32_16x16x32_bf16 v[20:23], v[196:199], v[220:223], v[20:23]
	v_mfma_f32_16x16x32_bf16 v[8:11], v[188:191], v[238:241], v[8:11]
	v_mfma_f32_16x16x32_bf16 v[4:7], v[196:199], v[238:241], v[4:7]
	s_barrier
	s_add_u32 s6, s6, 0x100
	s_addc_u32 s7, s7, 0
	s_add_u32 s78, s78, 0x100
	s_addc_u32 s79, s79, 0
	s_cmp_ge_u32 s80, s69
	s_mov_b32 s58, s80
	s_cbranch_scc0 .LBB0_476

; #define PG8_STAGE(bufoff, gbase, voff) do { _Pragma("unroll") for (int _i = 0; _i < 2; ++_i) \
;         __builtin_amdgcn_global_load_lds((const unsigned*)((const char*)(gbase) + (voff)[_i]), (PG8_LAS unsigned*)(lds + (bufoff) + ldsw + _i * 8192), 16, 0, 0); } while (0)
; #define PG8_LDA(dst, b, h) do { _Pragma("unroll") for (int m = 0; m < 4; ++m) _Pragma("unroll") for (int k = 0; k < 2; ++k) dst[m][k] = *(const PG8_LAS bf16x8*)(lds + PG8_SA(b, h) + aoff + m * 2048 + k * 1024); } while (0)
; #define PG8_LDB(dst, b, h) do { _Pragma("unroll") for (int n = 0; n < 2; ++n) _Pragma("unroll") for (int k = 0; k < 2; ++k) dst[n][k] = *(const PG8_LAS bf16x8*)(lds + PG8_SB(b, h) + boff + n * 2048 + k * 1024); } while (0)
; #define PG8_WAIT_V(n) asm volatile("s_waitcnt vmcnt(" #n ")" ::: "memory")
; #define PG8_WAIT_L(n) asm volatile("s_waitcnt lgkmcnt(" #n ")" ::: "memory")
; #define PG8_BAR __builtin_amdgcn_s_barrier()
; #define PG8_SCHED __builtin_amdgcn_sched_barrier(0)
; template <class Epi, class Sched, bool ALIGN_EPI = false, bool SP2 = false>
; __device__ __forceinline__ void gemm_phase(PG8_LAS unsigned char* lds, const Gemm g, const Sched& S, const Epi& E, const int tid) {
;     ...
;         const bool has_next = S.next(ui + 1, nxt);
;         const char* nA = has_next ? (const char*)g.A + (size_t)nxt.pm * tstep : cA; const char* nB = has_next ? (const char*)g.Bt + (size_t)nxt.pn * tstep : cB;
;         for (int t = 0; t < nt; t += 2) {
;             const bool last = (t == nt - 2);
;             const char* a1 = cA + (size_t)(t + 1) * kstep;
;             const char* a2 = last ? nA : cA + (size_t)(t + 2) * kstep; const char* b2 = last ? nB : cB + (size_t)(t + 2) * kstep;
;             const char* a3 = a2 + kstep; const char* b3 = b2 + kstep;
;             if (last && has_next) S.a_ready(nxt);
;             if constexpr (SP2) {
;             PG8_LDB(B0, 0, 0); PG8_LDB(B1, 0, 1); PG8_SCHED; PG8_LDA(At, 0, 0); PG8_STAGE(PG8_SA(1, 1), a1 + hstep, voffA);
;             PG8_WAIT_V(8); PG8_WAIT_L(0); PG8_BAR; PG8_MMA(0, 0, At, B0); PG8_MMA(0, 1, At, B1); PG8_BAR; PG8_SCHED;
;             PG8_LDA(At, 0, 1); PG8_STAGE(PG8_SB(0, 0), b2, voffB); PG8_STAGE(PG8_SB(0, 1), b2 + hstep, voffB); PG8_STAGE(PG8_SA(0, 0), a2, voffA);
;             PG8_WAIT_V(8); PG8_WAIT_L(0); PG8_BAR; PG8_MMA(1, 0, At, B0); PG8_MMA(1, 1, At, B1); PG8_BAR; PG8_SCHED;
.LBB0_521:
	s_ashr_i32 s13, s12, 31
	s_lshl_b64 s[14:15], s[12:13], 19
	s_add_u32 s14, s26, s14
	s_addc_u32 s15, s27, s15
	s_and_b64 s[16:17], s[2:3], exec
	s_cselect_b32 s13, s15, s19
	s_cselect_b32 s47, s14, s18
	s_ashr_i32 s11, s10, 31
	s_lshl_b64 s[16:17], s[10:11], 19
	s_add_u32 s16, s34, s16
	s_addc_u32 s17, s36, s17
	s_and_b64 s[22:23], s[2:3], exec
	s_cselect_b32 s11, s17, s21
	s_cselect_b32 s48, s16, s20
	s_add_u32 s18, s18, 0x40080
	s_addc_u32 s19, s19, 0
	s_add_u32 s49, s20, 0x100
	v_mov_b32_e32 v4, 0
	s_addc_u32 s50, s21, 0
	s_mov_b32 s51, -2
	s_add_u32 s20, s18, 0xfffc0080
	s_addc_u32 s21, s19, -1
	s_add_i32 s52, 0, 0x10000
	s_cmp_eq_u32 s51, 12
	s_cselect_b32 s23, s13, s21
	s_cselect_b32 s22, s47, s20
	v_add_u32_e32 v148, s52, v146
	s_cselect_b32 s21, s11, s50
	s_cselect_b32 s20, s48, s49
	s_add_i32 s54, 0, 0x14000
	ds_read_b128 v[142:145], v148
	ds_read_b128 v[166:169], v148 offset:1024
	ds_read_b128 v[170:173], v148 offset:2048
	ds_read_b128 v[174:177], v148 offset:3072
	v_add_u32_e32 v148, s54, v146
	ds_read_b128 v[178:181], v148
	ds_read_b128 v[182:185], v148 offset:1024
	ds_read_b128 v[186:189], v148 offset:2048
	ds_read_b128 v[190:193], v148 offset:3072
	v_lshl_add_u64 v[226:227], s[18:19], 0, v[138:139]
	s_add_i32 m0, s38, 0xc000
	ds_read_b128 v[194:197], v153
	ds_read_b128 v[198:201], v153 offset:1024
	ds_read_b128 v[202:205], v153 offset:2048
	ds_read_b128 v[206:209], v153 offset:3072
	ds_read_b128 v[210:213], v153 offset:4096
	ds_read_b128 v[214:217], v153 offset:5120
	ds_read_b128 v[218:221], v153 offset:6144
	ds_read_b128 v[222:225], v153 offset:7168
	global_load_lds_dwordx4 v[226:227], off
	s_add_i32 m0, s38, 0xe000
	v_lshl_add_u64 v[226:227], s[18:19], 0, v[140:141]
	global_load_lds_dwordx4 v[226:227], off
	s_waitcnt vmcnt(8)
	s_waitcnt lgkmcnt(0)
	s_barrier
	s_waitcnt lgkmcnt(0)
	v_mfma_f32_16x16x32_bf16 v[128:131], v[142:145], v[194:197], 0
	v_mfma_f32_16x16x32_bf16 v[120:123], v[170:173], v[194:197], 0
	v_mfma_f32_16x16x32_bf16 v[112:115], v[142:145], v[202:205], 0
	v_mfma_f32_16x16x32_bf16 v[104:107], v[170:173], v[202:205], 0
	v_mfma_f32_16x16x32_bf16 v[96:99], v[142:145], v[210:213], 0
	v_mfma_f32_16x16x32_bf16 v[88:91], v[170:173], v[210:213], 0
	v_mfma_f32_16x16x32_bf16 v[80:83], v[142:145], v[218:221], 0
	v_mfma_f32_16x16x32_bf16 v[72:75], v[170:173], v[218:221], 0
	v_mfma_f32_16x16x32_bf16 v[128:131], v[166:169], v[198:201], v[128:131]
	v_mfma_f32_16x16x32_bf16 v[120:123], v[174:177], v[198:201], v[120:123]
	v_mfma_f32_16x16x32_bf16 v[112:115], v[166:169], v[206:209], v[112:115]
	v_mfma_f32_16x16x32_bf16 v[104:107], v[174:177], v[206:209], v[104:107]
	v_mfma_f32_16x16x32_bf16 v[96:99], v[166:169], v[214:217], v[96:99]
	v_mfma_f32_16x16x32_bf16 v[88:91], v[174:177], v[214:217], v[88:91]
	v_mfma_f32_16x16x32_bf16 v[80:83], v[166:169], v[222:225], v[80:83]
	v_mfma_f32_16x16x32_bf16 v[72:75], v[174:177], v[222:225], v[72:75]
	v_mfma_f32_16x16x32_bf16 v[124:127], v[178:181], v[194:197], 0
	v_mfma_f32_16x16x32_bf16 v[116:119], v[186:189], v[194:197], 0
	v_mfma_f32_16x16x32_bf16 v[108:111], v[178:181], v[202:205], 0
	v_mfma_f32_16x16x32_bf16 v[100:103], v[186:189], v[202:205], 0
	v_mfma_f32_16x16x32_bf16 v[92:95], v[178:181], v[210:213], 0
	v_mfma_f32_16x16x32_bf16 v[84:87], v[186:189], v[210:213], 0
	v_mfma_f32_16x16x32_bf16 v[76:79], v[178:181], v[218:221], 0
	v_mfma_f32_16x16x32_bf16 v[68:71], v[186:189], v[218:221], 0
	v_mfma_f32_16x16x32_bf16 v[124:127], v[182:185], v[198:201], v[124:127]
	v_mfma_f32_16x16x32_bf16 v[116:119], v[190:193], v[198:201], v[116:119]
	v_mfma_f32_16x16x32_bf16 v[108:111], v[182:185], v[206:209], v[108:111]
	v_mfma_f32_16x16x32_bf16 v[100:103], v[190:193], v[206:209], v[100:103]
	v_mfma_f32_16x16x32_bf16 v[92:95], v[182:185], v[214:217], v[92:95]
	v_mfma_f32_16x16x32_bf16 v[84:87], v[190:193], v[214:217], v[84:87]
	v_mfma_f32_16x16x32_bf16 v[76:79], v[182:185], v[222:225], v[76:79]
	v_mfma_f32_16x16x32_bf16 v[68:71], v[190:193], v[222:225], v[68:71]
	s_barrier
	s_add_i32 s52, s52, s37
	v_lshl_add_u64 v[226:227], s[20:21], 0, v[134:135]
	s_mov_b32 m0, s52
	ds_read_b128 v[194:197], v153 offset:16384
	ds_read_b128 v[198:201], v153 offset:17408
	ds_read_b128 v[202:205], v153 offset:18432
	ds_read_b128 v[206:209], v153 offset:19456
	ds_read_b128 v[210:213], v153 offset:20480
	ds_read_b128 v[214:217], v153 offset:21504
	ds_read_b128 v[218:221], v153 offset:22528
	ds_read_b128 v[222:225], v153 offset:23552
	global_load_lds_dwordx4 v[226:227], off
	s_add_i32 m0, s52, 0x2000
	s_add_u32 s52, s20, 0x40000
	v_lshl_add_u64 v[238:239], s[20:21], 0, v[0:1]
	s_addc_u32 s53, s21, 0
	s_add_i32 s54, s54, s37
	global_load_lds_dwordx4 v[238:239], off
	v_lshl_add_u64 v[240:241], s[52:53], 0, v[134:135]
	s_mov_b32 m0, s54
	v_lshl_add_u64 v[242:243], s[22:23], 0, v[132:133]
	global_load_lds_dwordx4 v[240:241], off
	s_add_i32 m0, s54, 0x2000
	v_lshl_add_u64 v[240:241], s[52:53], 0, v[0:1]
	global_load_lds_dwordx4 v[240:241], off
	s_mov_b32 m0, s38
	v_lshl_add_u64 v[240:241], s[22:23], 0, v[136:137]
	global_load_lds_dwordx4 v[240:241], off
	s_mov_b32 m0, s39
	s_nop 0
	global_load_lds_dwordx4 v[242:243], off
	s_waitcnt vmcnt(8)
	s_waitcnt lgkmcnt(0)
	s_barrier
; #define PG8_STAGE(bufoff, gbase, voff) do { _Pragma("unroll") for (int _i = 0; _i < 2; ++_i) \
;         __builtin_amdgcn_global_load_lds((const unsigned*)((const char*)(gbase) + (voff)[_i]), (PG8_LAS unsigned*)(lds + (bufoff) + ldsw + _i * 8192), 16, 0, 0); } while (0)
; #define PG8_LDA(dst, b, h) do { _Pragma("unroll") for (int m = 0; m < 4; ++m) _Pragma("unroll") for (int k = 0; k < 2; ++k) dst[m][k] = *(const PG8_LAS bf16x8*)(lds + PG8_SA(b, h) + aoff + m * 2048 + k * 1024); } while (0)
; #define PG8_LDB(dst, b, h) do { _Pragma("unroll") for (int n = 0; n < 2; ++n) _Pragma("unroll") for (int k = 0; k < 2; ++k) dst[n][k] = *(const PG8_LAS bf16x8*)(lds + PG8_SB(b, h) + boff + n * 2048 + k * 1024); } while (0)
; #define PG8_MMA(ai, bj, At, Bt) do { __builtin_amdgcn_s_setprio(1); _Pragma("unroll") for (int m = 0; m < 4; ++m) _Pragma("unroll") for (int n = 0; n < 2; ++n) _Pragma("unroll") for (int k = 0; k < 2; ++k) \
;         acc[ai][bj][m][n] = __builtin_amdgcn_mfma_f32_16x16x32_bf16(Bt[n][k], At[m][k], acc[ai][bj][m][n], 0, 0, 0); __builtin_amdgcn_s_setprio(0); } while (0)
; #define PG8_WAIT_V(n) asm volatile("s_waitcnt vmcnt(" #n ")" ::: "memory")
; #define PG8_WAIT_L(n) asm volatile("s_waitcnt lgkmcnt(" #n ")" ::: "memory")
; #define PG8_BAR __builtin_amdgcn_s_barrier()
; #define PG8_SCHED __builtin_amdgcn_sched_barrier(0)
; template <class Epi, class Sched, bool ALIGN_EPI = false, bool SP2 = false>
; __device__ __forceinline__ void gemm_phase(PG8_LAS unsigned char* lds, const Gemm g, const Sched& S, const Epi& E, const int tid) {
;     ...
;             PG8_WAIT_V(8); PG8_WAIT_L(0); PG8_BAR; PG8_MMA(1, 0, At, B0); PG8_MMA(1, 1, At, B1); PG8_BAR; PG8_SCHED;
;             PG8_LDB(B0, 1, 0); PG8_LDB(B1, 1, 1); PG8_SCHED; PG8_LDA(At, 1, 0); PG8_STAGE(PG8_SA(0, 1), a2 + hstep, voffA);
;             PG8_WAIT_V(8); PG8_WAIT_L(0); PG8_BAR; PG8_MMA(0, 0, At, B0); PG8_MMA(0, 1, At, B1); PG8_BAR; PG8_SCHED;
	s_waitcnt lgkmcnt(0)
	v_mfma_f32_16x16x32_bf16 v[64:67], v[142:145], v[194:197], 0
	v_mfma_f32_16x16x32_bf16 v[56:59], v[170:173], v[194:197], 0
	v_mfma_f32_16x16x32_bf16 v[48:51], v[142:145], v[202:205], 0
	v_mfma_f32_16x16x32_bf16 v[40:43], v[170:173], v[202:205], 0
	v_mfma_f32_16x16x32_bf16 v[32:35], v[142:145], v[210:213], 0
	v_mfma_f32_16x16x32_bf16 v[24:27], v[170:173], v[210:213], 0
	v_mfma_f32_16x16x32_bf16 v[16:19], v[142:145], v[218:221], 0
	v_mfma_f32_16x16x32_bf16 v[8:11], v[170:173], v[218:221], 0
	v_mfma_f32_16x16x32_bf16 v[64:67], v[166:169], v[198:201], v[64:67]
	v_mfma_f32_16x16x32_bf16 v[56:59], v[174:177], v[198:201], v[56:59]
	v_mfma_f32_16x16x32_bf16 v[48:51], v[166:169], v[206:209], v[48:51]
	v_mfma_f32_16x16x32_bf16 v[40:43], v[174:177], v[206:209], v[40:43]
	v_mfma_f32_16x16x32_bf16 v[32:35], v[166:169], v[214:217], v[32:35]
	v_mfma_f32_16x16x32_bf16 v[24:27], v[174:177], v[214:217], v[24:27]
	v_mfma_f32_16x16x32_bf16 v[16:19], v[166:169], v[222:225], v[16:19]
	v_mfma_f32_16x16x32_bf16 v[8:11], v[174:177], v[222:225], v[8:11]
	v_mfma_f32_16x16x32_bf16 v[60:63], v[178:181], v[194:197], 0
	v_mfma_f32_16x16x32_bf16 v[52:55], v[186:189], v[194:197], 0
	v_mfma_f32_16x16x32_bf16 v[44:47], v[178:181], v[202:205], 0
	v_mfma_f32_16x16x32_bf16 v[36:39], v[186:189], v[202:205], 0
	v_mfma_f32_16x16x32_bf16 v[28:31], v[178:181], v[210:213], 0
	v_mfma_f32_16x16x32_bf16 v[20:23], v[186:189], v[210:213], 0
	v_mfma_f32_16x16x32_bf16 v[12:15], v[178:181], v[218:221], 0
	v_mfma_f32_16x16x32_bf16 v[4:7], v[186:189], v[218:221], 0
	v_mfma_f32_16x16x32_bf16 v[60:63], v[182:185], v[198:201], v[60:63]
	v_mfma_f32_16x16x32_bf16 v[52:55], v[190:193], v[198:201], v[52:55]
	v_mfma_f32_16x16x32_bf16 v[44:47], v[182:185], v[206:209], v[44:47]
	v_mfma_f32_16x16x32_bf16 v[36:39], v[190:193], v[206:209], v[36:39]
	v_mfma_f32_16x16x32_bf16 v[28:31], v[182:185], v[214:217], v[28:31]
	v_mfma_f32_16x16x32_bf16 v[20:23], v[190:193], v[214:217], v[20:23]
	v_mfma_f32_16x16x32_bf16 v[12:15], v[182:185], v[222:225], v[12:15]
	v_mfma_f32_16x16x32_bf16 v[4:7], v[190:193], v[222:225], v[4:7]
	s_barrier
	s_add_i32 s52, 0, 0x18000
	v_add_u32_e32 v148, s52, v146
	s_add_i32 s53, 0, 0x1c000
	ds_read_b128 v[142:145], v148
	ds_read_b128 v[166:169], v148 offset:1024
	ds_read_b128 v[170:173], v148 offset:2048
	ds_read_b128 v[174:177], v148 offset:3072
	v_add_u32_e32 v148, s53, v146
	ds_read_b128 v[178:181], v148
	ds_read_b128 v[182:185], v148 offset:1024
	ds_read_b128 v[186:189], v148 offset:2048
	ds_read_b128 v[190:193], v148 offset:3072
	s_add_u32 s22, s22, 0x40000
	s_addc_u32 s23, s23, 0
	s_mov_b32 m0, s40
	v_lshl_add_u64 v[244:245], s[22:23], 0, v[136:137]
	ds_read_b128 v[194:197], v153 offset:32768
	ds_read_b128 v[198:201], v153 offset:33792
	ds_read_b128 v[202:205], v153 offset:34816
	ds_read_b128 v[206:209], v153 offset:35840
	ds_read_b128 v[210:213], v153 offset:36864
	ds_read_b128 v[214:217], v153 offset:37888
	ds_read_b128 v[218:221], v153 offset:38912
	ds_read_b128 v[222:225], v153 offset:39936
	global_load_lds_dwordx4 v[244:245], off
	s_mov_b32 m0, s41
	v_lshl_add_u64 v[244:245], s[22:23], 0, v[132:133]
	global_load_lds_dwordx4 v[244:245], off
	s_waitcnt vmcnt(8)
	s_waitcnt lgkmcnt(0)
	s_barrier
	s_waitcnt lgkmcnt(0)
	v_mfma_f32_16x16x32_bf16 v[128:131], v[142:145], v[194:197], v[128:131]
	v_mfma_f32_16x16x32_bf16 v[120:123], v[170:173], v[194:197], v[120:123]
	v_mfma_f32_16x16x32_bf16 v[112:115], v[142:145], v[202:205], v[112:115]
	v_mfma_f32_16x16x32_bf16 v[104:107], v[170:173], v[202:205], v[104:107]
	v_mfma_f32_16x16x32_bf16 v[96:99], v[142:145], v[210:213], v[96:99]
	v_mfma_f32_16x16x32_bf16 v[88:91], v[170:173], v[210:213], v[88:91]
	v_mfma_f32_16x16x32_bf16 v[80:83], v[142:145], v[218:221], v[80:83]
	v_mfma_f32_16x16x32_bf16 v[72:75], v[170:173], v[218:221], v[72:75]
	v_mfma_f32_16x16x32_bf16 v[128:131], v[166:169], v[198:201], v[128:131]
	v_mfma_f32_16x16x32_bf16 v[120:123], v[174:177], v[198:201], v[120:123]
	v_mfma_f32_16x16x32_bf16 v[112:115], v[166:169], v[206:209], v[112:115]
	v_mfma_f32_16x16x32_bf16 v[104:107], v[174:177], v[206:209], v[104:107]
	v_mfma_f32_16x16x32_bf16 v[96:99], v[166:169], v[214:217], v[96:99]
	v_mfma_f32_16x16x32_bf16 v[88:91], v[174:177], v[214:217], v[88:91]
	v_mfma_f32_16x16x32_bf16 v[80:83], v[166:169], v[222:225], v[80:83]
	v_mfma_f32_16x16x32_bf16 v[72:75], v[174:177], v[222:225], v[72:75]
	v_mfma_f32_16x16x32_bf16 v[124:127], v[178:181], v[194:197], v[124:127]
	v_mfma_f32_16x16x32_bf16 v[116:119], v[186:189], v[194:197], v[116:119]
	v_mfma_f32_16x16x32_bf16 v[108:111], v[178:181], v[202:205], v[108:111]
	v_mfma_f32_16x16x32_bf16 v[100:103], v[186:189], v[202:205], v[100:103]
	v_mfma_f32_16x16x32_bf16 v[92:95], v[178:181], v[210:213], v[92:95]
	v_mfma_f32_16x16x32_bf16 v[84:87], v[186:189], v[210:213], v[84:87]
	v_mfma_f32_16x16x32_bf16 v[76:79], v[178:181], v[218:221], v[76:79]
	v_mfma_f32_16x16x32_bf16 v[68:71], v[186:189], v[218:221], v[68:71]
	v_mfma_f32_16x16x32_bf16 v[124:127], v[182:185], v[198:201], v[124:127]
	v_mfma_f32_16x16x32_bf16 v[116:119], v[190:193], v[198:201], v[116:119]
	v_mfma_f32_16x16x32_bf16 v[108:111], v[182:185], v[206:209], v[108:111]
	v_mfma_f32_16x16x32_bf16 v[100:103], v[190:193], v[206:209], v[100:103]
	v_mfma_f32_16x16x32_bf16 v[92:95], v[182:185], v[214:217], v[92:95]
	v_mfma_f32_16x16x32_bf16 v[84:87], v[190:193], v[214:217], v[84:87]
	v_mfma_f32_16x16x32_bf16 v[76:79], v[182:185], v[222:225], v[76:79]
	v_mfma_f32_16x16x32_bf16 v[68:71], v[190:193], v[222:225], v[68:71]
	s_barrier
; #define PG8_STAGE(bufoff, gbase, voff) do { _Pragma("unroll") for (int _i = 0; _i < 2; ++_i) \
;         __builtin_amdgcn_global_load_lds((const unsigned*)((const char*)(gbase) + (voff)[_i]), (PG8_LAS unsigned*)(lds + (bufoff) + ldsw + _i * 8192), 16, 0, 0); } while (0)
; #define PG8_LDA(dst, b, h) do { _Pragma("unroll") for (int m = 0; m < 4; ++m) _Pragma("unroll") for (int k = 0; k < 2; ++k) dst[m][k] = *(const PG8_LAS bf16x8*)(lds + PG8_SA(b, h) + aoff + m * 2048 + k * 1024); } while (0)
; #define PG8_WAIT_V(n) asm volatile("s_waitcnt vmcnt(" #n ")" ::: "memory")
; #define PG8_WAIT_L(n) asm volatile("s_waitcnt lgkmcnt(" #n ")" ::: "memory")
; #define PG8_BAR __builtin_amdgcn_s_barrier()
; template <class Epi, class Sched, bool ALIGN_EPI = false, bool SP2 = false>
; __device__ __forceinline__ void gemm_phase(PG8_LAS unsigned char* lds, const Gemm g, const Sched& S, const Epi& E, const int tid) {
;     ...
;         for (int t = 0; t < nt; t += 2) {
;             const bool last = (t == nt - 2);
;             const char* a1 = cA + (size_t)(t + 1) * kstep;
;             const char* a2 = last ? nA : cA + (size_t)(t + 2) * kstep; const char* b2 = last ? nB : cB + (size_t)(t + 2) * kstep;
;             const char* a3 = a2 + kstep; const char* b3 = b2 + kstep;
;             if (last && has_next) S.a_ready(nxt);
;             if constexpr (SP2) {
;             PG8_LDB(B0, 0, 0); PG8_LDB(B1, 0, 1); PG8_SCHED; PG8_LDA(At, 0, 0); PG8_STAGE(PG8_SA(1, 1), a1 + hstep, voffA);
;             PG8_WAIT_V(8); PG8_WAIT_L(0); PG8_BAR; PG8_MMA(0, 0, At, B0); PG8_MMA(0, 1, At, B1); PG8_BAR; PG8_SCHED;
;             PG8_LDA(At, 0, 1); PG8_STAGE(PG8_SB(0, 0), b2, voffB); PG8_STAGE(PG8_SB(0, 1), b2 + hstep, voffB); PG8_STAGE(PG8_SA(0, 0), a2, voffA);
;             PG8_WAIT_V(8); PG8_WAIT_L(0); PG8_BAR; PG8_MMA(1, 0, At, B0); PG8_MMA(1, 1, At, B1); PG8_BAR; PG8_SCHED;
;             PG8_LDB(B0, 1, 0); PG8_LDB(B1, 1, 1); PG8_SCHED; PG8_LDA(At, 1, 0); PG8_STAGE(PG8_SA(0, 1), a2 + hstep, voffA);
;             PG8_WAIT_V(8); PG8_WAIT_L(0); PG8_BAR; PG8_MMA(0, 0, At, B0); PG8_MMA(0, 1, At, B1); PG8_BAR; PG8_SCHED;
;             PG8_LDA(At, 1, 1); PG8_STAGE(PG8_SB(1, 0), b3, voffB); PG8_STAGE(PG8_SB(1, 1), b3 + hstep, voffB); PG8_STAGE(PG8_SA(1, 0), a3, voffA);
;             PG8_WAIT_V(8); PG8_WAIT_L(0); PG8_BAR; PG8_MMA(1, 0, At, B0); PG8_MMA(1, 1, At, B1); PG8_BAR; PG8_SCHED;
	s_add_i32 s22, s52, s37
	v_lshl_add_u64 v[226:227], v[226:227], 0, s[0:1]
	s_mov_b32 m0, s22
	ds_read_b128 v[194:197], v153 offset:49152
	ds_read_b128 v[198:201], v153 offset:50176
	ds_read_b128 v[202:205], v153 offset:51200
	ds_read_b128 v[206:209], v153 offset:52224
	ds_read_b128 v[210:213], v153 offset:53248
	ds_read_b128 v[214:217], v153 offset:54272
	ds_read_b128 v[218:221], v153 offset:55296
	ds_read_b128 v[222:225], v153 offset:56320
	global_load_lds_dwordx4 v[226:227], off
	s_add_i32 m0, s22, 0x2000
	s_add_u32 s20, s20, 0x40080
	v_lshl_add_u64 v[226:227], v[238:239], 0, s[0:1]
	s_addc_u32 s21, s21, 0
	s_add_i32 s22, s53, s37
	global_load_lds_dwordx4 v[226:227], off
	s_mov_b32 m0, s22
	v_lshl_add_u64 v[226:227], s[20:21], 0, v[134:135]
	global_load_lds_dwordx4 v[226:227], off
	s_add_i32 m0, s22, 0x2000
	v_lshl_add_u64 v[226:227], s[20:21], 0, v[0:1]
	global_load_lds_dwordx4 v[226:227], off
	s_mov_b32 m0, s42
	v_lshl_add_u64 v[226:227], v[240:241], 0, s[0:1]
	global_load_lds_dwordx4 v[226:227], off
	s_mov_b32 m0, s43
	v_lshl_add_u64 v[226:227], v[242:243], 0, s[0:1]
	global_load_lds_dwordx4 v[226:227], off
	s_waitcnt vmcnt(8)
	s_waitcnt lgkmcnt(0)
	s_barrier
	s_waitcnt lgkmcnt(0)
	v_mfma_f32_16x16x32_bf16 v[64:67], v[142:145], v[194:197], v[64:67]
	v_mfma_f32_16x16x32_bf16 v[56:59], v[170:173], v[194:197], v[56:59]
	v_mfma_f32_16x16x32_bf16 v[48:51], v[142:145], v[202:205], v[48:51]
	v_mfma_f32_16x16x32_bf16 v[40:43], v[170:173], v[202:205], v[40:43]
	v_mfma_f32_16x16x32_bf16 v[32:35], v[142:145], v[210:213], v[32:35]
	v_mfma_f32_16x16x32_bf16 v[24:27], v[170:173], v[210:213], v[24:27]
	v_mfma_f32_16x16x32_bf16 v[16:19], v[142:145], v[218:221], v[16:19]
	v_mfma_f32_16x16x32_bf16 v[8:11], v[170:173], v[218:221], v[8:11]
	v_mfma_f32_16x16x32_bf16 v[64:67], v[166:169], v[198:201], v[64:67]
	v_mfma_f32_16x16x32_bf16 v[56:59], v[174:177], v[198:201], v[56:59]
	v_mfma_f32_16x16x32_bf16 v[48:51], v[166:169], v[206:209], v[48:51]
	v_mfma_f32_16x16x32_bf16 v[40:43], v[174:177], v[206:209], v[40:43]
	v_mfma_f32_16x16x32_bf16 v[32:35], v[166:169], v[214:217], v[32:35]
	v_mfma_f32_16x16x32_bf16 v[24:27], v[174:177], v[214:217], v[24:27]
	v_mfma_f32_16x16x32_bf16 v[16:19], v[166:169], v[222:225], v[16:19]
	v_mfma_f32_16x16x32_bf16 v[8:11], v[174:177], v[222:225], v[8:11]
	v_mfma_f32_16x16x32_bf16 v[60:63], v[178:181], v[194:197], v[60:63]
	v_mfma_f32_16x16x32_bf16 v[52:55], v[186:189], v[194:197], v[52:55]
	v_mfma_f32_16x16x32_bf16 v[44:47], v[178:181], v[202:205], v[44:47]
	v_mfma_f32_16x16x32_bf16 v[36:39], v[186:189], v[202:205], v[36:39]
	v_mfma_f32_16x16x32_bf16 v[28:31], v[178:181], v[210:213], v[28:31]
	v_mfma_f32_16x16x32_bf16 v[20:23], v[186:189], v[210:213], v[20:23]
	v_mfma_f32_16x16x32_bf16 v[12:15], v[178:181], v[218:221], v[12:15]
	v_mfma_f32_16x16x32_bf16 v[4:7], v[186:189], v[218:221], v[4:7]
	v_mfma_f32_16x16x32_bf16 v[60:63], v[182:185], v[198:201], v[60:63]
	v_mfma_f32_16x16x32_bf16 v[52:55], v[190:193], v[198:201], v[52:55]
	v_mfma_f32_16x16x32_bf16 v[44:47], v[182:185], v[206:209], v[44:47]
	v_mfma_f32_16x16x32_bf16 v[36:39], v[190:193], v[206:209], v[36:39]
	v_mfma_f32_16x16x32_bf16 v[28:31], v[182:185], v[214:217], v[28:31]
	v_mfma_f32_16x16x32_bf16 v[20:23], v[190:193], v[214:217], v[20:23]
	v_mfma_f32_16x16x32_bf16 v[12:15], v[182:185], v[222:225], v[12:15]
	v_mfma_f32_16x16x32_bf16 v[4:7], v[190:193], v[222:225], v[4:7]
	s_barrier
	s_add_i32 s51, s51, 2
	s_add_u32 s18, s18, 0x100
	s_addc_u32 s19, s19, 0
	s_add_u32 s49, s49, 0x100
	s_addc_u32 s50, s50, 0
	s_cmp_gt_u32 s51, 13
	s_cbranch_scc0 .LBB0_522
	s_branch .Lpeel_exit3
.LBB0_522:
	s_add_u32 s20, s18, 0xfffc0080
	s_addc_u32 s21, s19, -1
	s_add_i32 s52, 0, 0x10000
	s_cmp_eq_u32 s51, 12
	s_cselect_b32 s23, s13, s21
	s_cselect_b32 s22, s47, s20
	v_add_u32_e32 v148, s52, v146
	s_cselect_b32 s21, s11, s50
	s_cselect_b32 s20, s48, s49
	s_add_i32 s54, 0, 0x14000
	ds_read_b128 v[142:145], v148
	ds_read_b128 v[166:169], v148 offset:1024
	ds_read_b128 v[170:173], v148 offset:2048
	ds_read_b128 v[174:177], v148 offset:3072
	v_add_u32_e32 v148, s54, v146
	ds_read_b128 v[178:181], v148
	ds_read_b128 v[182:185], v148 offset:1024
	ds_read_b128 v[186:189], v148 offset:2048
	ds_read_b128 v[190:193], v148 offset:3072
	v_lshl_add_u64 v[226:227], s[18:19], 0, v[138:139]
	s_add_i32 m0, s38, 0xc000
	ds_read_b128 v[194:197], v153
	ds_read_b128 v[198:201], v153 offset:1024
	ds_read_b128 v[202:205], v153 offset:2048
	ds_read_b128 v[206:209], v153 offset:3072
	ds_read_b128 v[210:213], v153 offset:4096
	ds_read_b128 v[214:217], v153 offset:5120
	ds_read_b128 v[218:221], v153 offset:6144
	ds_read_b128 v[222:225], v153 offset:7168
	global_load_lds_dwordx4 v[226:227], off
	s_add_i32 m0, s38, 0xe000
	v_lshl_add_u64 v[226:227], s[18:19], 0, v[140:141]
	global_load_lds_dwordx4 v[226:227], off
	s_waitcnt vmcnt(8)
	s_waitcnt lgkmcnt(0)
	s_barrier
; #define PG8_STAGE(bufoff, gbase, voff) do { _Pragma("unroll") for (int _i = 0; _i < 2; ++_i) \
;         __builtin_amdgcn_global_load_lds((const unsigned*)((const char*)(gbase) + (voff)[_i]), (PG8_LAS unsigned*)(lds + (bufoff) + ldsw + _i * 8192), 16, 0, 0); } while (0)
; #define PG8_LDA(dst, b, h) do { _Pragma("unroll") for (int m = 0; m < 4; ++m) _Pragma("unroll") for (int k = 0; k < 2; ++k) dst[m][k] = *(const PG8_LAS bf16x8*)(lds + PG8_SA(b, h) + aoff + m * 2048 + k * 1024); } while (0)
; #define PG8_LDB(dst, b, h) do { _Pragma("unroll") for (int n = 0; n < 2; ++n) _Pragma("unroll") for (int k = 0; k < 2; ++k) dst[n][k] = *(const PG8_LAS bf16x8*)(lds + PG8_SB(b, h) + boff + n * 2048 + k * 1024); } while (0)
; #define PG8_MMA(ai, bj, At, Bt) do { __builtin_amdgcn_s_setprio(1); _Pragma("unroll") for (int m = 0; m < 4; ++m) _Pragma("unroll") for (int n = 0; n < 2; ++n) _Pragma("unroll") for (int k = 0; k < 2; ++k) \
;         acc[ai][bj][m][n] = __builtin_amdgcn_mfma_f32_16x16x32_bf16(Bt[n][k], At[m][k], acc[ai][bj][m][n], 0, 0, 0); __builtin_amdgcn_s_setprio(0); } while (0)
; #define PG8_WAIT_V(n) asm volatile("s_waitcnt vmcnt(" #n ")" ::: "memory")
; #define PG8_WAIT_L(n) asm volatile("s_waitcnt lgkmcnt(" #n ")" ::: "memory")
; #define PG8_BAR __builtin_amdgcn_s_barrier()
; #define PG8_SCHED __builtin_amdgcn_sched_barrier(0)
; template <class Epi, class Sched, bool ALIGN_EPI = false, bool SP2 = false>
; __device__ __forceinline__ void gemm_phase(PG8_LAS unsigned char* lds, const Gemm g, const Sched& S, const Epi& E, const int tid) {
;     ...
;             PG8_LDB(B0, 0, 0); PG8_LDB(B1, 0, 1); PG8_SCHED; PG8_LDA(At, 0, 0); PG8_STAGE(PG8_SA(1, 1), a1 + hstep, voffA);
;             PG8_WAIT_V(8); PG8_WAIT_L(0); PG8_BAR; PG8_MMA(0, 0, At, B0); PG8_MMA(0, 1, At, B1); PG8_BAR; PG8_SCHED;
;             PG8_LDA(At, 0, 1); PG8_STAGE(PG8_SB(0, 0), b2, voffB); PG8_STAGE(PG8_SB(0, 1), b2 + hstep, voffB); PG8_STAGE(PG8_SA(0, 0), a2, voffA);
;             PG8_WAIT_V(8); PG8_WAIT_L(0); PG8_BAR; PG8_MMA(1, 0, At, B0); PG8_MMA(1, 1, At, B1); PG8_BAR; PG8_SCHED;
	s_waitcnt lgkmcnt(0)
	v_mfma_f32_16x16x32_bf16 v[128:131], v[142:145], v[194:197], v[128:131]
	v_mfma_f32_16x16x32_bf16 v[120:123], v[170:173], v[194:197], v[120:123]
	v_mfma_f32_16x16x32_bf16 v[112:115], v[142:145], v[202:205], v[112:115]
	v_mfma_f32_16x16x32_bf16 v[104:107], v[170:173], v[202:205], v[104:107]
	v_mfma_f32_16x16x32_bf16 v[96:99], v[142:145], v[210:213], v[96:99]
	v_mfma_f32_16x16x32_bf16 v[88:91], v[170:173], v[210:213], v[88:91]
	v_mfma_f32_16x16x32_bf16 v[80:83], v[142:145], v[218:221], v[80:83]
	v_mfma_f32_16x16x32_bf16 v[72:75], v[170:173], v[218:221], v[72:75]
	v_mfma_f32_16x16x32_bf16 v[128:131], v[166:169], v[198:201], v[128:131]
	v_mfma_f32_16x16x32_bf16 v[120:123], v[174:177], v[198:201], v[120:123]
	v_mfma_f32_16x16x32_bf16 v[112:115], v[166:169], v[206:209], v[112:115]
	v_mfma_f32_16x16x32_bf16 v[104:107], v[174:177], v[206:209], v[104:107]
	v_mfma_f32_16x16x32_bf16 v[96:99], v[166:169], v[214:217], v[96:99]
	v_mfma_f32_16x16x32_bf16 v[88:91], v[174:177], v[214:217], v[88:91]
	v_mfma_f32_16x16x32_bf16 v[80:83], v[166:169], v[222:225], v[80:83]
	v_mfma_f32_16x16x32_bf16 v[72:75], v[174:177], v[222:225], v[72:75]
	v_mfma_f32_16x16x32_bf16 v[124:127], v[178:181], v[194:197], v[124:127]
	v_mfma_f32_16x16x32_bf16 v[116:119], v[186:189], v[194:197], v[116:119]
	v_mfma_f32_16x16x32_bf16 v[108:111], v[178:181], v[202:205], v[108:111]
	v_mfma_f32_16x16x32_bf16 v[100:103], v[186:189], v[202:205], v[100:103]
	v_mfma_f32_16x16x32_bf16 v[92:95], v[178:181], v[210:213], v[92:95]
	v_mfma_f32_16x16x32_bf16 v[84:87], v[186:189], v[210:213], v[84:87]
	v_mfma_f32_16x16x32_bf16 v[76:79], v[178:181], v[218:221], v[76:79]
	v_mfma_f32_16x16x32_bf16 v[68:71], v[186:189], v[218:221], v[68:71]
	v_mfma_f32_16x16x32_bf16 v[124:127], v[182:185], v[198:201], v[124:127]
	v_mfma_f32_16x16x32_bf16 v[116:119], v[190:193], v[198:201], v[116:119]
	v_mfma_f32_16x16x32_bf16 v[108:111], v[182:185], v[206:209], v[108:111]
	v_mfma_f32_16x16x32_bf16 v[100:103], v[190:193], v[206:209], v[100:103]
	v_mfma_f32_16x16x32_bf16 v[92:95], v[182:185], v[214:217], v[92:95]
	v_mfma_f32_16x16x32_bf16 v[84:87], v[190:193], v[214:217], v[84:87]
	v_mfma_f32_16x16x32_bf16 v[76:79], v[182:185], v[222:225], v[76:79]
	v_mfma_f32_16x16x32_bf16 v[68:71], v[190:193], v[222:225], v[68:71]
	s_barrier
	s_add_i32 s52, s52, s37
	v_lshl_add_u64 v[226:227], s[20:21], 0, v[134:135]
	s_mov_b32 m0, s52
	ds_read_b128 v[194:197], v153 offset:16384
	ds_read_b128 v[198:201], v153 offset:17408
	ds_read_b128 v[202:205], v153 offset:18432
	ds_read_b128 v[206:209], v153 offset:19456
	ds_read_b128 v[210:213], v153 offset:20480
	ds_read_b128 v[214:217], v153 offset:21504
	ds_read_b128 v[218:221], v153 offset:22528
	ds_read_b128 v[222:225], v153 offset:23552
	global_load_lds_dwordx4 v[226:227], off
	s_add_i32 m0, s52, 0x2000
	s_add_u32 s52, s20, 0x40000
	v_lshl_add_u64 v[238:239], s[20:21], 0, v[0:1]
	s_addc_u32 s53, s21, 0
	s_add_i32 s54, s54, s37
	global_load_lds_dwordx4 v[238:239], off
	v_lshl_add_u64 v[240:241], s[52:53], 0, v[134:135]
	s_mov_b32 m0, s54
	v_lshl_add_u64 v[242:243], s[22:23], 0, v[132:133]
	global_load_lds_dwordx4 v[240:241], off
	s_add_i32 m0, s54, 0x2000
	v_lshl_add_u64 v[240:241], s[52:53], 0, v[0:1]
	global_load_lds_dwordx4 v[240:241], off
	s_mov_b32 m0, s38
	v_lshl_add_u64 v[240:241], s[22:23], 0, v[136:137]
	global_load_lds_dwordx4 v[240:241], off
	s_mov_b32 m0, s39
	s_nop 0
	global_load_lds_dwordx4 v[242:243], off
	s_waitcnt vmcnt(8)
	s_waitcnt lgkmcnt(0)
	s_barrier
	s_waitcnt lgkmcnt(0)
	v_mfma_f32_16x16x32_bf16 v[64:67], v[142:145], v[194:197], v[64:67]
	v_mfma_f32_16x16x32_bf16 v[56:59], v[170:173], v[194:197], v[56:59]
	v_mfma_f32_16x16x32_bf16 v[48:51], v[142:145], v[202:205], v[48:51]
	v_mfma_f32_16x16x32_bf16 v[40:43], v[170:173], v[202:205], v[40:43]
	v_mfma_f32_16x16x32_bf16 v[32:35], v[142:145], v[210:213], v[32:35]
	v_mfma_f32_16x16x32_bf16 v[24:27], v[170:173], v[210:213], v[24:27]
	v_mfma_f32_16x16x32_bf16 v[16:19], v[142:145], v[218:221], v[16:19]
	v_mfma_f32_16x16x32_bf16 v[8:11], v[170:173], v[218:221], v[8:11]
	v_mfma_f32_16x16x32_bf16 v[64:67], v[166:169], v[198:201], v[64:67]
	v_mfma_f32_16x16x32_bf16 v[56:59], v[174:177], v[198:201], v[56:59]
	v_mfma_f32_16x16x32_bf16 v[48:51], v[166:169], v[206:209], v[48:51]
	v_mfma_f32_16x16x32_bf16 v[40:43], v[174:177], v[206:209], v[40:43]
	v_mfma_f32_16x16x32_bf16 v[32:35], v[166:169], v[214:217], v[32:35]
	v_mfma_f32_16x16x32_bf16 v[24:27], v[174:177], v[214:217], v[24:27]
	v_mfma_f32_16x16x32_bf16 v[16:19], v[166:169], v[222:225], v[16:19]
	v_mfma_f32_16x16x32_bf16 v[8:11], v[174:177], v[222:225], v[8:11]
	v_mfma_f32_16x16x32_bf16 v[60:63], v[178:181], v[194:197], v[60:63]
	v_mfma_f32_16x16x32_bf16 v[52:55], v[186:189], v[194:197], v[52:55]
	v_mfma_f32_16x16x32_bf16 v[44:47], v[178:181], v[202:205], v[44:47]
	v_mfma_f32_16x16x32_bf16 v[36:39], v[186:189], v[202:205], v[36:39]
	v_mfma_f32_16x16x32_bf16 v[28:31], v[178:181], v[210:213], v[28:31]
	v_mfma_f32_16x16x32_bf16 v[20:23], v[186:189], v[210:213], v[20:23]
	v_mfma_f32_16x16x32_bf16 v[12:15], v[178:181], v[218:221], v[12:15]
	v_mfma_f32_16x16x32_bf16 v[4:7], v[186:189], v[218:221], v[4:7]
	v_mfma_f32_16x16x32_bf16 v[60:63], v[182:185], v[198:201], v[60:63]
	v_mfma_f32_16x16x32_bf16 v[52:55], v[190:193], v[198:201], v[52:55]
	v_mfma_f32_16x16x32_bf16 v[44:47], v[182:185], v[206:209], v[44:47]
	v_mfma_f32_16x16x32_bf16 v[36:39], v[190:193], v[206:209], v[36:39]
	v_mfma_f32_16x16x32_bf16 v[28:31], v[182:185], v[214:217], v[28:31]
	v_mfma_f32_16x16x32_bf16 v[20:23], v[190:193], v[214:217], v[20:23]
	v_mfma_f32_16x16x32_bf16 v[12:15], v[182:185], v[222:225], v[12:15]
	v_mfma_f32_16x16x32_bf16 v[4:7], v[190:193], v[222:225], v[4:7]
	s_barrier
; #define PG8_STAGE(bufoff, gbase, voff) do { _Pragma("unroll") for (int _i = 0; _i < 2; ++_i) \
;         __builtin_amdgcn_global_load_lds((const unsigned*)((const char*)(gbase) + (voff)[_i]), (PG8_LAS unsigned*)(lds + (bufoff) + ldsw + _i * 8192), 16, 0, 0); } while (0)
; #define PG8_LDA(dst, b, h) do { _Pragma("unroll") for (int m = 0; m < 4; ++m) _Pragma("unroll") for (int k = 0; k < 2; ++k) dst[m][k] = *(const PG8_LAS bf16x8*)(lds + PG8_SA(b, h) + aoff + m * 2048 + k * 1024); } while (0)
; #define PG8_LDB(dst, b, h) do { _Pragma("unroll") for (int n = 0; n < 2; ++n) _Pragma("unroll") for (int k = 0; k < 2; ++k) dst[n][k] = *(const PG8_LAS bf16x8*)(lds + PG8_SB(b, h) + boff + n * 2048 + k * 1024); } while (0)
; #define PG8_MMA(ai, bj, At, Bt) do { __builtin_amdgcn_s_setprio(1); _Pragma("unroll") for (int m = 0; m < 4; ++m) _Pragma("unroll") for (int n = 0; n < 2; ++n) _Pragma("unroll") for (int k = 0; k < 2; ++k) \
;         acc[ai][bj][m][n] = __builtin_amdgcn_mfma_f32_16x16x32_bf16(Bt[n][k], At[m][k], acc[ai][bj][m][n], 0, 0, 0); __builtin_amdgcn_s_setprio(0); } while (0)
; #define PG8_WAIT_V(n) asm volatile("s_waitcnt vmcnt(" #n ")" ::: "memory")
; #define PG8_WAIT_L(n) asm volatile("s_waitcnt lgkmcnt(" #n ")" ::: "memory")
; #define PG8_BAR __builtin_amdgcn_s_barrier()
; #define PG8_SCHED __builtin_amdgcn_sched_barrier(0)
; template <class Epi, class Sched, bool ALIGN_EPI = false, bool SP2 = false>
; __device__ __forceinline__ void gemm_phase(PG8_LAS unsigned char* lds, const Gemm g, const Sched& S, const Epi& E, const int tid) {
;     ...
;             PG8_LDB(B0, 1, 0); PG8_LDB(B1, 1, 1); PG8_SCHED; PG8_LDA(At, 1, 0); PG8_STAGE(PG8_SA(0, 1), a2 + hstep, voffA);
;             PG8_WAIT_V(8); PG8_WAIT_L(0); PG8_BAR; PG8_MMA(0, 0, At, B0); PG8_MMA(0, 1, At, B1); PG8_BAR; PG8_SCHED;
;             PG8_LDA(At, 1, 1); PG8_STAGE(PG8_SB(1, 0), b3, voffB); PG8_STAGE(PG8_SB(1, 1), b3 + hstep, voffB); PG8_STAGE(PG8_SA(1, 0), a3, voffA);
;             PG8_WAIT_V(8); PG8_WAIT_L(0); PG8_BAR; PG8_MMA(1, 0, At, B0); PG8_MMA(1, 1, At, B1); PG8_BAR; PG8_SCHED;
	s_add_i32 s52, 0, 0x18000
	v_add_u32_e32 v148, s52, v146
	s_add_i32 s53, 0, 0x1c000
	ds_read_b128 v[142:145], v148
	ds_read_b128 v[166:169], v148 offset:1024
	ds_read_b128 v[170:173], v148 offset:2048
	ds_read_b128 v[174:177], v148 offset:3072
	v_add_u32_e32 v148, s53, v146
	ds_read_b128 v[178:181], v148
	ds_read_b128 v[182:185], v148 offset:1024
	ds_read_b128 v[186:189], v148 offset:2048
	ds_read_b128 v[190:193], v148 offset:3072
	s_add_u32 s22, s22, 0x40000
	s_addc_u32 s23, s23, 0
	s_mov_b32 m0, s40
	v_lshl_add_u64 v[244:245], s[22:23], 0, v[136:137]
	ds_read_b128 v[194:197], v153 offset:32768
	ds_read_b128 v[198:201], v153 offset:33792
	ds_read_b128 v[202:205], v153 offset:34816
	ds_read_b128 v[206:209], v153 offset:35840
	ds_read_b128 v[210:213], v153 offset:36864
	ds_read_b128 v[214:217], v153 offset:37888
	ds_read_b128 v[218:221], v153 offset:38912
	ds_read_b128 v[222:225], v153 offset:39936
	global_load_lds_dwordx4 v[244:245], off
	s_mov_b32 m0, s41
	v_lshl_add_u64 v[244:245], s[22:23], 0, v[132:133]
	global_load_lds_dwordx4 v[244:245], off
	s_waitcnt vmcnt(8)
	s_waitcnt lgkmcnt(0)
	s_barrier
	s_waitcnt lgkmcnt(0)
	v_mfma_f32_16x16x32_bf16 v[128:131], v[142:145], v[194:197], v[128:131]
	v_mfma_f32_16x16x32_bf16 v[120:123], v[170:173], v[194:197], v[120:123]
	v_mfma_f32_16x16x32_bf16 v[112:115], v[142:145], v[202:205], v[112:115]
	v_mfma_f32_16x16x32_bf16 v[104:107], v[170:173], v[202:205], v[104:107]
	v_mfma_f32_16x16x32_bf16 v[96:99], v[142:145], v[210:213], v[96:99]
	v_mfma_f32_16x16x32_bf16 v[88:91], v[170:173], v[210:213], v[88:91]
	v_mfma_f32_16x16x32_bf16 v[80:83], v[142:145], v[218:221], v[80:83]
	v_mfma_f32_16x16x32_bf16 v[72:75], v[170:173], v[218:221], v[72:75]
	v_mfma_f32_16x16x32_bf16 v[128:131], v[166:169], v[198:201], v[128:131]
	v_mfma_f32_16x16x32_bf16 v[120:123], v[174:177], v[198:201], v[120:123]
	v_mfma_f32_16x16x32_bf16 v[112:115], v[166:169], v[206:209], v[112:115]
	v_mfma_f32_16x16x32_bf16 v[104:107], v[174:177], v[206:209], v[104:107]
	v_mfma_f32_16x16x32_bf16 v[96:99], v[166:169], v[214:217], v[96:99]
	v_mfma_f32_16x16x32_bf16 v[88:91], v[174:177], v[214:217], v[88:91]
	v_mfma_f32_16x16x32_bf16 v[80:83], v[166:169], v[222:225], v[80:83]
	v_mfma_f32_16x16x32_bf16 v[72:75], v[174:177], v[222:225], v[72:75]
	v_mfma_f32_16x16x32_bf16 v[124:127], v[178:181], v[194:197], v[124:127]
	v_mfma_f32_16x16x32_bf16 v[116:119], v[186:189], v[194:197], v[116:119]
	v_mfma_f32_16x16x32_bf16 v[108:111], v[178:181], v[202:205], v[108:111]
	v_mfma_f32_16x16x32_bf16 v[100:103], v[186:189], v[202:205], v[100:103]
	v_mfma_f32_16x16x32_bf16 v[92:95], v[178:181], v[210:213], v[92:95]
	v_mfma_f32_16x16x32_bf16 v[84:87], v[186:189], v[210:213], v[84:87]
	v_mfma_f32_16x16x32_bf16 v[76:79], v[178:181], v[218:221], v[76:79]
	v_mfma_f32_16x16x32_bf16 v[68:71], v[186:189], v[218:221], v[68:71]
	v_mfma_f32_16x16x32_bf16 v[124:127], v[182:185], v[198:201], v[124:127]
	v_mfma_f32_16x16x32_bf16 v[116:119], v[190:193], v[198:201], v[116:119]
	v_mfma_f32_16x16x32_bf16 v[108:111], v[182:185], v[206:209], v[108:111]
	v_mfma_f32_16x16x32_bf16 v[100:103], v[190:193], v[206:209], v[100:103]
	v_mfma_f32_16x16x32_bf16 v[92:95], v[182:185], v[214:217], v[92:95]
	v_mfma_f32_16x16x32_bf16 v[84:87], v[190:193], v[214:217], v[84:87]
	v_mfma_f32_16x16x32_bf16 v[76:79], v[182:185], v[222:225], v[76:79]
	v_mfma_f32_16x16x32_bf16 v[68:71], v[190:193], v[222:225], v[68:71]
	s_barrier
	s_add_i32 s22, s52, s37
	v_lshl_add_u64 v[226:227], v[226:227], 0, s[0:1]
	s_mov_b32 m0, s22
	ds_read_b128 v[194:197], v153 offset:49152
	ds_read_b128 v[198:201], v153 offset:50176
	ds_read_b128 v[202:205], v153 offset:51200
	ds_read_b128 v[206:209], v153 offset:52224
	ds_read_b128 v[210:213], v153 offset:53248
	ds_read_b128 v[214:217], v153 offset:54272
	ds_read_b128 v[218:221], v153 offset:55296
	ds_read_b128 v[222:225], v153 offset:56320
	global_load_lds_dwordx4 v[226:227], off
	s_add_i32 m0, s22, 0x2000
	s_add_u32 s20, s20, 0x40080
	v_lshl_add_u64 v[226:227], v[238:239], 0, s[0:1]
	s_addc_u32 s21, s21, 0
	s_add_i32 s22, s53, s37
	global_load_lds_dwordx4 v[226:227], off
	s_mov_b32 m0, s22
	v_lshl_add_u64 v[226:227], s[20:21], 0, v[134:135]
	global_load_lds_dwordx4 v[226:227], off
	s_add_i32 m0, s22, 0x2000
	v_lshl_add_u64 v[226:227], s[20:21], 0, v[0:1]
	global_load_lds_dwordx4 v[226:227], off
	s_mov_b32 m0, s42
	v_lshl_add_u64 v[226:227], v[240:241], 0, s[0:1]
	global_load_lds_dwordx4 v[226:227], off
	s_mov_b32 m0, s43
	v_lshl_add_u64 v[226:227], v[242:243], 0, s[0:1]
	global_load_lds_dwordx4 v[226:227], off
	s_waitcnt vmcnt(8)
	s_waitcnt lgkmcnt(0)
	s_barrier
	s_waitcnt lgkmcnt(0)
	v_mfma_f32_16x16x32_bf16 v[64:67], v[142:145], v[194:197], v[64:67]
	v_mfma_f32_16x16x32_bf16 v[56:59], v[170:173], v[194:197], v[56:59]
	v_mfma_f32_16x16x32_bf16 v[48:51], v[142:145], v[202:205], v[48:51]
	v_mfma_f32_16x16x32_bf16 v[40:43], v[170:173], v[202:205], v[40:43]
	v_mfma_f32_16x16x32_bf16 v[32:35], v[142:145], v[210:213], v[32:35]
	v_mfma_f32_16x16x32_bf16 v[24:27], v[170:173], v[210:213], v[24:27]
	v_mfma_f32_16x16x32_bf16 v[16:19], v[142:145], v[218:221], v[16:19]
	v_mfma_f32_16x16x32_bf16 v[8:11], v[170:173], v[218:221], v[8:11]
	v_mfma_f32_16x16x32_bf16 v[64:67], v[166:169], v[198:201], v[64:67]
	v_mfma_f32_16x16x32_bf16 v[56:59], v[174:177], v[198:201], v[56:59]
	v_mfma_f32_16x16x32_bf16 v[48:51], v[166:169], v[206:209], v[48:51]
	v_mfma_f32_16x16x32_bf16 v[40:43], v[174:177], v[206:209], v[40:43]
	v_mfma_f32_16x16x32_bf16 v[32:35], v[166:169], v[214:217], v[32:35]
	v_mfma_f32_16x16x32_bf16 v[24:27], v[174:177], v[214:217], v[24:27]
	v_mfma_f32_16x16x32_bf16 v[16:19], v[166:169], v[222:225], v[16:19]
	v_mfma_f32_16x16x32_bf16 v[8:11], v[174:177], v[222:225], v[8:11]
	v_mfma_f32_16x16x32_bf16 v[60:63], v[178:181], v[194:197], v[60:63]
	v_mfma_f32_16x16x32_bf16 v[52:55], v[186:189], v[194:197], v[52:55]
	v_mfma_f32_16x16x32_bf16 v[44:47], v[178:181], v[202:205], v[44:47]
	v_mfma_f32_16x16x32_bf16 v[36:39], v[186:189], v[202:205], v[36:39]
	v_mfma_f32_16x16x32_bf16 v[28:31], v[178:181], v[210:213], v[28:31]
	v_mfma_f32_16x16x32_bf16 v[20:23], v[186:189], v[210:213], v[20:23]
	v_mfma_f32_16x16x32_bf16 v[12:15], v[178:181], v[218:221], v[12:15]
	v_mfma_f32_16x16x32_bf16 v[4:7], v[186:189], v[218:221], v[4:7]
	v_mfma_f32_16x16x32_bf16 v[60:63], v[182:185], v[198:201], v[60:63]
	v_mfma_f32_16x16x32_bf16 v[52:55], v[190:193], v[198:201], v[52:55]
	v_mfma_f32_16x16x32_bf16 v[44:47], v[182:185], v[206:209], v[44:47]
	v_mfma_f32_16x16x32_bf16 v[36:39], v[190:193], v[206:209], v[36:39]
	v_mfma_f32_16x16x32_bf16 v[28:31], v[182:185], v[214:217], v[28:31]
	v_mfma_f32_16x16x32_bf16 v[20:23], v[190:193], v[214:217], v[20:23]
	v_mfma_f32_16x16x32_bf16 v[12:15], v[182:185], v[222:225], v[12:15]
	v_mfma_f32_16x16x32_bf16 v[4:7], v[190:193], v[222:225], v[4:7]
	s_barrier
	s_add_i32 s51, s51, 2
	s_add_u32 s18, s18, 0x100
	s_addc_u32 s19, s19, 0
	s_add_u32 s49, s49, 0x100
	s_addc_u32 s50, s50, 0
	s_cmp_gt_u32 s51, 13
	s_cbranch_scc0 .LBB0_522

; #define PG8_STAGE(bufoff, gbase, voff) do { _Pragma("unroll") for (int _i = 0; _i < 2; ++_i) \
;         __builtin_amdgcn_global_load_lds((const unsigned*)((const char*)(gbase) + (voff)[_i]), (PG8_LAS unsigned*)(lds + (bufoff) + ldsw + _i * 8192), 16, 0, 0); } while (0)
; #define PG8_LDA(dst, b, h) do { _Pragma("unroll") for (int m = 0; m < 4; ++m) _Pragma("unroll") for (int k = 0; k < 2; ++k) dst[m][k] = *(const PG8_LAS bf16x8*)(lds + PG8_SA(b, h) + aoff + m * 2048 + k * 1024); } while (0)
; #define PG8_LDB(dst, b, h) do { _Pragma("unroll") for (int n = 0; n < 2; ++n) _Pragma("unroll") for (int k = 0; k < 2; ++k) dst[n][k] = *(const PG8_LAS bf16x8*)(lds + PG8_SB(b, h) + boff + n * 2048 + k * 1024); } while (0)
; #define PG8_WAIT_V(n) asm volatile("s_waitcnt vmcnt(" #n ")" ::: "memory")
; #define PG8_WAIT_L(n) asm volatile("s_waitcnt lgkmcnt(" #n ")" ::: "memory")
; #define PG8_BAR __builtin_amdgcn_s_barrier()
; #define PG8_SCHED __builtin_amdgcn_sched_barrier(0)
; template <class Epi, class Sched, bool ALIGN_EPI = false, bool SP2 = false>
; __device__ __forceinline__ void gemm_phase(PG8_LAS unsigned char* lds, const Gemm g, const Sched& S, const Epi& E, const int tid) {
;     ...
;         const bool has_next = S.next(ui + 1, nxt);
;         const char* nA = has_next ? (const char*)g.A + (size_t)nxt.pm * tstep : cA; const char* nB = has_next ? (const char*)g.Bt + (size_t)nxt.pn * tstep : cB;
;         for (int t = 0; t < nt; t += 2) {
;             const bool last = (t == nt - 2);
;             const char* a1 = cA + (size_t)(t + 1) * kstep;
;             const char* a2 = last ? nA : cA + (size_t)(t + 2) * kstep; const char* b2 = last ? nB : cB + (size_t)(t + 2) * kstep;
;             const char* a3 = a2 + kstep; const char* b3 = b2 + kstep;
;             if (last && has_next) S.a_ready(nxt);
;             if constexpr (SP2) {
;             PG8_LDB(B0, 0, 0); PG8_LDB(B1, 0, 1); PG8_SCHED; PG8_LDA(At, 0, 0); PG8_STAGE(PG8_SA(1, 1), a1 + hstep, voffA);
;             PG8_WAIT_V(8); PG8_WAIT_L(0); PG8_BAR; PG8_MMA(0, 0, At, B0); PG8_MMA(0, 1, At, B1); PG8_BAR; PG8_SCHED;
;             PG8_LDA(At, 0, 1); PG8_STAGE(PG8_SB(0, 0), b2, voffB); PG8_STAGE(PG8_SB(0, 1), b2 + hstep, voffB); PG8_STAGE(PG8_SA(0, 0), a2, voffA);
;             PG8_WAIT_V(8); PG8_WAIT_L(0); PG8_BAR; PG8_MMA(1, 0, At, B0); PG8_MMA(1, 1, At, B1); PG8_BAR; PG8_SCHED;
.LBB0_841:
	s_ashr_i32 s13, s12, 31
	s_lshl_b64 s[14:15], s[12:13], 19
	s_add_u32 s14, s34, s14
	s_addc_u32 s15, s36, s15
	s_and_b64 s[16:17], s[38:39], exec
	s_cselect_b32 s13, s15, s23
	s_cselect_b32 s19, s14, s22
	s_ashr_i32 s11, s10, 31
	s_lshl_b64 s[16:17], s[10:11], 19
	s_add_u32 s16, s4, s16
	s_addc_u32 s17, s5, s17
	s_and_b64 s[26:27], s[38:39], exec
	s_cselect_b32 s11, s17, s25
	s_cselect_b32 s46, s16, s24
	s_add_u32 s22, s22, 0x40080
	s_addc_u32 s23, s23, 0
	s_add_u32 s47, s24, 0x100
	v_mov_b32_e32 v4, 0
	s_addc_u32 s48, s25, 0
	s_mov_b32 s49, -2
	s_add_u32 s24, s22, 0xfffc0080
	s_addc_u32 s25, s23, -1
	s_add_i32 s50, 0, 0x10000
	s_cmp_eq_u32 s49, 12
	s_cselect_b32 s27, s13, s25
	s_cselect_b32 s26, s19, s24
	v_add_u32_e32 v148, s50, v146
	s_cselect_b32 s25, s11, s48
	s_cselect_b32 s24, s46, s47
	s_add_i32 s52, 0, 0x14000
	ds_read_b128 v[142:145], v148
	ds_read_b128 v[166:169], v148 offset:1024
	ds_read_b128 v[170:173], v148 offset:2048
	ds_read_b128 v[174:177], v148 offset:3072
	v_add_u32_e32 v148, s52, v146
	ds_read_b128 v[178:181], v148
	ds_read_b128 v[182:185], v148 offset:1024
	ds_read_b128 v[186:189], v148 offset:2048
	ds_read_b128 v[190:193], v148 offset:3072
	v_lshl_add_u64 v[226:227], s[22:23], 0, v[138:139]
	s_add_i32 m0, s21, 0xc000
	ds_read_b128 v[194:197], v153
	ds_read_b128 v[198:201], v153 offset:1024
	ds_read_b128 v[202:205], v153 offset:2048
	ds_read_b128 v[206:209], v153 offset:3072
	ds_read_b128 v[210:213], v153 offset:4096
	ds_read_b128 v[214:217], v153 offset:5120
	ds_read_b128 v[218:221], v153 offset:6144
	ds_read_b128 v[222:225], v153 offset:7168
	global_load_lds_dwordx4 v[226:227], off
	s_add_i32 m0, s21, 0xe000
	v_lshl_add_u64 v[226:227], s[22:23], 0, v[140:141]
	global_load_lds_dwordx4 v[226:227], off
	s_waitcnt vmcnt(8)
	s_waitcnt lgkmcnt(0)
	s_barrier
	s_waitcnt lgkmcnt(0)
	v_mfma_f32_16x16x32_bf16 v[128:131], v[142:145], v[194:197], 0
	v_mfma_f32_16x16x32_bf16 v[124:127], v[170:173], v[194:197], 0
	v_mfma_f32_16x16x32_bf16 v[112:115], v[142:145], v[202:205], 0
	v_mfma_f32_16x16x32_bf16 v[108:111], v[170:173], v[202:205], 0
	v_mfma_f32_16x16x32_bf16 v[96:99], v[142:145], v[210:213], 0
	v_mfma_f32_16x16x32_bf16 v[92:95], v[170:173], v[210:213], 0
	v_mfma_f32_16x16x32_bf16 v[80:83], v[142:145], v[218:221], 0
	v_mfma_f32_16x16x32_bf16 v[76:79], v[170:173], v[218:221], 0
	v_mfma_f32_16x16x32_bf16 v[128:131], v[166:169], v[198:201], v[128:131]
	v_mfma_f32_16x16x32_bf16 v[124:127], v[174:177], v[198:201], v[124:127]
	v_mfma_f32_16x16x32_bf16 v[112:115], v[166:169], v[206:209], v[112:115]
	v_mfma_f32_16x16x32_bf16 v[108:111], v[174:177], v[206:209], v[108:111]
	v_mfma_f32_16x16x32_bf16 v[96:99], v[166:169], v[214:217], v[96:99]
	v_mfma_f32_16x16x32_bf16 v[92:95], v[174:177], v[214:217], v[92:95]
	v_mfma_f32_16x16x32_bf16 v[80:83], v[166:169], v[222:225], v[80:83]
	v_mfma_f32_16x16x32_bf16 v[76:79], v[174:177], v[222:225], v[76:79]
	v_mfma_f32_16x16x32_bf16 v[120:123], v[178:181], v[194:197], 0
	v_mfma_f32_16x16x32_bf16 v[116:119], v[186:189], v[194:197], 0
	v_mfma_f32_16x16x32_bf16 v[104:107], v[178:181], v[202:205], 0
	v_mfma_f32_16x16x32_bf16 v[100:103], v[186:189], v[202:205], 0
	v_mfma_f32_16x16x32_bf16 v[88:91], v[178:181], v[210:213], 0
	v_mfma_f32_16x16x32_bf16 v[84:87], v[186:189], v[210:213], 0
	v_mfma_f32_16x16x32_bf16 v[72:75], v[178:181], v[218:221], 0
	v_mfma_f32_16x16x32_bf16 v[68:71], v[186:189], v[218:221], 0
	v_mfma_f32_16x16x32_bf16 v[120:123], v[182:185], v[198:201], v[120:123]
	v_mfma_f32_16x16x32_bf16 v[116:119], v[190:193], v[198:201], v[116:119]
	v_mfma_f32_16x16x32_bf16 v[104:107], v[182:185], v[206:209], v[104:107]
	v_mfma_f32_16x16x32_bf16 v[100:103], v[190:193], v[206:209], v[100:103]
	v_mfma_f32_16x16x32_bf16 v[88:91], v[182:185], v[214:217], v[88:91]
	v_mfma_f32_16x16x32_bf16 v[84:87], v[190:193], v[214:217], v[84:87]
	v_mfma_f32_16x16x32_bf16 v[72:75], v[182:185], v[222:225], v[72:75]
	v_mfma_f32_16x16x32_bf16 v[68:71], v[190:193], v[222:225], v[68:71]
	s_barrier
	s_add_i32 s50, s50, s37
	v_lshl_add_u64 v[226:227], s[24:25], 0, v[132:133]
	s_mov_b32 m0, s50
	ds_read_b128 v[194:197], v153 offset:16384
	ds_read_b128 v[198:201], v153 offset:17408
	ds_read_b128 v[202:205], v153 offset:18432
	ds_read_b128 v[206:209], v153 offset:19456
	ds_read_b128 v[210:213], v153 offset:20480
	ds_read_b128 v[214:217], v153 offset:21504
	ds_read_b128 v[218:221], v153 offset:22528
	ds_read_b128 v[222:225], v153 offset:23552
	global_load_lds_dwordx4 v[226:227], off
	s_add_i32 m0, s50, 0x2000
	s_add_u32 s50, s24, 0x40000
	v_lshl_add_u64 v[238:239], s[24:25], 0, v[136:137]
	s_addc_u32 s51, s25, 0
	s_add_i32 s52, s52, s37
	global_load_lds_dwordx4 v[238:239], off
	v_lshl_add_u64 v[240:241], s[50:51], 0, v[132:133]
	s_mov_b32 m0, s52
	v_lshl_add_u64 v[242:243], s[26:27], 0, v[134:135]
	global_load_lds_dwordx4 v[240:241], off
	s_add_i32 m0, s52, 0x2000
	v_lshl_add_u64 v[240:241], s[50:51], 0, v[136:137]
	global_load_lds_dwordx4 v[240:241], off
	s_mov_b32 m0, s21
	v_lshl_add_u64 v[240:241], s[26:27], 0, v[0:1]
	global_load_lds_dwordx4 v[240:241], off
	s_mov_b32 m0, s40
	s_nop 0
	global_load_lds_dwordx4 v[242:243], off
	s_waitcnt vmcnt(8)
	s_waitcnt lgkmcnt(0)
	s_barrier
; #define PG8_STAGE(bufoff, gbase, voff) do { _Pragma("unroll") for (int _i = 0; _i < 2; ++_i) \
;         __builtin_amdgcn_global_load_lds((const unsigned*)((const char*)(gbase) + (voff)[_i]), (PG8_LAS unsigned*)(lds + (bufoff) + ldsw + _i * 8192), 16, 0, 0); } while (0)
; #define PG8_LDA(dst, b, h) do { _Pragma("unroll") for (int m = 0; m < 4; ++m) _Pragma("unroll") for (int k = 0; k < 2; ++k) dst[m][k] = *(const PG8_LAS bf16x8*)(lds + PG8_SA(b, h) + aoff + m * 2048 + k * 1024); } while (0)
; #define PG8_LDB(dst, b, h) do { _Pragma("unroll") for (int n = 0; n < 2; ++n) _Pragma("unroll") for (int k = 0; k < 2; ++k) dst[n][k] = *(const PG8_LAS bf16x8*)(lds + PG8_SB(b, h) + boff + n * 2048 + k * 1024); } while (0)
; #define PG8_MMA(ai, bj, At, Bt) do { __builtin_amdgcn_s_setprio(1); _Pragma("unroll") for (int m = 0; m < 4; ++m) _Pragma("unroll") for (int n = 0; n < 2; ++n) _Pragma("unroll") for (int k = 0; k < 2; ++k) \
;         acc[ai][bj][m][n] = __builtin_amdgcn_mfma_f32_16x16x32_bf16(Bt[n][k], At[m][k], acc[ai][bj][m][n], 0, 0, 0); __builtin_amdgcn_s_setprio(0); } while (0)
; #define PG8_WAIT_V(n) asm volatile("s_waitcnt vmcnt(" #n ")" ::: "memory")
; #define PG8_WAIT_L(n) asm volatile("s_waitcnt lgkmcnt(" #n ")" ::: "memory")
; #define PG8_BAR __builtin_amdgcn_s_barrier()
; #define PG8_SCHED __builtin_amdgcn_sched_barrier(0)
; template <class Epi, class Sched, bool ALIGN_EPI = false, bool SP2 = false>
; __device__ __forceinline__ void gemm_phase(PG8_LAS unsigned char* lds, const Gemm g, const Sched& S, const Epi& E, const int tid) {
;     ...
;             PG8_WAIT_V(8); PG8_WAIT_L(0); PG8_BAR; PG8_MMA(1, 0, At, B0); PG8_MMA(1, 1, At, B1); PG8_BAR; PG8_SCHED;
;             PG8_LDB(B0, 1, 0); PG8_LDB(B1, 1, 1); PG8_SCHED; PG8_LDA(At, 1, 0); PG8_STAGE(PG8_SA(0, 1), a2 + hstep, voffA);
;             PG8_WAIT_V(8); PG8_WAIT_L(0); PG8_BAR; PG8_MMA(0, 0, At, B0); PG8_MMA(0, 1, At, B1); PG8_BAR; PG8_SCHED;
	s_waitcnt lgkmcnt(0)
	v_mfma_f32_16x16x32_bf16 v[64:67], v[142:145], v[194:197], 0
	v_mfma_f32_16x16x32_bf16 v[60:63], v[170:173], v[194:197], 0
	v_mfma_f32_16x16x32_bf16 v[48:51], v[142:145], v[202:205], 0
	v_mfma_f32_16x16x32_bf16 v[44:47], v[170:173], v[202:205], 0
	v_mfma_f32_16x16x32_bf16 v[32:35], v[142:145], v[210:213], 0
	v_mfma_f32_16x16x32_bf16 v[28:31], v[170:173], v[210:213], 0
	v_mfma_f32_16x16x32_bf16 v[16:19], v[142:145], v[218:221], 0
	v_mfma_f32_16x16x32_bf16 v[12:15], v[170:173], v[218:221], 0
	v_mfma_f32_16x16x32_bf16 v[64:67], v[166:169], v[198:201], v[64:67]
	v_mfma_f32_16x16x32_bf16 v[60:63], v[174:177], v[198:201], v[60:63]
	v_mfma_f32_16x16x32_bf16 v[48:51], v[166:169], v[206:209], v[48:51]
	v_mfma_f32_16x16x32_bf16 v[44:47], v[174:177], v[206:209], v[44:47]
	v_mfma_f32_16x16x32_bf16 v[32:35], v[166:169], v[214:217], v[32:35]
	v_mfma_f32_16x16x32_bf16 v[28:31], v[174:177], v[214:217], v[28:31]
	v_mfma_f32_16x16x32_bf16 v[16:19], v[166:169], v[222:225], v[16:19]
	v_mfma_f32_16x16x32_bf16 v[12:15], v[174:177], v[222:225], v[12:15]
	v_mfma_f32_16x16x32_bf16 v[56:59], v[178:181], v[194:197], 0
	v_mfma_f32_16x16x32_bf16 v[52:55], v[186:189], v[194:197], 0
	v_mfma_f32_16x16x32_bf16 v[40:43], v[178:181], v[202:205], 0
	v_mfma_f32_16x16x32_bf16 v[36:39], v[186:189], v[202:205], 0
	v_mfma_f32_16x16x32_bf16 v[24:27], v[178:181], v[210:213], 0
	v_mfma_f32_16x16x32_bf16 v[20:23], v[186:189], v[210:213], 0
	v_mfma_f32_16x16x32_bf16 v[8:11], v[178:181], v[218:221], 0
	v_mfma_f32_16x16x32_bf16 v[4:7], v[186:189], v[218:221], 0
	v_mfma_f32_16x16x32_bf16 v[56:59], v[182:185], v[198:201], v[56:59]
	v_mfma_f32_16x16x32_bf16 v[52:55], v[190:193], v[198:201], v[52:55]
	v_mfma_f32_16x16x32_bf16 v[40:43], v[182:185], v[206:209], v[40:43]
	v_mfma_f32_16x16x32_bf16 v[36:39], v[190:193], v[206:209], v[36:39]
	v_mfma_f32_16x16x32_bf16 v[24:27], v[182:185], v[214:217], v[24:27]
	v_mfma_f32_16x16x32_bf16 v[20:23], v[190:193], v[214:217], v[20:23]
	v_mfma_f32_16x16x32_bf16 v[8:11], v[182:185], v[222:225], v[8:11]
	v_mfma_f32_16x16x32_bf16 v[4:7], v[190:193], v[222:225], v[4:7]
	s_barrier
	s_add_i32 s50, 0, 0x18000
	v_add_u32_e32 v148, s50, v146
	s_add_i32 s51, 0, 0x1c000
	ds_read_b128 v[142:145], v148
	ds_read_b128 v[166:169], v148 offset:1024
	ds_read_b128 v[170:173], v148 offset:2048
	ds_read_b128 v[174:177], v148 offset:3072
	v_add_u32_e32 v148, s51, v146
	ds_read_b128 v[178:181], v148
	ds_read_b128 v[182:185], v148 offset:1024
	ds_read_b128 v[186:189], v148 offset:2048
	ds_read_b128 v[190:193], v148 offset:3072
	s_add_u32 s26, s26, 0x40000
	s_addc_u32 s27, s27, 0
	s_mov_b32 m0, s41
	v_lshl_add_u64 v[244:245], s[26:27], 0, v[0:1]
	ds_read_b128 v[194:197], v153 offset:32768
	ds_read_b128 v[198:201], v153 offset:33792
	ds_read_b128 v[202:205], v153 offset:34816
	ds_read_b128 v[206:209], v153 offset:35840
	ds_read_b128 v[210:213], v153 offset:36864
	ds_read_b128 v[214:217], v153 offset:37888
	ds_read_b128 v[218:221], v153 offset:38912
	ds_read_b128 v[222:225], v153 offset:39936
	global_load_lds_dwordx4 v[244:245], off
	s_mov_b32 m0, s42
	v_lshl_add_u64 v[244:245], s[26:27], 0, v[134:135]
	global_load_lds_dwordx4 v[244:245], off
	s_waitcnt vmcnt(8)
	s_waitcnt lgkmcnt(0)
	s_barrier
	s_waitcnt lgkmcnt(0)
	v_mfma_f32_16x16x32_bf16 v[128:131], v[142:145], v[194:197], v[128:131]
	v_mfma_f32_16x16x32_bf16 v[124:127], v[170:173], v[194:197], v[124:127]
	v_mfma_f32_16x16x32_bf16 v[112:115], v[142:145], v[202:205], v[112:115]
	v_mfma_f32_16x16x32_bf16 v[108:111], v[170:173], v[202:205], v[108:111]
	v_mfma_f32_16x16x32_bf16 v[96:99], v[142:145], v[210:213], v[96:99]
	v_mfma_f32_16x16x32_bf16 v[92:95], v[170:173], v[210:213], v[92:95]
	v_mfma_f32_16x16x32_bf16 v[80:83], v[142:145], v[218:221], v[80:83]
	v_mfma_f32_16x16x32_bf16 v[76:79], v[170:173], v[218:221], v[76:79]
	v_mfma_f32_16x16x32_bf16 v[128:131], v[166:169], v[198:201], v[128:131]
	v_mfma_f32_16x16x32_bf16 v[124:127], v[174:177], v[198:201], v[124:127]
	v_mfma_f32_16x16x32_bf16 v[112:115], v[166:169], v[206:209], v[112:115]
	v_mfma_f32_16x16x32_bf16 v[108:111], v[174:177], v[206:209], v[108:111]
	v_mfma_f32_16x16x32_bf16 v[96:99], v[166:169], v[214:217], v[96:99]
	v_mfma_f32_16x16x32_bf16 v[92:95], v[174:177], v[214:217], v[92:95]
	v_mfma_f32_16x16x32_bf16 v[80:83], v[166:169], v[222:225], v[80:83]
	v_mfma_f32_16x16x32_bf16 v[76:79], v[174:177], v[222:225], v[76:79]
	v_mfma_f32_16x16x32_bf16 v[120:123], v[178:181], v[194:197], v[120:123]
	v_mfma_f32_16x16x32_bf16 v[116:119], v[186:189], v[194:197], v[116:119]
	v_mfma_f32_16x16x32_bf16 v[104:107], v[178:181], v[202:205], v[104:107]
	v_mfma_f32_16x16x32_bf16 v[100:103], v[186:189], v[202:205], v[100:103]
	v_mfma_f32_16x16x32_bf16 v[88:91], v[178:181], v[210:213], v[88:91]
	v_mfma_f32_16x16x32_bf16 v[84:87], v[186:189], v[210:213], v[84:87]
	v_mfma_f32_16x16x32_bf16 v[72:75], v[178:181], v[218:221], v[72:75]
	v_mfma_f32_16x16x32_bf16 v[68:71], v[186:189], v[218:221], v[68:71]
	v_mfma_f32_16x16x32_bf16 v[120:123], v[182:185], v[198:201], v[120:123]
	v_mfma_f32_16x16x32_bf16 v[116:119], v[190:193], v[198:201], v[116:119]
	v_mfma_f32_16x16x32_bf16 v[104:107], v[182:185], v[206:209], v[104:107]
	v_mfma_f32_16x16x32_bf16 v[100:103], v[190:193], v[206:209], v[100:103]
	v_mfma_f32_16x16x32_bf16 v[88:91], v[182:185], v[214:217], v[88:91]
	v_mfma_f32_16x16x32_bf16 v[84:87], v[190:193], v[214:217], v[84:87]
	v_mfma_f32_16x16x32_bf16 v[72:75], v[182:185], v[222:225], v[72:75]
	v_mfma_f32_16x16x32_bf16 v[68:71], v[190:193], v[222:225], v[68:71]
	s_barrier
; #define PG8_STAGE(bufoff, gbase, voff) do { _Pragma("unroll") for (int _i = 0; _i < 2; ++_i) \
;         __builtin_amdgcn_global_load_lds((const unsigned*)((const char*)(gbase) + (voff)[_i]), (PG8_LAS unsigned*)(lds + (bufoff) + ldsw + _i * 8192), 16, 0, 0); } while (0)
; #define PG8_LDA(dst, b, h) do { _Pragma("unroll") for (int m = 0; m < 4; ++m) _Pragma("unroll") for (int k = 0; k < 2; ++k) dst[m][k] = *(const PG8_LAS bf16x8*)(lds + PG8_SA(b, h) + aoff + m * 2048 + k * 1024); } while (0)
; #define PG8_WAIT_V(n) asm volatile("s_waitcnt vmcnt(" #n ")" ::: "memory")
; #define PG8_WAIT_L(n) asm volatile("s_waitcnt lgkmcnt(" #n ")" ::: "memory")
; #define PG8_BAR __builtin_amdgcn_s_barrier()
; template <class Epi, class Sched, bool ALIGN_EPI = false, bool SP2 = false>
; __device__ __forceinline__ void gemm_phase(PG8_LAS unsigned char* lds, const Gemm g, const Sched& S, const Epi& E, const int tid) {
;     ...
;         for (int t = 0; t < nt; t += 2) {
;             const bool last = (t == nt - 2);
;             const char* a1 = cA + (size_t)(t + 1) * kstep;
;             const char* a2 = last ? nA : cA + (size_t)(t + 2) * kstep; const char* b2 = last ? nB : cB + (size_t)(t + 2) * kstep;
;             const char* a3 = a2 + kstep; const char* b3 = b2 + kstep;
;             if (last && has_next) S.a_ready(nxt);
;             if constexpr (SP2) {
;             PG8_LDB(B0, 0, 0); PG8_LDB(B1, 0, 1); PG8_SCHED; PG8_LDA(At, 0, 0); PG8_STAGE(PG8_SA(1, 1), a1 + hstep, voffA);
;             PG8_WAIT_V(8); PG8_WAIT_L(0); PG8_BAR; PG8_MMA(0, 0, At, B0); PG8_MMA(0, 1, At, B1); PG8_BAR; PG8_SCHED;
;             PG8_LDA(At, 0, 1); PG8_STAGE(PG8_SB(0, 0), b2, voffB); PG8_STAGE(PG8_SB(0, 1), b2 + hstep, voffB); PG8_STAGE(PG8_SA(0, 0), a2, voffA);
;             PG8_WAIT_V(8); PG8_WAIT_L(0); PG8_BAR; PG8_MMA(1, 0, At, B0); PG8_MMA(1, 1, At, B1); PG8_BAR; PG8_SCHED;
;             PG8_LDB(B0, 1, 0); PG8_LDB(B1, 1, 1); PG8_SCHED; PG8_LDA(At, 1, 0); PG8_STAGE(PG8_SA(0, 1), a2 + hstep, voffA);
;             PG8_WAIT_V(8); PG8_WAIT_L(0); PG8_BAR; PG8_MMA(0, 0, At, B0); PG8_MMA(0, 1, At, B1); PG8_BAR; PG8_SCHED;
;             PG8_LDA(At, 1, 1); PG8_STAGE(PG8_SB(1, 0), b3, voffB); PG8_STAGE(PG8_SB(1, 1), b3 + hstep, voffB); PG8_STAGE(PG8_SA(1, 0), a3, voffA);
;             PG8_WAIT_V(8); PG8_WAIT_L(0); PG8_BAR; PG8_MMA(1, 0, At, B0); PG8_MMA(1, 1, At, B1); PG8_BAR; PG8_SCHED;
	s_add_i32 s26, s50, s37
	v_lshl_add_u64 v[226:227], v[226:227], 0, s[0:1]
	s_mov_b32 m0, s26
	ds_read_b128 v[194:197], v153 offset:49152
	ds_read_b128 v[198:201], v153 offset:50176
	ds_read_b128 v[202:205], v153 offset:51200
	ds_read_b128 v[206:209], v153 offset:52224
	ds_read_b128 v[210:213], v153 offset:53248
	ds_read_b128 v[214:217], v153 offset:54272
	ds_read_b128 v[218:221], v153 offset:55296
	ds_read_b128 v[222:225], v153 offset:56320
	global_load_lds_dwordx4 v[226:227], off
	s_add_i32 m0, s26, 0x2000
	s_add_u32 s24, s24, 0x40080
	v_lshl_add_u64 v[226:227], v[238:239], 0, s[0:1]
	s_addc_u32 s25, s25, 0
	s_add_i32 s26, s51, s37
	global_load_lds_dwordx4 v[226:227], off
	s_mov_b32 m0, s26
	v_lshl_add_u64 v[226:227], s[24:25], 0, v[132:133]
	global_load_lds_dwordx4 v[226:227], off
	s_add_i32 m0, s26, 0x2000
	v_lshl_add_u64 v[226:227], s[24:25], 0, v[136:137]
	global_load_lds_dwordx4 v[226:227], off
	s_mov_b32 m0, s43
	v_lshl_add_u64 v[226:227], v[240:241], 0, s[0:1]
	global_load_lds_dwordx4 v[226:227], off
	s_mov_b32 m0, s44
	v_lshl_add_u64 v[226:227], v[242:243], 0, s[0:1]
	global_load_lds_dwordx4 v[226:227], off
	s_waitcnt vmcnt(8)
	s_waitcnt lgkmcnt(0)
	s_barrier
	s_waitcnt lgkmcnt(0)
	v_mfma_f32_16x16x32_bf16 v[64:67], v[142:145], v[194:197], v[64:67]
	v_mfma_f32_16x16x32_bf16 v[60:63], v[170:173], v[194:197], v[60:63]
	v_mfma_f32_16x16x32_bf16 v[48:51], v[142:145], v[202:205], v[48:51]
	v_mfma_f32_16x16x32_bf16 v[44:47], v[170:173], v[202:205], v[44:47]
	v_mfma_f32_16x16x32_bf16 v[32:35], v[142:145], v[210:213], v[32:35]
	v_mfma_f32_16x16x32_bf16 v[28:31], v[170:173], v[210:213], v[28:31]
	v_mfma_f32_16x16x32_bf16 v[16:19], v[142:145], v[218:221], v[16:19]
	v_mfma_f32_16x16x32_bf16 v[12:15], v[170:173], v[218:221], v[12:15]
	v_mfma_f32_16x16x32_bf16 v[64:67], v[166:169], v[198:201], v[64:67]
	v_mfma_f32_16x16x32_bf16 v[60:63], v[174:177], v[198:201], v[60:63]
	v_mfma_f32_16x16x32_bf16 v[48:51], v[166:169], v[206:209], v[48:51]
	v_mfma_f32_16x16x32_bf16 v[44:47], v[174:177], v[206:209], v[44:47]
	v_mfma_f32_16x16x32_bf16 v[32:35], v[166:169], v[214:217], v[32:35]
	v_mfma_f32_16x16x32_bf16 v[28:31], v[174:177], v[214:217], v[28:31]
	v_mfma_f32_16x16x32_bf16 v[16:19], v[166:169], v[222:225], v[16:19]
	v_mfma_f32_16x16x32_bf16 v[12:15], v[174:177], v[222:225], v[12:15]
	v_mfma_f32_16x16x32_bf16 v[56:59], v[178:181], v[194:197], v[56:59]
	v_mfma_f32_16x16x32_bf16 v[52:55], v[186:189], v[194:197], v[52:55]
	v_mfma_f32_16x16x32_bf16 v[40:43], v[178:181], v[202:205], v[40:43]
	v_mfma_f32_16x16x32_bf16 v[36:39], v[186:189], v[202:205], v[36:39]
	v_mfma_f32_16x16x32_bf16 v[24:27], v[178:181], v[210:213], v[24:27]
	v_mfma_f32_16x16x32_bf16 v[20:23], v[186:189], v[210:213], v[20:23]
	v_mfma_f32_16x16x32_bf16 v[8:11], v[178:181], v[218:221], v[8:11]
	v_mfma_f32_16x16x32_bf16 v[4:7], v[186:189], v[218:221], v[4:7]
	v_mfma_f32_16x16x32_bf16 v[56:59], v[182:185], v[198:201], v[56:59]
	v_mfma_f32_16x16x32_bf16 v[52:55], v[190:193], v[198:201], v[52:55]
	v_mfma_f32_16x16x32_bf16 v[40:43], v[182:185], v[206:209], v[40:43]
	v_mfma_f32_16x16x32_bf16 v[36:39], v[190:193], v[206:209], v[36:39]
	v_mfma_f32_16x16x32_bf16 v[24:27], v[182:185], v[214:217], v[24:27]
	v_mfma_f32_16x16x32_bf16 v[20:23], v[190:193], v[214:217], v[20:23]
	v_mfma_f32_16x16x32_bf16 v[8:11], v[182:185], v[222:225], v[8:11]
	v_mfma_f32_16x16x32_bf16 v[4:7], v[190:193], v[222:225], v[4:7]
	s_barrier
	s_add_i32 s49, s49, 2
	s_add_u32 s22, s22, 0x100
	s_addc_u32 s23, s23, 0
	s_add_u32 s47, s47, 0x100
	s_addc_u32 s48, s48, 0
	s_cmp_gt_u32 s49, 13
	s_cbranch_scc0 .LBB0_842
	s_branch .Lpeel_exit4
.LBB0_842:
	s_add_u32 s24, s22, 0xfffc0080
	s_addc_u32 s25, s23, -1
	s_add_i32 s50, 0, 0x10000
	s_cmp_eq_u32 s49, 12
	s_cselect_b32 s27, s13, s25
	s_cselect_b32 s26, s19, s24
	v_add_u32_e32 v148, s50, v146
	s_cselect_b32 s25, s11, s48
	s_cselect_b32 s24, s46, s47
	s_add_i32 s52, 0, 0x14000
	ds_read_b128 v[142:145], v148
	ds_read_b128 v[166:169], v148 offset:1024
	ds_read_b128 v[170:173], v148 offset:2048
	ds_read_b128 v[174:177], v148 offset:3072
	v_add_u32_e32 v148, s52, v146
	ds_read_b128 v[178:181], v148
	ds_read_b128 v[182:185], v148 offset:1024
	ds_read_b128 v[186:189], v148 offset:2048
	ds_read_b128 v[190:193], v148 offset:3072
	v_lshl_add_u64 v[226:227], s[22:23], 0, v[138:139]
	s_add_i32 m0, s21, 0xc000
	ds_read_b128 v[194:197], v153
	ds_read_b128 v[198:201], v153 offset:1024
	ds_read_b128 v[202:205], v153 offset:2048
	ds_read_b128 v[206:209], v153 offset:3072
	ds_read_b128 v[210:213], v153 offset:4096
	ds_read_b128 v[214:217], v153 offset:5120
	ds_read_b128 v[218:221], v153 offset:6144
	ds_read_b128 v[222:225], v153 offset:7168
	global_load_lds_dwordx4 v[226:227], off
	s_add_i32 m0, s21, 0xe000
	v_lshl_add_u64 v[226:227], s[22:23], 0, v[140:141]
	global_load_lds_dwordx4 v[226:227], off
	s_waitcnt vmcnt(8)
	s_waitcnt lgkmcnt(0)
	s_barrier
; #define PG8_STAGE(bufoff, gbase, voff) do { _Pragma("unroll") for (int _i = 0; _i < 2; ++_i) \
;         __builtin_amdgcn_global_load_lds((const unsigned*)((const char*)(gbase) + (voff)[_i]), (PG8_LAS unsigned*)(lds + (bufoff) + ldsw + _i * 8192), 16, 0, 0); } while (0)
; #define PG8_LDA(dst, b, h) do { _Pragma("unroll") for (int m = 0; m < 4; ++m) _Pragma("unroll") for (int k = 0; k < 2; ++k) dst[m][k] = *(const PG8_LAS bf16x8*)(lds + PG8_SA(b, h) + aoff + m * 2048 + k * 1024); } while (0)
; #define PG8_LDB(dst, b, h) do { _Pragma("unroll") for (int n = 0; n < 2; ++n) _Pragma("unroll") for (int k = 0; k < 2; ++k) dst[n][k] = *(const PG8_LAS bf16x8*)(lds + PG8_SB(b, h) + boff + n * 2048 + k * 1024); } while (0)
; #define PG8_MMA(ai, bj, At, Bt) do { __builtin_amdgcn_s_setprio(1); _Pragma("unroll") for (int m = 0; m < 4; ++m) _Pragma("unroll") for (int n = 0; n < 2; ++n) _Pragma("unroll") for (int k = 0; k < 2; ++k) \
;         acc[ai][bj][m][n] = __builtin_amdgcn_mfma_f32_16x16x32_bf16(Bt[n][k], At[m][k], acc[ai][bj][m][n], 0, 0, 0); __builtin_amdgcn_s_setprio(0); } while (0)
; #define PG8_WAIT_V(n) asm volatile("s_waitcnt vmcnt(" #n ")" ::: "memory")
; #define PG8_WAIT_L(n) asm volatile("s_waitcnt lgkmcnt(" #n ")" ::: "memory")
; #define PG8_BAR __builtin_amdgcn_s_barrier()
; #define PG8_SCHED __builtin_amdgcn_sched_barrier(0)
; template <class Epi, class Sched, bool ALIGN_EPI = false, bool SP2 = false>
; __device__ __forceinline__ void gemm_phase(PG8_LAS unsigned char* lds, const Gemm g, const Sched& S, const Epi& E, const int tid) {
;     ...
;             PG8_LDB(B0, 0, 0); PG8_LDB(B1, 0, 1); PG8_SCHED; PG8_LDA(At, 0, 0); PG8_STAGE(PG8_SA(1, 1), a1 + hstep, voffA);
;             PG8_WAIT_V(8); PG8_WAIT_L(0); PG8_BAR; PG8_MMA(0, 0, At, B0); PG8_MMA(0, 1, At, B1); PG8_BAR; PG8_SCHED;
;             PG8_LDA(At, 0, 1); PG8_STAGE(PG8_SB(0, 0), b2, voffB); PG8_STAGE(PG8_SB(0, 1), b2 + hstep, voffB); PG8_STAGE(PG8_SA(0, 0), a2, voffA);
;             PG8_WAIT_V(8); PG8_WAIT_L(0); PG8_BAR; PG8_MMA(1, 0, At, B0); PG8_MMA(1, 1, At, B1); PG8_BAR; PG8_SCHED;
	s_waitcnt lgkmcnt(0)
	v_mfma_f32_16x16x32_bf16 v[128:131], v[142:145], v[194:197], v[128:131]
	v_mfma_f32_16x16x32_bf16 v[124:127], v[170:173], v[194:197], v[124:127]
	v_mfma_f32_16x16x32_bf16 v[112:115], v[142:145], v[202:205], v[112:115]
	v_mfma_f32_16x16x32_bf16 v[108:111], v[170:173], v[202:205], v[108:111]
	v_mfma_f32_16x16x32_bf16 v[96:99], v[142:145], v[210:213], v[96:99]
	v_mfma_f32_16x16x32_bf16 v[92:95], v[170:173], v[210:213], v[92:95]
	v_mfma_f32_16x16x32_bf16 v[80:83], v[142:145], v[218:221], v[80:83]
	v_mfma_f32_16x16x32_bf16 v[76:79], v[170:173], v[218:221], v[76:79]
	v_mfma_f32_16x16x32_bf16 v[128:131], v[166:169], v[198:201], v[128:131]
	v_mfma_f32_16x16x32_bf16 v[124:127], v[174:177], v[198:201], v[124:127]
	v_mfma_f32_16x16x32_bf16 v[112:115], v[166:169], v[206:209], v[112:115]
	v_mfma_f32_16x16x32_bf16 v[108:111], v[174:177], v[206:209], v[108:111]
	v_mfma_f32_16x16x32_bf16 v[96:99], v[166:169], v[214:217], v[96:99]
	v_mfma_f32_16x16x32_bf16 v[92:95], v[174:177], v[214:217], v[92:95]
	v_mfma_f32_16x16x32_bf16 v[80:83], v[166:169], v[222:225], v[80:83]
	v_mfma_f32_16x16x32_bf16 v[76:79], v[174:177], v[222:225], v[76:79]
	v_mfma_f32_16x16x32_bf16 v[120:123], v[178:181], v[194:197], v[120:123]
	v_mfma_f32_16x16x32_bf16 v[116:119], v[186:189], v[194:197], v[116:119]
	v_mfma_f32_16x16x32_bf16 v[104:107], v[178:181], v[202:205], v[104:107]
	v_mfma_f32_16x16x32_bf16 v[100:103], v[186:189], v[202:205], v[100:103]
	v_mfma_f32_16x16x32_bf16 v[88:91], v[178:181], v[210:213], v[88:91]
	v_mfma_f32_16x16x32_bf16 v[84:87], v[186:189], v[210:213], v[84:87]
	v_mfma_f32_16x16x32_bf16 v[72:75], v[178:181], v[218:221], v[72:75]
	v_mfma_f32_16x16x32_bf16 v[68:71], v[186:189], v[218:221], v[68:71]
	v_mfma_f32_16x16x32_bf16 v[120:123], v[182:185], v[198:201], v[120:123]
	v_mfma_f32_16x16x32_bf16 v[116:119], v[190:193], v[198:201], v[116:119]
	v_mfma_f32_16x16x32_bf16 v[104:107], v[182:185], v[206:209], v[104:107]
	v_mfma_f32_16x16x32_bf16 v[100:103], v[190:193], v[206:209], v[100:103]
	v_mfma_f32_16x16x32_bf16 v[88:91], v[182:185], v[214:217], v[88:91]
	v_mfma_f32_16x16x32_bf16 v[84:87], v[190:193], v[214:217], v[84:87]
	v_mfma_f32_16x16x32_bf16 v[72:75], v[182:185], v[222:225], v[72:75]
	v_mfma_f32_16x16x32_bf16 v[68:71], v[190:193], v[222:225], v[68:71]
	s_barrier
	s_add_i32 s50, s50, s37
	v_lshl_add_u64 v[226:227], s[24:25], 0, v[132:133]
	s_mov_b32 m0, s50
	ds_read_b128 v[194:197], v153 offset:16384
	ds_read_b128 v[198:201], v153 offset:17408
	ds_read_b128 v[202:205], v153 offset:18432
	ds_read_b128 v[206:209], v153 offset:19456
	ds_read_b128 v[210:213], v153 offset:20480
	ds_read_b128 v[214:217], v153 offset:21504
	ds_read_b128 v[218:221], v153 offset:22528
	ds_read_b128 v[222:225], v153 offset:23552
	global_load_lds_dwordx4 v[226:227], off
	s_add_i32 m0, s50, 0x2000
	s_add_u32 s50, s24, 0x40000
	v_lshl_add_u64 v[238:239], s[24:25], 0, v[136:137]
	s_addc_u32 s51, s25, 0
	s_add_i32 s52, s52, s37
	global_load_lds_dwordx4 v[238:239], off
	v_lshl_add_u64 v[240:241], s[50:51], 0, v[132:133]
	s_mov_b32 m0, s52
	v_lshl_add_u64 v[242:243], s[26:27], 0, v[134:135]
	global_load_lds_dwordx4 v[240:241], off
	s_add_i32 m0, s52, 0x2000
	v_lshl_add_u64 v[240:241], s[50:51], 0, v[136:137]
	global_load_lds_dwordx4 v[240:241], off
	s_mov_b32 m0, s21
	v_lshl_add_u64 v[240:241], s[26:27], 0, v[0:1]
	global_load_lds_dwordx4 v[240:241], off
	s_mov_b32 m0, s40
	s_nop 0
	global_load_lds_dwordx4 v[242:243], off
	s_waitcnt vmcnt(8)
	s_waitcnt lgkmcnt(0)
	s_barrier
	s_waitcnt lgkmcnt(0)
	v_mfma_f32_16x16x32_bf16 v[64:67], v[142:145], v[194:197], v[64:67]
	v_mfma_f32_16x16x32_bf16 v[60:63], v[170:173], v[194:197], v[60:63]
	v_mfma_f32_16x16x32_bf16 v[48:51], v[142:145], v[202:205], v[48:51]
	v_mfma_f32_16x16x32_bf16 v[44:47], v[170:173], v[202:205], v[44:47]
	v_mfma_f32_16x16x32_bf16 v[32:35], v[142:145], v[210:213], v[32:35]
	v_mfma_f32_16x16x32_bf16 v[28:31], v[170:173], v[210:213], v[28:31]
	v_mfma_f32_16x16x32_bf16 v[16:19], v[142:145], v[218:221], v[16:19]
	v_mfma_f32_16x16x32_bf16 v[12:15], v[170:173], v[218:221], v[12:15]
	v_mfma_f32_16x16x32_bf16 v[64:67], v[166:169], v[198:201], v[64:67]
	v_mfma_f32_16x16x32_bf16 v[60:63], v[174:177], v[198:201], v[60:63]
	v_mfma_f32_16x16x32_bf16 v[48:51], v[166:169], v[206:209], v[48:51]
	v_mfma_f32_16x16x32_bf16 v[44:47], v[174:177], v[206:209], v[44:47]
	v_mfma_f32_16x16x32_bf16 v[32:35], v[166:169], v[214:217], v[32:35]
	v_mfma_f32_16x16x32_bf16 v[28:31], v[174:177], v[214:217], v[28:31]
	v_mfma_f32_16x16x32_bf16 v[16:19], v[166:169], v[222:225], v[16:19]
	v_mfma_f32_16x16x32_bf16 v[12:15], v[174:177], v[222:225], v[12:15]
	v_mfma_f32_16x16x32_bf16 v[56:59], v[178:181], v[194:197], v[56:59]
	v_mfma_f32_16x16x32_bf16 v[52:55], v[186:189], v[194:197], v[52:55]
	v_mfma_f32_16x16x32_bf16 v[40:43], v[178:181], v[202:205], v[40:43]
	v_mfma_f32_16x16x32_bf16 v[36:39], v[186:189], v[202:205], v[36:39]
	v_mfma_f32_16x16x32_bf16 v[24:27], v[178:181], v[210:213], v[24:27]
	v_mfma_f32_16x16x32_bf16 v[20:23], v[186:189], v[210:213], v[20:23]
	v_mfma_f32_16x16x32_bf16 v[8:11], v[178:181], v[218:221], v[8:11]
	v_mfma_f32_16x16x32_bf16 v[4:7], v[186:189], v[218:221], v[4:7]
	v_mfma_f32_16x16x32_bf16 v[56:59], v[182:185], v[198:201], v[56:59]
	v_mfma_f32_16x16x32_bf16 v[52:55], v[190:193], v[198:201], v[52:55]
	v_mfma_f32_16x16x32_bf16 v[40:43], v[182:185], v[206:209], v[40:43]
	v_mfma_f32_16x16x32_bf16 v[36:39], v[190:193], v[206:209], v[36:39]
	v_mfma_f32_16x16x32_bf16 v[24:27], v[182:185], v[214:217], v[24:27]
	v_mfma_f32_16x16x32_bf16 v[20:23], v[190:193], v[214:217], v[20:23]
	v_mfma_f32_16x16x32_bf16 v[8:11], v[182:185], v[222:225], v[8:11]
	v_mfma_f32_16x16x32_bf16 v[4:7], v[190:193], v[222:225], v[4:7]
	s_barrier
; #define PG8_STAGE(bufoff, gbase, voff) do { _Pragma("unroll") for (int _i = 0; _i < 2; ++_i) \
;         __builtin_amdgcn_global_load_lds((const unsigned*)((const char*)(gbase) + (voff)[_i]), (PG8_LAS unsigned*)(lds + (bufoff) + ldsw + _i * 8192), 16, 0, 0); } while (0)
; #define PG8_LDA(dst, b, h) do { _Pragma("unroll") for (int m = 0; m < 4; ++m) _Pragma("unroll") for (int k = 0; k < 2; ++k) dst[m][k] = *(const PG8_LAS bf16x8*)(lds + PG8_SA(b, h) + aoff + m * 2048 + k * 1024); } while (0)
; #define PG8_LDB(dst, b, h) do { _Pragma("unroll") for (int n = 0; n < 2; ++n) _Pragma("unroll") for (int k = 0; k < 2; ++k) dst[n][k] = *(const PG8_LAS bf16x8*)(lds + PG8_SB(b, h) + boff + n * 2048 + k * 1024); } while (0)
; #define PG8_MMA(ai, bj, At, Bt) do { __builtin_amdgcn_s_setprio(1); _Pragma("unroll") for (int m = 0; m < 4; ++m) _Pragma("unroll") for (int n = 0; n < 2; ++n) _Pragma("unroll") for (int k = 0; k < 2; ++k) \
;         acc[ai][bj][m][n] = __builtin_amdgcn_mfma_f32_16x16x32_bf16(Bt[n][k], At[m][k], acc[ai][bj][m][n], 0, 0, 0); __builtin_amdgcn_s_setprio(0); } while (0)
; #define PG8_WAIT_V(n) asm volatile("s_waitcnt vmcnt(" #n ")" ::: "memory")
; #define PG8_WAIT_L(n) asm volatile("s_waitcnt lgkmcnt(" #n ")" ::: "memory")
; #define PG8_BAR __builtin_amdgcn_s_barrier()
; #define PG8_SCHED __builtin_amdgcn_sched_barrier(0)
; template <class Epi, class Sched, bool ALIGN_EPI = false, bool SP2 = false>
; __device__ __forceinline__ void gemm_phase(PG8_LAS unsigned char* lds, const Gemm g, const Sched& S, const Epi& E, const int tid) {
;     ...
;             PG8_LDB(B0, 1, 0); PG8_LDB(B1, 1, 1); PG8_SCHED; PG8_LDA(At, 1, 0); PG8_STAGE(PG8_SA(0, 1), a2 + hstep, voffA);
;             PG8_WAIT_V(8); PG8_WAIT_L(0); PG8_BAR; PG8_MMA(0, 0, At, B0); PG8_MMA(0, 1, At, B1); PG8_BAR; PG8_SCHED;
;             PG8_LDA(At, 1, 1); PG8_STAGE(PG8_SB(1, 0), b3, voffB); PG8_STAGE(PG8_SB(1, 1), b3 + hstep, voffB); PG8_STAGE(PG8_SA(1, 0), a3, voffA);
;             PG8_WAIT_V(8); PG8_WAIT_L(0); PG8_BAR; PG8_MMA(1, 0, At, B0); PG8_MMA(1, 1, At, B1); PG8_BAR; PG8_SCHED;
	s_add_i32 s50, 0, 0x18000
	v_add_u32_e32 v148, s50, v146
	s_add_i32 s51, 0, 0x1c000
	ds_read_b128 v[142:145], v148
	ds_read_b128 v[166:169], v148 offset:1024
	ds_read_b128 v[170:173], v148 offset:2048
	ds_read_b128 v[174:177], v148 offset:3072
	v_add_u32_e32 v148, s51, v146
	ds_read_b128 v[178:181], v148
	ds_read_b128 v[182:185], v148 offset:1024
	ds_read_b128 v[186:189], v148 offset:2048
	ds_read_b128 v[190:193], v148 offset:3072
	s_add_u32 s26, s26, 0x40000
	s_addc_u32 s27, s27, 0
	s_mov_b32 m0, s41
	v_lshl_add_u64 v[244:245], s[26:27], 0, v[0:1]
	ds_read_b128 v[194:197], v153 offset:32768
	ds_read_b128 v[198:201], v153 offset:33792
	ds_read_b128 v[202:205], v153 offset:34816
	ds_read_b128 v[206:209], v153 offset:35840
	ds_read_b128 v[210:213], v153 offset:36864
	ds_read_b128 v[214:217], v153 offset:37888
	ds_read_b128 v[218:221], v153 offset:38912
	ds_read_b128 v[222:225], v153 offset:39936
	global_load_lds_dwordx4 v[244:245], off
	s_mov_b32 m0, s42
	v_lshl_add_u64 v[244:245], s[26:27], 0, v[134:135]
	global_load_lds_dwordx4 v[244:245], off
	s_waitcnt vmcnt(8)
	s_waitcnt lgkmcnt(0)
	s_barrier
	s_waitcnt lgkmcnt(0)
	v_mfma_f32_16x16x32_bf16 v[128:131], v[142:145], v[194:197], v[128:131]
	v_mfma_f32_16x16x32_bf16 v[124:127], v[170:173], v[194:197], v[124:127]
	v_mfma_f32_16x16x32_bf16 v[112:115], v[142:145], v[202:205], v[112:115]
	v_mfma_f32_16x16x32_bf16 v[108:111], v[170:173], v[202:205], v[108:111]
	v_mfma_f32_16x16x32_bf16 v[96:99], v[142:145], v[210:213], v[96:99]
	v_mfma_f32_16x16x32_bf16 v[92:95], v[170:173], v[210:213], v[92:95]
	v_mfma_f32_16x16x32_bf16 v[80:83], v[142:145], v[218:221], v[80:83]
	v_mfma_f32_16x16x32_bf16 v[76:79], v[170:173], v[218:221], v[76:79]
	v_mfma_f32_16x16x32_bf16 v[128:131], v[166:169], v[198:201], v[128:131]
	v_mfma_f32_16x16x32_bf16 v[124:127], v[174:177], v[198:201], v[124:127]
	v_mfma_f32_16x16x32_bf16 v[112:115], v[166:169], v[206:209], v[112:115]
	v_mfma_f32_16x16x32_bf16 v[108:111], v[174:177], v[206:209], v[108:111]
	v_mfma_f32_16x16x32_bf16 v[96:99], v[166:169], v[214:217], v[96:99]
	v_mfma_f32_16x16x32_bf16 v[92:95], v[174:177], v[214:217], v[92:95]
	v_mfma_f32_16x16x32_bf16 v[80:83], v[166:169], v[222:225], v[80:83]
	v_mfma_f32_16x16x32_bf16 v[76:79], v[174:177], v[222:225], v[76:79]
	v_mfma_f32_16x16x32_bf16 v[120:123], v[178:181], v[194:197], v[120:123]
	v_mfma_f32_16x16x32_bf16 v[116:119], v[186:189], v[194:197], v[116:119]
	v_mfma_f32_16x16x32_bf16 v[104:107], v[178:181], v[202:205], v[104:107]
	v_mfma_f32_16x16x32_bf16 v[100:103], v[186:189], v[202:205], v[100:103]
	v_mfma_f32_16x16x32_bf16 v[88:91], v[178:181], v[210:213], v[88:91]
	v_mfma_f32_16x16x32_bf16 v[84:87], v[186:189], v[210:213], v[84:87]
	v_mfma_f32_16x16x32_bf16 v[72:75], v[178:181], v[218:221], v[72:75]
	v_mfma_f32_16x16x32_bf16 v[68:71], v[186:189], v[218:221], v[68:71]
	v_mfma_f32_16x16x32_bf16 v[120:123], v[182:185], v[198:201], v[120:123]
	v_mfma_f32_16x16x32_bf16 v[116:119], v[190:193], v[198:201], v[116:119]
	v_mfma_f32_16x16x32_bf16 v[104:107], v[182:185], v[206:209], v[104:107]
	v_mfma_f32_16x16x32_bf16 v[100:103], v[190:193], v[206:209], v[100:103]
	v_mfma_f32_16x16x32_bf16 v[88:91], v[182:185], v[214:217], v[88:91]
	v_mfma_f32_16x16x32_bf16 v[84:87], v[190:193], v[214:217], v[84:87]
	v_mfma_f32_16x16x32_bf16 v[72:75], v[182:185], v[222:225], v[72:75]
	v_mfma_f32_16x16x32_bf16 v[68:71], v[190:193], v[222:225], v[68:71]
	s_barrier
	s_add_i32 s26, s50, s37
	v_lshl_add_u64 v[226:227], v[226:227], 0, s[0:1]
	s_mov_b32 m0, s26
	ds_read_b128 v[194:197], v153 offset:49152
	ds_read_b128 v[198:201], v153 offset:50176
	ds_read_b128 v[202:205], v153 offset:51200
	ds_read_b128 v[206:209], v153 offset:52224
	ds_read_b128 v[210:213], v153 offset:53248
	ds_read_b128 v[214:217], v153 offset:54272
	ds_read_b128 v[218:221], v153 offset:55296
	ds_read_b128 v[222:225], v153 offset:56320
	global_load_lds_dwordx4 v[226:227], off
	s_add_i32 m0, s26, 0x2000
	s_add_u32 s24, s24, 0x40080
	v_lshl_add_u64 v[226:227], v[238:239], 0, s[0:1]
	s_addc_u32 s25, s25, 0
	s_add_i32 s26, s51, s37
	global_load_lds_dwordx4 v[226:227], off
	s_mov_b32 m0, s26
	v_lshl_add_u64 v[226:227], s[24:25], 0, v[132:133]
	global_load_lds_dwordx4 v[226:227], off
	s_add_i32 m0, s26, 0x2000
	v_lshl_add_u64 v[226:227], s[24:25], 0, v[136:137]
	global_load_lds_dwordx4 v[226:227], off
	s_mov_b32 m0, s43
	v_lshl_add_u64 v[226:227], v[240:241], 0, s[0:1]
	global_load_lds_dwordx4 v[226:227], off
	s_mov_b32 m0, s44
	v_lshl_add_u64 v[226:227], v[242:243], 0, s[0:1]
	global_load_lds_dwordx4 v[226:227], off
	s_waitcnt vmcnt(8)
	s_waitcnt lgkmcnt(0)
	s_barrier
	s_waitcnt lgkmcnt(0)
	v_mfma_f32_16x16x32_bf16 v[64:67], v[142:145], v[194:197], v[64:67]
	v_mfma_f32_16x16x32_bf16 v[60:63], v[170:173], v[194:197], v[60:63]
	v_mfma_f32_16x16x32_bf16 v[48:51], v[142:145], v[202:205], v[48:51]
	v_mfma_f32_16x16x32_bf16 v[44:47], v[170:173], v[202:205], v[44:47]
	v_mfma_f32_16x16x32_bf16 v[32:35], v[142:145], v[210:213], v[32:35]
	v_mfma_f32_16x16x32_bf16 v[28:31], v[170:173], v[210:213], v[28:31]
	v_mfma_f32_16x16x32_bf16 v[16:19], v[142:145], v[218:221], v[16:19]
	v_mfma_f32_16x16x32_bf16 v[12:15], v[170:173], v[218:221], v[12:15]
	v_mfma_f32_16x16x32_bf16 v[64:67], v[166:169], v[198:201], v[64:67]
	v_mfma_f32_16x16x32_bf16 v[60:63], v[174:177], v[198:201], v[60:63]
	v_mfma_f32_16x16x32_bf16 v[48:51], v[166:169], v[206:209], v[48:51]
	v_mfma_f32_16x16x32_bf16 v[44:47], v[174:177], v[206:209], v[44:47]
	v_mfma_f32_16x16x32_bf16 v[32:35], v[166:169], v[214:217], v[32:35]
	v_mfma_f32_16x16x32_bf16 v[28:31], v[174:177], v[214:217], v[28:31]
	v_mfma_f32_16x16x32_bf16 v[16:19], v[166:169], v[222:225], v[16:19]
	v_mfma_f32_16x16x32_bf16 v[12:15], v[174:177], v[222:225], v[12:15]
	v_mfma_f32_16x16x32_bf16 v[56:59], v[178:181], v[194:197], v[56:59]
	v_mfma_f32_16x16x32_bf16 v[52:55], v[186:189], v[194:197], v[52:55]
	v_mfma_f32_16x16x32_bf16 v[40:43], v[178:181], v[202:205], v[40:43]
	v_mfma_f32_16x16x32_bf16 v[36:39], v[186:189], v[202:205], v[36:39]
	v_mfma_f32_16x16x32_bf16 v[24:27], v[178:181], v[210:213], v[24:27]
	v_mfma_f32_16x16x32_bf16 v[20:23], v[186:189], v[210:213], v[20:23]
	v_mfma_f32_16x16x32_bf16 v[8:11], v[178:181], v[218:221], v[8:11]
	v_mfma_f32_16x16x32_bf16 v[4:7], v[186:189], v[218:221], v[4:7]
	v_mfma_f32_16x16x32_bf16 v[56:59], v[182:185], v[198:201], v[56:59]
	v_mfma_f32_16x16x32_bf16 v[52:55], v[190:193], v[198:201], v[52:55]
	v_mfma_f32_16x16x32_bf16 v[40:43], v[182:185], v[206:209], v[40:43]
	v_mfma_f32_16x16x32_bf16 v[36:39], v[190:193], v[206:209], v[36:39]
	v_mfma_f32_16x16x32_bf16 v[24:27], v[182:185], v[214:217], v[24:27]
	v_mfma_f32_16x16x32_bf16 v[20:23], v[190:193], v[214:217], v[20:23]
	v_mfma_f32_16x16x32_bf16 v[8:11], v[182:185], v[222:225], v[8:11]
	v_mfma_f32_16x16x32_bf16 v[4:7], v[190:193], v[222:225], v[4:7]
	s_barrier
	s_add_i32 s49, s49, 2
	s_add_u32 s22, s22, 0x100
	s_addc_u32 s23, s23, 0
	s_add_u32 s47, s47, 0x100
	s_addc_u32 s48, s48, 0
	s_cmp_gt_u32 s49, 13
	s_cbranch_scc0 .LBB0_842
